# v63 with the forward substitution's off-diagonal part in packed f32 FMAs (two M columns per instruction, rows four in flight), diagonal 4x4 part scalar
# speedup vs baseline: 1.0108x; 1.0067x over previous
; #define LAS __attribute__((address_space(3)))
; __device__ __forceinline__ void gdn_local_unit(LAS unsigned char* lds, const GdnP& P, int unit, const int tid, const int pf) {
;     ...
;             for (int t = 0; t < 64; ++t) sol2[t >> 1][t & 1] = Ks[t * 132 + col - 128] * rk[t] * beta[t] * eG[t];
;         }
; #pragma unroll
;         for (int c = 1; c < 64; ++c) { f32x2 sp = (f32x2){sol2[c >> 1][c & 1], 0.f};
; #pragma unroll
;             for (int jb = 0; jb <= (c - 1) / 4; ++jb) { const f32x4 m4 = *(const LAS f32x4*)(Ms + c * 64 + 4 * jb);
;                 sp -= (f32x2){m4.x, m4.y} * sol2[2 * jb]; sp -= (f32x2){m4.z, m4.w} * sol2[2 * jb + 1]; }
;             sol2[c >> 1][c & 1] = sp.x + sp.y; }
.LBB0_1025:
	s_or_b64 exec, exec, s[0:1]
	v_add_u32_e32 v3, v130, v3
	ds_read_b32 v3, v3
	ds_read_b128 v[142:145], v109 offset:256
	ds_read_b128 v[146:149], v109 offset:512
	ds_read_b128 v[150:153], v109 offset:768
	ds_read_b128 v[154:157], v109 offset:1024
	ds_read_b128 v[158:161], v109 offset:1280
	ds_read_b128 v[220:223], v109 offset:1536
	ds_read_b128 v[230:233], v109 offset:1792
	ds_read_b128 v[234:237], v109 offset:2048
	s_waitcnt lgkmcnt(5)
	v_mul_f32_e32 v3, v5, v3
	v_fma_f32 v1, -v142, v0, v1
	ds_read_b128 v[142:145], v109 offset:2304
	v_fma_f32 v8, -v146, v0, v8
	v_fma_f32 v9, -v150, v0, v9
	v_fma_f32 v8, -v147, v1, v8
	ds_read_b128 v[146:149], v109 offset:2560
	v_fma_f32 v9, -v151, v1, v9
	v_fma_f32 v9, -v152, v8, v9
	ds_read_b128 v[150:153], v109 offset:2816
	s_waitcnt lgkmcnt(4)
	v_pk_mul_f32 v[28:29], v[154:155], v[0:1] neg_lo:[1,0] neg_hi:[1,0]
	v_pk_mul_f32 v[34:35], v[158:159], v[0:1] neg_lo:[1,0] neg_hi:[1,0]
	v_pk_mul_f32 v[38:39], v[220:221], v[0:1] neg_lo:[1,0] neg_hi:[1,0]
	v_pk_mul_f32 v[42:43], v[230:231], v[0:1] neg_lo:[1,0] neg_hi:[1,0]
	v_pk_fma_f32 v[28:29], v[156:157], v[8:9], v[28:29] neg_lo:[1,0,0] neg_hi:[1,0,0]
	ds_read_b128 v[154:157], v109 offset:1296
	v_pk_fma_f32 v[34:35], v[160:161], v[8:9], v[34:35] neg_lo:[1,0,0] neg_hi:[1,0,0]
	ds_read_b128 v[158:161], v109 offset:1552
	v_pk_fma_f32 v[38:39], v[222:223], v[8:9], v[38:39] neg_lo:[1,0,0] neg_hi:[1,0,0]
	ds_read_b128 v[220:223], v109 offset:1808
	v_pk_fma_f32 v[42:43], v[232:233], v[8:9], v[42:43] neg_lo:[1,0,0] neg_hi:[1,0,0]
	ds_read_b128 v[230:233], v109 offset:2064
	v_add_f32_e32 v28, v28, v29
	s_waitcnt lgkmcnt(5)
	v_pk_mul_f32 v[10:11], v[234:235], v[0:1] neg_lo:[1,0] neg_hi:[1,0]
	v_pk_mul_f32 v[16:17], v[142:143], v[0:1] neg_lo:[1,0] neg_hi:[1,0]
	v_add_f32_e32 v34, v34, v35
	v_pk_mul_f32 v[20:21], v[146:147], v[0:1] neg_lo:[1,0] neg_hi:[1,0]
	s_waitcnt lgkmcnt(4)
	v_pk_mul_f32 v[24:25], v[150:151], v[0:1] neg_lo:[1,0] neg_hi:[1,0]
	v_add_f32_e32 v38, v38, v39
	v_pk_fma_f32 v[10:11], v[236:237], v[8:9], v[10:11] neg_lo:[1,0,0] neg_hi:[1,0,0]
	ds_read_b128 v[234:237], v109 offset:2320
	v_pk_fma_f32 v[16:17], v[144:145], v[8:9], v[16:17] neg_lo:[1,0,0] neg_hi:[1,0,0]
	ds_read_b128 v[142:145], v109 offset:2576
	v_add_f32_e32 v42, v42, v43
	v_pk_fma_f32 v[20:21], v[148:149], v[8:9], v[20:21] neg_lo:[1,0,0] neg_hi:[1,0,0]
	ds_read_b128 v[146:149], v109 offset:2832
	v_pk_fma_f32 v[24:25], v[152:153], v[8:9], v[24:25] neg_lo:[1,0,0] neg_hi:[1,0,0]
	ds_read_b128 v[150:153], v109 offset:3072
	v_add_f32_e32 v14, v28, v14
	v_add_f32_e32 v34, v34, v15
	v_add_f32_e32 v38, v38, v18
	v_add_f32_e32 v42, v42, v19
	s_waitcnt lgkmcnt(5)
	v_fma_f32 v15, -v154, v14, v34
	ds_read_b128 v[154:157], v109 offset:3328
	v_fma_f32 v38, -v158, v14, v38
	v_fma_f32 v42, -v220, v14, v42
	v_fma_f32 v18, -v159, v15, v38
	ds_read_b128 v[158:161], v109 offset:3584
	v_fma_f32 v42, -v221, v15, v42
	v_fma_f32 v19, -v222, v18, v42
	ds_read_b128 v[220:223], v109 offset:3840
	s_waitcnt lgkmcnt(4)
	v_pk_fma_f32 v[10:11], v[230:231], v[14:15], v[10:11] neg_lo:[1,0,0] neg_hi:[1,0,0]
	v_pk_fma_f32 v[16:17], v[234:235], v[14:15], v[16:17] neg_lo:[1,0,0] neg_hi:[1,0,0]
	v_pk_fma_f32 v[20:21], v[142:143], v[14:15], v[20:21] neg_lo:[1,0,0] neg_hi:[1,0,0]
	v_pk_fma_f32 v[24:25], v[146:147], v[14:15], v[24:25] neg_lo:[1,0,0] neg_hi:[1,0,0]
	v_pk_fma_f32 v[10:11], v[232:233], v[18:19], v[10:11] neg_lo:[1,0,0] neg_hi:[1,0,0]
	ds_read_b128 v[230:233], v109 offset:3088
	v_pk_fma_f32 v[16:17], v[236:237], v[18:19], v[16:17] neg_lo:[1,0,0] neg_hi:[1,0,0]
	ds_read_b128 v[234:237], v109 offset:3344
	v_pk_fma_f32 v[20:21], v[144:145], v[18:19], v[20:21] neg_lo:[1,0,0] neg_hi:[1,0,0]
	ds_read_b128 v[142:145], v109 offset:3600
	v_pk_fma_f32 v[24:25], v[148:149], v[18:19], v[24:25] neg_lo:[1,0,0] neg_hi:[1,0,0]
	ds_read_b128 v[146:149], v109 offset:3856
	v_add_f32_e32 v10, v10, v11
	s_waitcnt lgkmcnt(5)
	v_pk_mul_f32 v[28:29], v[150:151], v[0:1] neg_lo:[1,0] neg_hi:[1,0]
	v_pk_mul_f32 v[34:35], v[154:155], v[0:1] neg_lo:[1,0] neg_hi:[1,0]
	v_add_f32_e32 v16, v16, v17
	v_pk_mul_f32 v[38:39], v[158:159], v[0:1] neg_lo:[1,0] neg_hi:[1,0]
	s_waitcnt lgkmcnt(4)
	v_pk_mul_f32 v[42:43], v[220:221], v[0:1] neg_lo:[1,0] neg_hi:[1,0]
	v_add_f32_e32 v20, v20, v21
	v_pk_fma_f32 v[28:29], v[152:153], v[8:9], v[28:29] neg_lo:[1,0,0] neg_hi:[1,0,0]
	ds_read_b128 v[150:153], v109 offset:2336
	v_pk_fma_f32 v[34:35], v[156:157], v[8:9], v[34:35] neg_lo:[1,0,0] neg_hi:[1,0,0]
	ds_read_b128 v[154:157], v109 offset:2592
	v_add_f32_e32 v24, v24, v25
	v_pk_fma_f32 v[38:39], v[160:161], v[8:9], v[38:39] neg_lo:[1,0,0] neg_hi:[1,0,0]
	ds_read_b128 v[158:161], v109 offset:2848
	v_pk_fma_f32 v[42:43], v[222:223], v[8:9], v[42:43] neg_lo:[1,0,0] neg_hi:[1,0,0]
	ds_read_b128 v[220:223], v109 offset:3104
	v_add_f32_e32 v22, v10, v22
	s_waitcnt lgkmcnt(5)
	v_pk_fma_f32 v[28:29], v[230:231], v[14:15], v[28:29] neg_lo:[1,0,0] neg_hi:[1,0,0]
	v_pk_fma_f32 v[34:35], v[234:235], v[14:15], v[34:35] neg_lo:[1,0,0] neg_hi:[1,0,0]
	v_add_f32_e32 v16, v16, v23
	v_pk_fma_f32 v[38:39], v[142:143], v[14:15], v[38:39] neg_lo:[1,0,0] neg_hi:[1,0,0]
	s_waitcnt lgkmcnt(4)
	v_pk_fma_f32 v[42:43], v[146:147], v[14:15], v[42:43] neg_lo:[1,0,0] neg_hi:[1,0,0]
	v_add_f32_e32 v20, v20, v26
	v_pk_fma_f32 v[28:29], v[232:233], v[18:19], v[28:29] neg_lo:[1,0,0] neg_hi:[1,0,0]
	ds_read_b128 v[230:233], v109 offset:3360
	v_pk_fma_f32 v[34:35], v[236:237], v[18:19], v[34:35] neg_lo:[1,0,0] neg_hi:[1,0,0]
	ds_read_b128 v[234:237], v109 offset:3616
	v_add_f32_e32 v24, v24, v27
	v_pk_fma_f32 v[38:39], v[144:145], v[18:19], v[38:39] neg_lo:[1,0,0] neg_hi:[1,0,0]
	ds_read_b128 v[142:145], v109 offset:3872
	v_pk_fma_f32 v[42:43], v[148:149], v[18:19], v[42:43] neg_lo:[1,0,0] neg_hi:[1,0,0]
	ds_read_b128 v[146:149], v109 offset:4096
	s_waitcnt lgkmcnt(5)
; #define LAS __attribute__((address_space(3)))
; __device__ __forceinline__ void gdn_local_unit(LAS unsigned char* lds, const GdnP& P, int unit, const int tid, const int pf) {
;     ...
; #pragma unroll
;         for (int c = 1; c < 64; ++c) { f32x2 sp = (f32x2){sol2[c >> 1][c & 1], 0.f};
; #pragma unroll
;             for (int jb = 0; jb <= (c - 1) / 4; ++jb) { const f32x4 m4 = *(const LAS f32x4*)(Ms + c * 64 + 4 * jb);
;                 sp -= (f32x2){m4.x, m4.y} * sol2[2 * jb]; sp -= (f32x2){m4.z, m4.w} * sol2[2 * jb + 1]; }
;             sol2[c >> 1][c & 1] = sp.x + sp.y; }
	v_fma_f32 v23, -v150, v22, v16
	ds_read_b128 v[150:153], v109 offset:4352
	v_fma_f32 v20, -v154, v22, v20
	v_fma_f32 v24, -v158, v22, v24
	v_fma_f32 v26, -v155, v23, v20
	ds_read_b128 v[154:157], v109 offset:4608
	v_fma_f32 v24, -v159, v23, v24
	v_fma_f32 v27, -v160, v26, v24
	ds_read_b128 v[158:161], v109 offset:4864
	s_waitcnt lgkmcnt(4)
	v_pk_fma_f32 v[28:29], v[220:221], v[22:23], v[28:29] neg_lo:[1,0,0] neg_hi:[1,0,0]
	v_pk_fma_f32 v[34:35], v[230:231], v[22:23], v[34:35] neg_lo:[1,0,0] neg_hi:[1,0,0]
	v_pk_fma_f32 v[38:39], v[234:235], v[22:23], v[38:39] neg_lo:[1,0,0] neg_hi:[1,0,0]
	v_pk_fma_f32 v[42:43], v[142:143], v[22:23], v[42:43] neg_lo:[1,0,0] neg_hi:[1,0,0]
	v_pk_fma_f32 v[28:29], v[222:223], v[26:27], v[28:29] neg_lo:[1,0,0] neg_hi:[1,0,0]
	ds_read_b128 v[220:223], v109 offset:4112
	v_pk_fma_f32 v[34:35], v[232:233], v[26:27], v[34:35] neg_lo:[1,0,0] neg_hi:[1,0,0]
	ds_read_b128 v[230:233], v109 offset:4368
	v_pk_fma_f32 v[38:39], v[236:237], v[26:27], v[38:39] neg_lo:[1,0,0] neg_hi:[1,0,0]
	ds_read_b128 v[234:237], v109 offset:4624
	v_pk_fma_f32 v[42:43], v[144:145], v[26:27], v[42:43] neg_lo:[1,0,0] neg_hi:[1,0,0]
	ds_read_b128 v[142:145], v109 offset:4880
	v_add_f32_e32 v28, v28, v29
	s_waitcnt lgkmcnt(5)
	v_pk_mul_f32 v[10:11], v[146:147], v[0:1] neg_lo:[1,0] neg_hi:[1,0]
	v_pk_mul_f32 v[16:17], v[150:151], v[0:1] neg_lo:[1,0] neg_hi:[1,0]
	v_add_f32_e32 v34, v34, v35
	v_pk_mul_f32 v[20:21], v[154:155], v[0:1] neg_lo:[1,0] neg_hi:[1,0]
	s_waitcnt lgkmcnt(4)
	v_pk_mul_f32 v[24:25], v[158:159], v[0:1] neg_lo:[1,0] neg_hi:[1,0]
	v_add_f32_e32 v38, v38, v39
	v_pk_fma_f32 v[10:11], v[148:149], v[8:9], v[10:11] neg_lo:[1,0,0] neg_hi:[1,0,0]
	ds_read_b128 v[146:149], v109 offset:3376
	v_pk_fma_f32 v[16:17], v[152:153], v[8:9], v[16:17] neg_lo:[1,0,0] neg_hi:[1,0,0]
	ds_read_b128 v[150:153], v109 offset:4128
	v_add_f32_e32 v42, v42, v43
	v_pk_fma_f32 v[20:21], v[156:157], v[8:9], v[20:21] neg_lo:[1,0,0] neg_hi:[1,0,0]
	ds_read_b128 v[154:157], v109 offset:4384
	v_pk_fma_f32 v[24:25], v[160:161], v[8:9], v[24:25] neg_lo:[1,0,0] neg_hi:[1,0,0]
	ds_read_b128 v[158:161], v109 offset:3632
	v_add_f32_e32 v30, v28, v30
	s_waitcnt lgkmcnt(5)
	v_pk_fma_f32 v[10:11], v[220:221], v[14:15], v[10:11] neg_lo:[1,0,0] neg_hi:[1,0,0]
	v_pk_fma_f32 v[16:17], v[230:231], v[14:15], v[16:17] neg_lo:[1,0,0] neg_hi:[1,0,0]
	v_add_f32_e32 v34, v34, v31
	v_pk_fma_f32 v[20:21], v[234:235], v[14:15], v[20:21] neg_lo:[1,0,0] neg_hi:[1,0,0]
	s_waitcnt lgkmcnt(4)
	v_pk_fma_f32 v[24:25], v[142:143], v[14:15], v[24:25] neg_lo:[1,0,0] neg_hi:[1,0,0]
	v_add_f32_e32 v38, v38, v36
	v_pk_fma_f32 v[10:11], v[222:223], v[18:19], v[10:11] neg_lo:[1,0,0] neg_hi:[1,0,0]
	ds_read_b128 v[220:223], v109 offset:4640
	v_pk_fma_f32 v[16:17], v[232:233], v[18:19], v[16:17] neg_lo:[1,0,0] neg_hi:[1,0,0]
	ds_read_b128 v[230:233], v109 offset:4896
	v_add_f32_e32 v42, v42, v37
	v_pk_fma_f32 v[20:21], v[236:237], v[18:19], v[20:21] neg_lo:[1,0,0] neg_hi:[1,0,0]
	ds_read_b128 v[234:237], v109 offset:3888
	v_pk_fma_f32 v[24:25], v[144:145], v[18:19], v[24:25] neg_lo:[1,0,0] neg_hi:[1,0,0]
	ds_read_b128 v[142:145], v109 offset:4144
	s_waitcnt lgkmcnt(4)
	v_fma_f32 v31, -v146, v30, v34
	ds_read_b128 v[146:149], v109 offset:4400
	v_pk_fma_f32 v[10:11], v[150:151], v[22:23], v[10:11] neg_lo:[1,0,0] neg_hi:[1,0,0]
	v_pk_fma_f32 v[16:17], v[154:155], v[22:23], v[16:17] neg_lo:[1,0,0] neg_hi:[1,0,0]
	v_fma_f32 v38, -v158, v30, v38
	s_waitcnt lgkmcnt(2)
	v_pk_fma_f32 v[20:21], v[220:221], v[22:23], v[20:21] neg_lo:[1,0,0] neg_hi:[1,0,0]
	v_pk_fma_f32 v[24:25], v[230:231], v[22:23], v[24:25] neg_lo:[1,0,0] neg_hi:[1,0,0]
	v_fma_f32 v42, -v234, v30, v42
	v_pk_fma_f32 v[10:11], v[152:153], v[26:27], v[10:11] neg_lo:[1,0,0] neg_hi:[1,0,0]
	ds_read_b128 v[150:153], v109 offset:4656
	v_pk_fma_f32 v[16:17], v[156:157], v[26:27], v[16:17] neg_lo:[1,0,0] neg_hi:[1,0,0]
	ds_read_b128 v[154:157], v109 offset:4912
	v_fma_f32 v36, -v159, v31, v38
	ds_read_b128 v[158:161], v109 offset:5120
	v_pk_fma_f32 v[20:21], v[222:223], v[26:27], v[20:21] neg_lo:[1,0,0] neg_hi:[1,0,0]
	ds_read_b128 v[220:223], v109 offset:5376
	v_pk_fma_f32 v[24:25], v[232:233], v[26:27], v[24:25] neg_lo:[1,0,0] neg_hi:[1,0,0]
	ds_read_b128 v[230:233], v109 offset:5632
	v_fma_f32 v42, -v235, v31, v42
	v_fma_f32 v37, -v236, v36, v42
	ds_read_b128 v[234:237], v109 offset:5888
	s_waitcnt lgkmcnt(4)
	v_pk_fma_f32 v[10:11], v[142:143], v[30:31], v[10:11] neg_lo:[1,0,0] neg_hi:[1,0,0]
	v_pk_fma_f32 v[16:17], v[146:147], v[30:31], v[16:17] neg_lo:[1,0,0] neg_hi:[1,0,0]
	v_pk_fma_f32 v[20:21], v[150:151], v[30:31], v[20:21] neg_lo:[1,0,0] neg_hi:[1,0,0]
	v_pk_fma_f32 v[24:25], v[154:155], v[30:31], v[24:25] neg_lo:[1,0,0] neg_hi:[1,0,0]
	v_pk_fma_f32 v[10:11], v[144:145], v[36:37], v[10:11] neg_lo:[1,0,0] neg_hi:[1,0,0]
	ds_read_b128 v[142:145], v109 offset:5136
	v_pk_fma_f32 v[16:17], v[148:149], v[36:37], v[16:17] neg_lo:[1,0,0] neg_hi:[1,0,0]
	ds_read_b128 v[146:149], v109 offset:5392
	v_pk_fma_f32 v[20:21], v[152:153], v[36:37], v[20:21] neg_lo:[1,0,0] neg_hi:[1,0,0]
	ds_read_b128 v[150:153], v109 offset:5648
	v_pk_fma_f32 v[24:25], v[156:157], v[36:37], v[24:25] neg_lo:[1,0,0] neg_hi:[1,0,0]
	ds_read_b128 v[154:157], v109 offset:5904
	v_add_f32_e32 v10, v10, v11
	s_waitcnt lgkmcnt(5)
	v_pk_mul_f32 v[28:29], v[158:159], v[0:1] neg_lo:[1,0] neg_hi:[1,0]
	v_pk_mul_f32 v[34:35], v[220:221], v[0:1] neg_lo:[1,0] neg_hi:[1,0]
	v_add_f32_e32 v16, v16, v17
	v_pk_mul_f32 v[38:39], v[230:231], v[0:1] neg_lo:[1,0] neg_hi:[1,0]
	s_waitcnt lgkmcnt(4)
; #define LAS __attribute__((address_space(3)))
; __device__ __forceinline__ void gdn_local_unit(LAS unsigned char* lds, const GdnP& P, int unit, const int tid, const int pf) {
;     ...
; #pragma unroll
;         for (int c = 1; c < 64; ++c) { f32x2 sp = (f32x2){sol2[c >> 1][c & 1], 0.f};
; #pragma unroll
;             for (int jb = 0; jb <= (c - 1) / 4; ++jb) { const f32x4 m4 = *(const LAS f32x4*)(Ms + c * 64 + 4 * jb);
;                 sp -= (f32x2){m4.x, m4.y} * sol2[2 * jb]; sp -= (f32x2){m4.z, m4.w} * sol2[2 * jb + 1]; }
;             sol2[c >> 1][c & 1] = sp.x + sp.y; }
	v_pk_mul_f32 v[42:43], v[234:235], v[0:1] neg_lo:[1,0] neg_hi:[1,0]
	v_add_f32_e32 v20, v20, v21
	v_pk_fma_f32 v[28:29], v[160:161], v[8:9], v[28:29] neg_lo:[1,0,0] neg_hi:[1,0,0]
	ds_read_b128 v[158:161], v109 offset:4416
	v_pk_fma_f32 v[34:35], v[222:223], v[8:9], v[34:35] neg_lo:[1,0,0] neg_hi:[1,0,0]
	ds_read_b128 v[220:223], v109 offset:5152
	v_add_f32_e32 v24, v24, v25
	v_pk_fma_f32 v[38:39], v[232:233], v[8:9], v[38:39] neg_lo:[1,0,0] neg_hi:[1,0,0]
	ds_read_b128 v[230:233], v109 offset:5408
	v_pk_fma_f32 v[42:43], v[236:237], v[8:9], v[42:43] neg_lo:[1,0,0] neg_hi:[1,0,0]
	ds_read_b128 v[234:237], v109 offset:4672
	v_add_f32_e32 v40, v10, v40
	s_waitcnt lgkmcnt(5)
	v_pk_fma_f32 v[28:29], v[142:143], v[14:15], v[28:29] neg_lo:[1,0,0] neg_hi:[1,0,0]
	v_pk_fma_f32 v[34:35], v[146:147], v[14:15], v[34:35] neg_lo:[1,0,0] neg_hi:[1,0,0]
	v_add_f32_e32 v16, v16, v41
	v_pk_fma_f32 v[38:39], v[150:151], v[14:15], v[38:39] neg_lo:[1,0,0] neg_hi:[1,0,0]
	s_waitcnt lgkmcnt(4)
	v_pk_fma_f32 v[42:43], v[154:155], v[14:15], v[42:43] neg_lo:[1,0,0] neg_hi:[1,0,0]
	v_add_f32_e32 v20, v20, v44
	v_pk_fma_f32 v[28:29], v[144:145], v[18:19], v[28:29] neg_lo:[1,0,0] neg_hi:[1,0,0]
	ds_read_b128 v[142:145], v109 offset:5664
	v_pk_fma_f32 v[34:35], v[148:149], v[18:19], v[34:35] neg_lo:[1,0,0] neg_hi:[1,0,0]
	ds_read_b128 v[146:149], v109 offset:5920
	v_add_f32_e32 v24, v24, v45
	v_pk_fma_f32 v[38:39], v[152:153], v[18:19], v[38:39] neg_lo:[1,0,0] neg_hi:[1,0,0]
	ds_read_b128 v[150:153], v109 offset:4928
	v_pk_fma_f32 v[42:43], v[156:157], v[18:19], v[42:43] neg_lo:[1,0,0] neg_hi:[1,0,0]
	ds_read_b128 v[154:157], v109 offset:5168
	s_waitcnt lgkmcnt(4)
	v_fma_f32 v41, -v158, v40, v16
	ds_read_b128 v[158:161], v109 offset:5424
	v_pk_fma_f32 v[28:29], v[220:221], v[22:23], v[28:29] neg_lo:[1,0,0] neg_hi:[1,0,0]
	v_pk_fma_f32 v[34:35], v[230:231], v[22:23], v[34:35] neg_lo:[1,0,0] neg_hi:[1,0,0]
	v_fma_f32 v20, -v234, v40, v20
	s_waitcnt lgkmcnt(2)
	v_pk_fma_f32 v[38:39], v[142:143], v[22:23], v[38:39] neg_lo:[1,0,0] neg_hi:[1,0,0]
	v_pk_fma_f32 v[42:43], v[146:147], v[22:23], v[42:43] neg_lo:[1,0,0] neg_hi:[1,0,0]
	v_fma_f32 v24, -v150, v40, v24
	v_pk_fma_f32 v[28:29], v[222:223], v[26:27], v[28:29] neg_lo:[1,0,0] neg_hi:[1,0,0]
	ds_read_b128 v[220:223], v109 offset:5680
	v_pk_fma_f32 v[34:35], v[232:233], v[26:27], v[34:35] neg_lo:[1,0,0] neg_hi:[1,0,0]
	ds_read_b128 v[230:233], v109 offset:5936
	v_fma_f32 v44, -v235, v41, v20
	ds_read_b128 v[234:237], v109 offset:5184
	v_pk_fma_f32 v[38:39], v[144:145], v[26:27], v[38:39] neg_lo:[1,0,0] neg_hi:[1,0,0]
	ds_read_b128 v[142:145], v109 offset:5440
	v_pk_fma_f32 v[42:43], v[148:149], v[26:27], v[42:43] neg_lo:[1,0,0] neg_hi:[1,0,0]
	ds_read_b128 v[146:149], v109 offset:5696
	v_fma_f32 v24, -v151, v41, v24
	s_waitcnt lgkmcnt(4)
	v_pk_fma_f32 v[28:29], v[154:155], v[30:31], v[28:29] neg_lo:[1,0,0] neg_hi:[1,0,0]
	v_pk_fma_f32 v[34:35], v[158:159], v[30:31], v[34:35] neg_lo:[1,0,0] neg_hi:[1,0,0]
	v_fma_f32 v45, -v152, v44, v24
	ds_read_b128 v[150:153], v109 offset:5952
	v_pk_fma_f32 v[38:39], v[220:221], v[30:31], v[38:39] neg_lo:[1,0,0] neg_hi:[1,0,0]
	s_waitcnt lgkmcnt(4)
	v_pk_fma_f32 v[42:43], v[230:231], v[30:31], v[42:43] neg_lo:[1,0,0] neg_hi:[1,0,0]
	v_pk_fma_f32 v[28:29], v[156:157], v[36:37], v[28:29] neg_lo:[1,0,0] neg_hi:[1,0,0]
	ds_read_b128 v[154:157], v109 offset:6144
	v_pk_fma_f32 v[34:35], v[160:161], v[36:37], v[34:35] neg_lo:[1,0,0] neg_hi:[1,0,0]
	ds_read_b128 v[158:161], v109 offset:6400
	v_pk_fma_f32 v[38:39], v[222:223], v[36:37], v[38:39] neg_lo:[1,0,0] neg_hi:[1,0,0]
	ds_read_b128 v[220:223], v109 offset:6656
	v_pk_fma_f32 v[42:43], v[232:233], v[36:37], v[42:43] neg_lo:[1,0,0] neg_hi:[1,0,0]
	ds_read_b128 v[230:233], v109 offset:6912
	s_waitcnt lgkmcnt(4)
	v_pk_fma_f32 v[28:29], v[234:235], v[40:41], v[28:29] neg_lo:[1,0,0] neg_hi:[1,0,0]
	v_pk_fma_f32 v[34:35], v[142:143], v[40:41], v[34:35] neg_lo:[1,0,0] neg_hi:[1,0,0]
	v_pk_fma_f32 v[38:39], v[146:147], v[40:41], v[38:39] neg_lo:[1,0,0] neg_hi:[1,0,0]
	v_pk_fma_f32 v[42:43], v[150:151], v[40:41], v[42:43] neg_lo:[1,0,0] neg_hi:[1,0,0]
	v_pk_fma_f32 v[28:29], v[236:237], v[44:45], v[28:29] neg_lo:[1,0,0] neg_hi:[1,0,0]
	ds_read_b128 v[234:237], v109 offset:6160
	v_pk_fma_f32 v[34:35], v[144:145], v[44:45], v[34:35] neg_lo:[1,0,0] neg_hi:[1,0,0]
	ds_read_b128 v[142:145], v109 offset:6416
	v_pk_fma_f32 v[38:39], v[148:149], v[44:45], v[38:39] neg_lo:[1,0,0] neg_hi:[1,0,0]
	ds_read_b128 v[146:149], v109 offset:6672
	v_pk_fma_f32 v[42:43], v[152:153], v[44:45], v[42:43] neg_lo:[1,0,0] neg_hi:[1,0,0]
	ds_read_b128 v[150:153], v109 offset:6928
	v_add_f32_e32 v28, v28, v29
	s_waitcnt lgkmcnt(5)
	v_pk_mul_f32 v[10:11], v[154:155], v[0:1] neg_lo:[1,0] neg_hi:[1,0]
	v_pk_mul_f32 v[16:17], v[158:159], v[0:1] neg_lo:[1,0] neg_hi:[1,0]
	v_add_f32_e32 v34, v34, v35
	v_pk_mul_f32 v[20:21], v[220:221], v[0:1] neg_lo:[1,0] neg_hi:[1,0]
	s_waitcnt lgkmcnt(4)
	v_pk_mul_f32 v[24:25], v[230:231], v[0:1] neg_lo:[1,0] neg_hi:[1,0]
	v_add_f32_e32 v38, v38, v39
	v_pk_fma_f32 v[10:11], v[156:157], v[8:9], v[10:11] neg_lo:[1,0,0] neg_hi:[1,0,0]
	ds_read_b128 v[154:157], v109 offset:5456
	v_pk_fma_f32 v[16:17], v[160:161], v[8:9], v[16:17] neg_lo:[1,0,0] neg_hi:[1,0,0]
	ds_read_b128 v[158:161], v109 offset:6176
	v_add_f32_e32 v42, v42, v43
	v_pk_fma_f32 v[20:21], v[222:223], v[8:9], v[20:21] neg_lo:[1,0,0] neg_hi:[1,0,0]
	ds_read_b128 v[220:223], v109 offset:6432
	v_pk_fma_f32 v[24:25], v[232:233], v[8:9], v[24:25] neg_lo:[1,0,0] neg_hi:[1,0,0]
	ds_read_b128 v[230:233], v109 offset:5712
	v_add_f32_e32 v50, v28, v50
	s_waitcnt lgkmcnt(5)
; #define LAS __attribute__((address_space(3)))
; __device__ __forceinline__ void gdn_local_unit(LAS unsigned char* lds, const GdnP& P, int unit, const int tid, const int pf) {
;     ...
; #pragma unroll
;         for (int c = 1; c < 64; ++c) { f32x2 sp = (f32x2){sol2[c >> 1][c & 1], 0.f};
; #pragma unroll
;             for (int jb = 0; jb <= (c - 1) / 4; ++jb) { const f32x4 m4 = *(const LAS f32x4*)(Ms + c * 64 + 4 * jb);
;                 sp -= (f32x2){m4.x, m4.y} * sol2[2 * jb]; sp -= (f32x2){m4.z, m4.w} * sol2[2 * jb + 1]; }
;             sol2[c >> 1][c & 1] = sp.x + sp.y; }
	v_pk_fma_f32 v[10:11], v[234:235], v[14:15], v[10:11] neg_lo:[1,0,0] neg_hi:[1,0,0]
	v_pk_fma_f32 v[16:17], v[142:143], v[14:15], v[16:17] neg_lo:[1,0,0] neg_hi:[1,0,0]
	v_add_f32_e32 v34, v34, v51
	v_pk_fma_f32 v[20:21], v[146:147], v[14:15], v[20:21] neg_lo:[1,0,0] neg_hi:[1,0,0]
	s_waitcnt lgkmcnt(4)
	v_pk_fma_f32 v[24:25], v[150:151], v[14:15], v[24:25] neg_lo:[1,0,0] neg_hi:[1,0,0]
	v_add_f32_e32 v38, v38, v54
	v_pk_fma_f32 v[10:11], v[236:237], v[18:19], v[10:11] neg_lo:[1,0,0] neg_hi:[1,0,0]
	ds_read_b128 v[234:237], v109 offset:6688
	v_pk_fma_f32 v[16:17], v[144:145], v[18:19], v[16:17] neg_lo:[1,0,0] neg_hi:[1,0,0]
	ds_read_b128 v[142:145], v109 offset:6944
	v_add_f32_e32 v42, v42, v55
	v_pk_fma_f32 v[20:21], v[148:149], v[18:19], v[20:21] neg_lo:[1,0,0] neg_hi:[1,0,0]
	ds_read_b128 v[146:149], v109 offset:5968
	v_pk_fma_f32 v[24:25], v[152:153], v[18:19], v[24:25] neg_lo:[1,0,0] neg_hi:[1,0,0]
	ds_read_b128 v[150:153], v109 offset:6192
	s_waitcnt lgkmcnt(4)
	v_fma_f32 v51, -v154, v50, v34
	ds_read_b128 v[154:157], v109 offset:6448
	v_pk_fma_f32 v[10:11], v[158:159], v[22:23], v[10:11] neg_lo:[1,0,0] neg_hi:[1,0,0]
	v_pk_fma_f32 v[16:17], v[220:221], v[22:23], v[16:17] neg_lo:[1,0,0] neg_hi:[1,0,0]
	v_fma_f32 v38, -v230, v50, v38
	s_waitcnt lgkmcnt(2)
	v_pk_fma_f32 v[20:21], v[234:235], v[22:23], v[20:21] neg_lo:[1,0,0] neg_hi:[1,0,0]
	v_pk_fma_f32 v[24:25], v[142:143], v[22:23], v[24:25] neg_lo:[1,0,0] neg_hi:[1,0,0]
	v_fma_f32 v42, -v146, v50, v42
	v_pk_fma_f32 v[10:11], v[160:161], v[26:27], v[10:11] neg_lo:[1,0,0] neg_hi:[1,0,0]
	ds_read_b128 v[158:161], v109 offset:6704
	v_pk_fma_f32 v[16:17], v[222:223], v[26:27], v[16:17] neg_lo:[1,0,0] neg_hi:[1,0,0]
	ds_read_b128 v[220:223], v109 offset:6960
	v_fma_f32 v54, -v231, v51, v38
	ds_read_b128 v[230:233], v109 offset:6208
	v_pk_fma_f32 v[20:21], v[236:237], v[26:27], v[20:21] neg_lo:[1,0,0] neg_hi:[1,0,0]
	ds_read_b128 v[234:237], v109 offset:6464
	v_pk_fma_f32 v[24:25], v[144:145], v[26:27], v[24:25] neg_lo:[1,0,0] neg_hi:[1,0,0]
	ds_read_b128 v[142:145], v109 offset:6720
	v_fma_f32 v42, -v147, v51, v42
	s_waitcnt lgkmcnt(4)
	v_pk_fma_f32 v[10:11], v[150:151], v[30:31], v[10:11] neg_lo:[1,0,0] neg_hi:[1,0,0]
	v_pk_fma_f32 v[16:17], v[154:155], v[30:31], v[16:17] neg_lo:[1,0,0] neg_hi:[1,0,0]
	v_fma_f32 v55, -v148, v54, v42
	ds_read_b128 v[146:149], v109 offset:6976
	v_pk_fma_f32 v[20:21], v[158:159], v[30:31], v[20:21] neg_lo:[1,0,0] neg_hi:[1,0,0]
	s_waitcnt lgkmcnt(4)
	v_pk_fma_f32 v[24:25], v[220:221], v[30:31], v[24:25] neg_lo:[1,0,0] neg_hi:[1,0,0]
	v_pk_fma_f32 v[10:11], v[152:153], v[36:37], v[10:11] neg_lo:[1,0,0] neg_hi:[1,0,0]
	ds_read_b128 v[150:153], v109 offset:6224
	v_pk_fma_f32 v[16:17], v[156:157], v[36:37], v[16:17] neg_lo:[1,0,0] neg_hi:[1,0,0]
	ds_read_b128 v[154:157], v109 offset:6480
	v_pk_fma_f32 v[20:21], v[160:161], v[36:37], v[20:21] neg_lo:[1,0,0] neg_hi:[1,0,0]
	ds_read_b128 v[158:161], v109 offset:6736
	v_pk_fma_f32 v[24:25], v[222:223], v[36:37], v[24:25] neg_lo:[1,0,0] neg_hi:[1,0,0]
	ds_read_b128 v[220:223], v109 offset:6992
	s_waitcnt lgkmcnt(4)
	v_pk_fma_f32 v[10:11], v[230:231], v[40:41], v[10:11] neg_lo:[1,0,0] neg_hi:[1,0,0]
	v_pk_fma_f32 v[16:17], v[234:235], v[40:41], v[16:17] neg_lo:[1,0,0] neg_hi:[1,0,0]
	v_pk_fma_f32 v[20:21], v[142:143], v[40:41], v[20:21] neg_lo:[1,0,0] neg_hi:[1,0,0]
	v_pk_fma_f32 v[24:25], v[146:147], v[40:41], v[24:25] neg_lo:[1,0,0] neg_hi:[1,0,0]
	v_pk_fma_f32 v[10:11], v[232:233], v[44:45], v[10:11] neg_lo:[1,0,0] neg_hi:[1,0,0]
	ds_read_b128 v[230:233], v109 offset:7168
	v_pk_fma_f32 v[16:17], v[236:237], v[44:45], v[16:17] neg_lo:[1,0,0] neg_hi:[1,0,0]
	ds_read_b128 v[234:237], v109 offset:7424
	v_pk_fma_f32 v[20:21], v[144:145], v[44:45], v[20:21] neg_lo:[1,0,0] neg_hi:[1,0,0]
	ds_read_b128 v[142:145], v109 offset:7680
	v_pk_fma_f32 v[24:25], v[148:149], v[44:45], v[24:25] neg_lo:[1,0,0] neg_hi:[1,0,0]
	ds_read_b128 v[146:149], v109 offset:7936
	s_waitcnt lgkmcnt(4)
	v_pk_fma_f32 v[10:11], v[150:151], v[50:51], v[10:11] neg_lo:[1,0,0] neg_hi:[1,0,0]
	v_pk_fma_f32 v[16:17], v[154:155], v[50:51], v[16:17] neg_lo:[1,0,0] neg_hi:[1,0,0]
	v_pk_fma_f32 v[20:21], v[158:159], v[50:51], v[20:21] neg_lo:[1,0,0] neg_hi:[1,0,0]
	v_pk_fma_f32 v[24:25], v[220:221], v[50:51], v[24:25] neg_lo:[1,0,0] neg_hi:[1,0,0]
	v_pk_fma_f32 v[10:11], v[152:153], v[54:55], v[10:11] neg_lo:[1,0,0] neg_hi:[1,0,0]
	ds_read_b128 v[150:153], v109 offset:7184
	v_pk_fma_f32 v[16:17], v[156:157], v[54:55], v[16:17] neg_lo:[1,0,0] neg_hi:[1,0,0]
	ds_read_b128 v[154:157], v109 offset:7440
	v_pk_fma_f32 v[20:21], v[160:161], v[54:55], v[20:21] neg_lo:[1,0,0] neg_hi:[1,0,0]
	ds_read_b128 v[158:161], v109 offset:7696
	v_pk_fma_f32 v[24:25], v[222:223], v[54:55], v[24:25] neg_lo:[1,0,0] neg_hi:[1,0,0]
	ds_read_b128 v[220:223], v109 offset:7952
	v_add_f32_e32 v10, v10, v11
	s_waitcnt lgkmcnt(5)
	v_pk_mul_f32 v[28:29], v[230:231], v[0:1] neg_lo:[1,0] neg_hi:[1,0]
	v_pk_mul_f32 v[34:35], v[234:235], v[0:1] neg_lo:[1,0] neg_hi:[1,0]
	v_add_f32_e32 v16, v16, v17
	v_pk_mul_f32 v[38:39], v[142:143], v[0:1] neg_lo:[1,0] neg_hi:[1,0]
	s_waitcnt lgkmcnt(4)
	v_pk_mul_f32 v[42:43], v[146:147], v[0:1] neg_lo:[1,0] neg_hi:[1,0]
	v_add_f32_e32 v20, v20, v21
	v_pk_fma_f32 v[28:29], v[232:233], v[8:9], v[28:29] neg_lo:[1,0,0] neg_hi:[1,0,0]
	ds_read_b128 v[230:233], v109 offset:6496
	v_pk_fma_f32 v[34:35], v[236:237], v[8:9], v[34:35] neg_lo:[1,0,0] neg_hi:[1,0,0]
	ds_read_b128 v[234:237], v109 offset:7200
	v_add_f32_e32 v24, v24, v25
	v_pk_fma_f32 v[38:39], v[144:145], v[8:9], v[38:39] neg_lo:[1,0,0] neg_hi:[1,0,0]
	ds_read_b128 v[142:145], v109 offset:7456
	v_pk_fma_f32 v[42:43], v[148:149], v[8:9], v[42:43] neg_lo:[1,0,0] neg_hi:[1,0,0]
	ds_read_b128 v[146:149], v109 offset:6752
	v_add_f32_e32 v60, v10, v60
	s_waitcnt lgkmcnt(5)
; #define LAS __attribute__((address_space(3)))
; __device__ __forceinline__ void gdn_local_unit(LAS unsigned char* lds, const GdnP& P, int unit, const int tid, const int pf) {
;     ...
; #pragma unroll
;         for (int c = 1; c < 64; ++c) { f32x2 sp = (f32x2){sol2[c >> 1][c & 1], 0.f};
; #pragma unroll
;             for (int jb = 0; jb <= (c - 1) / 4; ++jb) { const f32x4 m4 = *(const LAS f32x4*)(Ms + c * 64 + 4 * jb);
;                 sp -= (f32x2){m4.x, m4.y} * sol2[2 * jb]; sp -= (f32x2){m4.z, m4.w} * sol2[2 * jb + 1]; }
;             sol2[c >> 1][c & 1] = sp.x + sp.y; }
	v_pk_fma_f32 v[28:29], v[150:151], v[14:15], v[28:29] neg_lo:[1,0,0] neg_hi:[1,0,0]
	v_pk_fma_f32 v[34:35], v[154:155], v[14:15], v[34:35] neg_lo:[1,0,0] neg_hi:[1,0,0]
	v_add_f32_e32 v16, v16, v61
	v_pk_fma_f32 v[38:39], v[158:159], v[14:15], v[38:39] neg_lo:[1,0,0] neg_hi:[1,0,0]
	s_waitcnt lgkmcnt(4)
	v_pk_fma_f32 v[42:43], v[220:221], v[14:15], v[42:43] neg_lo:[1,0,0] neg_hi:[1,0,0]
	v_add_f32_e32 v20, v20, v64
	v_pk_fma_f32 v[28:29], v[152:153], v[18:19], v[28:29] neg_lo:[1,0,0] neg_hi:[1,0,0]
	ds_read_b128 v[150:153], v109 offset:7712
	v_pk_fma_f32 v[34:35], v[156:157], v[18:19], v[34:35] neg_lo:[1,0,0] neg_hi:[1,0,0]
	ds_read_b128 v[154:157], v109 offset:7968
	v_add_f32_e32 v24, v24, v65
	v_pk_fma_f32 v[38:39], v[160:161], v[18:19], v[38:39] neg_lo:[1,0,0] neg_hi:[1,0,0]
	ds_read_b128 v[158:161], v109 offset:7008
	v_pk_fma_f32 v[42:43], v[222:223], v[18:19], v[42:43] neg_lo:[1,0,0] neg_hi:[1,0,0]
	ds_read_b128 v[220:223], v109 offset:7216
	s_waitcnt lgkmcnt(4)
	v_fma_f32 v61, -v230, v60, v16
	ds_read_b128 v[230:233], v109 offset:7472
	v_pk_fma_f32 v[28:29], v[234:235], v[22:23], v[28:29] neg_lo:[1,0,0] neg_hi:[1,0,0]
	v_pk_fma_f32 v[34:35], v[142:143], v[22:23], v[34:35] neg_lo:[1,0,0] neg_hi:[1,0,0]
	v_fma_f32 v20, -v146, v60, v20
	s_waitcnt lgkmcnt(2)
	v_pk_fma_f32 v[38:39], v[150:151], v[22:23], v[38:39] neg_lo:[1,0,0] neg_hi:[1,0,0]
	v_pk_fma_f32 v[42:43], v[154:155], v[22:23], v[42:43] neg_lo:[1,0,0] neg_hi:[1,0,0]
	v_fma_f32 v24, -v158, v60, v24
	v_pk_fma_f32 v[28:29], v[236:237], v[26:27], v[28:29] neg_lo:[1,0,0] neg_hi:[1,0,0]
	ds_read_b128 v[234:237], v109 offset:7728
	v_pk_fma_f32 v[34:35], v[144:145], v[26:27], v[34:35] neg_lo:[1,0,0] neg_hi:[1,0,0]
	ds_read_b128 v[142:145], v109 offset:7984
	v_fma_f32 v64, -v147, v61, v20
	ds_read_b128 v[146:149], v109 offset:7232
	v_pk_fma_f32 v[38:39], v[152:153], v[26:27], v[38:39] neg_lo:[1,0,0] neg_hi:[1,0,0]
	ds_read_b128 v[150:153], v109 offset:7488
	v_pk_fma_f32 v[42:43], v[156:157], v[26:27], v[42:43] neg_lo:[1,0,0] neg_hi:[1,0,0]
	ds_read_b128 v[154:157], v109 offset:7744
	v_fma_f32 v24, -v159, v61, v24
	s_waitcnt lgkmcnt(4)
	v_pk_fma_f32 v[28:29], v[220:221], v[30:31], v[28:29] neg_lo:[1,0,0] neg_hi:[1,0,0]
	v_pk_fma_f32 v[34:35], v[230:231], v[30:31], v[34:35] neg_lo:[1,0,0] neg_hi:[1,0,0]
	v_fma_f32 v65, -v160, v64, v24
	ds_read_b128 v[158:161], v109 offset:8000
	v_pk_fma_f32 v[38:39], v[234:235], v[30:31], v[38:39] neg_lo:[1,0,0] neg_hi:[1,0,0]
	s_waitcnt lgkmcnt(4)
	v_pk_fma_f32 v[42:43], v[142:143], v[30:31], v[42:43] neg_lo:[1,0,0] neg_hi:[1,0,0]
	v_pk_fma_f32 v[28:29], v[222:223], v[36:37], v[28:29] neg_lo:[1,0,0] neg_hi:[1,0,0]
	ds_read_b128 v[220:223], v109 offset:7248
	v_pk_fma_f32 v[34:35], v[232:233], v[36:37], v[34:35] neg_lo:[1,0,0] neg_hi:[1,0,0]
	ds_read_b128 v[230:233], v109 offset:7504
	v_pk_fma_f32 v[38:39], v[236:237], v[36:37], v[38:39] neg_lo:[1,0,0] neg_hi:[1,0,0]
	ds_read_b128 v[234:237], v109 offset:7760
	v_pk_fma_f32 v[42:43], v[144:145], v[36:37], v[42:43] neg_lo:[1,0,0] neg_hi:[1,0,0]
	ds_read_b128 v[142:145], v109 offset:8016
	s_waitcnt lgkmcnt(4)
	v_pk_fma_f32 v[28:29], v[146:147], v[40:41], v[28:29] neg_lo:[1,0,0] neg_hi:[1,0,0]
	v_pk_fma_f32 v[34:35], v[150:151], v[40:41], v[34:35] neg_lo:[1,0,0] neg_hi:[1,0,0]
	v_pk_fma_f32 v[38:39], v[154:155], v[40:41], v[38:39] neg_lo:[1,0,0] neg_hi:[1,0,0]
	v_pk_fma_f32 v[42:43], v[158:159], v[40:41], v[42:43] neg_lo:[1,0,0] neg_hi:[1,0,0]
	v_pk_fma_f32 v[28:29], v[148:149], v[44:45], v[28:29] neg_lo:[1,0,0] neg_hi:[1,0,0]
	ds_read_b128 v[146:149], v109 offset:7264
	v_pk_fma_f32 v[34:35], v[152:153], v[44:45], v[34:35] neg_lo:[1,0,0] neg_hi:[1,0,0]
	ds_read_b128 v[150:153], v109 offset:7520
	v_pk_fma_f32 v[38:39], v[156:157], v[44:45], v[38:39] neg_lo:[1,0,0] neg_hi:[1,0,0]
	ds_read_b128 v[154:157], v109 offset:7776
	v_pk_fma_f32 v[42:43], v[160:161], v[44:45], v[42:43] neg_lo:[1,0,0] neg_hi:[1,0,0]
	ds_read_b128 v[158:161], v109 offset:8032
	s_waitcnt lgkmcnt(4)
	v_pk_fma_f32 v[28:29], v[220:221], v[50:51], v[28:29] neg_lo:[1,0,0] neg_hi:[1,0,0]
	v_pk_fma_f32 v[34:35], v[230:231], v[50:51], v[34:35] neg_lo:[1,0,0] neg_hi:[1,0,0]
	v_pk_fma_f32 v[38:39], v[234:235], v[50:51], v[38:39] neg_lo:[1,0,0] neg_hi:[1,0,0]
	v_pk_fma_f32 v[42:43], v[142:143], v[50:51], v[42:43] neg_lo:[1,0,0] neg_hi:[1,0,0]
	v_pk_fma_f32 v[28:29], v[222:223], v[54:55], v[28:29] neg_lo:[1,0,0] neg_hi:[1,0,0]
	ds_read_b128 v[220:223], v109 offset:8192
	v_pk_fma_f32 v[34:35], v[232:233], v[54:55], v[34:35] neg_lo:[1,0,0] neg_hi:[1,0,0]
	ds_read_b128 v[230:233], v109 offset:8448
	v_pk_fma_f32 v[38:39], v[236:237], v[54:55], v[38:39] neg_lo:[1,0,0] neg_hi:[1,0,0]
	ds_read_b128 v[234:237], v109 offset:8704
	v_pk_fma_f32 v[42:43], v[144:145], v[54:55], v[42:43] neg_lo:[1,0,0] neg_hi:[1,0,0]
	ds_read_b128 v[142:145], v109 offset:8960
	s_waitcnt lgkmcnt(4)
	v_pk_fma_f32 v[28:29], v[146:147], v[60:61], v[28:29] neg_lo:[1,0,0] neg_hi:[1,0,0]
	v_pk_fma_f32 v[34:35], v[150:151], v[60:61], v[34:35] neg_lo:[1,0,0] neg_hi:[1,0,0]
	v_pk_fma_f32 v[38:39], v[154:155], v[60:61], v[38:39] neg_lo:[1,0,0] neg_hi:[1,0,0]
	v_pk_fma_f32 v[42:43], v[158:159], v[60:61], v[42:43] neg_lo:[1,0,0] neg_hi:[1,0,0]
	v_pk_fma_f32 v[28:29], v[148:149], v[64:65], v[28:29] neg_lo:[1,0,0] neg_hi:[1,0,0]
	ds_read_b128 v[146:149], v109 offset:8208
	v_pk_fma_f32 v[34:35], v[152:153], v[64:65], v[34:35] neg_lo:[1,0,0] neg_hi:[1,0,0]
	ds_read_b128 v[150:153], v109 offset:8464
	v_pk_fma_f32 v[38:39], v[156:157], v[64:65], v[38:39] neg_lo:[1,0,0] neg_hi:[1,0,0]
	ds_read_b128 v[154:157], v109 offset:8720
	v_pk_fma_f32 v[42:43], v[160:161], v[64:65], v[42:43] neg_lo:[1,0,0] neg_hi:[1,0,0]
	ds_read_b128 v[158:161], v109 offset:8976
	v_add_f32_e32 v28, v28, v29
	s_waitcnt lgkmcnt(5)
; #define LAS __attribute__((address_space(3)))
; __device__ __forceinline__ void gdn_local_unit(LAS unsigned char* lds, const GdnP& P, int unit, const int tid, const int pf) {
;     ...
; #pragma unroll
;         for (int c = 1; c < 64; ++c) { f32x2 sp = (f32x2){sol2[c >> 1][c & 1], 0.f};
; #pragma unroll
;             for (int jb = 0; jb <= (c - 1) / 4; ++jb) { const f32x4 m4 = *(const LAS f32x4*)(Ms + c * 64 + 4 * jb);
;                 sp -= (f32x2){m4.x, m4.y} * sol2[2 * jb]; sp -= (f32x2){m4.z, m4.w} * sol2[2 * jb + 1]; }
;             sol2[c >> 1][c & 1] = sp.x + sp.y; }
	v_pk_mul_f32 v[10:11], v[220:221], v[0:1] neg_lo:[1,0] neg_hi:[1,0]
	v_pk_mul_f32 v[16:17], v[230:231], v[0:1] neg_lo:[1,0] neg_hi:[1,0]
	v_add_f32_e32 v34, v34, v35
	v_pk_mul_f32 v[20:21], v[234:235], v[0:1] neg_lo:[1,0] neg_hi:[1,0]
	s_waitcnt lgkmcnt(4)
	v_pk_mul_f32 v[24:25], v[142:143], v[0:1] neg_lo:[1,0] neg_hi:[1,0]
	v_add_f32_e32 v38, v38, v39
	v_pk_fma_f32 v[10:11], v[222:223], v[8:9], v[10:11] neg_lo:[1,0,0] neg_hi:[1,0,0]
	ds_read_b128 v[220:223], v109 offset:7536
	v_pk_fma_f32 v[16:17], v[232:233], v[8:9], v[16:17] neg_lo:[1,0,0] neg_hi:[1,0,0]
	ds_read_b128 v[230:233], v109 offset:8224
	v_add_f32_e32 v42, v42, v43
	v_pk_fma_f32 v[20:21], v[236:237], v[8:9], v[20:21] neg_lo:[1,0,0] neg_hi:[1,0,0]
	ds_read_b128 v[234:237], v109 offset:8480
	v_pk_fma_f32 v[24:25], v[144:145], v[8:9], v[24:25] neg_lo:[1,0,0] neg_hi:[1,0,0]
	ds_read_b128 v[142:145], v109 offset:7792
	v_add_f32_e32 v70, v28, v70
	s_waitcnt lgkmcnt(5)
	v_pk_fma_f32 v[10:11], v[146:147], v[14:15], v[10:11] neg_lo:[1,0,0] neg_hi:[1,0,0]
	v_pk_fma_f32 v[16:17], v[150:151], v[14:15], v[16:17] neg_lo:[1,0,0] neg_hi:[1,0,0]
	v_add_f32_e32 v34, v34, v71
	v_pk_fma_f32 v[20:21], v[154:155], v[14:15], v[20:21] neg_lo:[1,0,0] neg_hi:[1,0,0]
	s_waitcnt lgkmcnt(4)
	v_pk_fma_f32 v[24:25], v[158:159], v[14:15], v[24:25] neg_lo:[1,0,0] neg_hi:[1,0,0]
	v_add_f32_e32 v38, v38, v112
	v_pk_fma_f32 v[10:11], v[148:149], v[18:19], v[10:11] neg_lo:[1,0,0] neg_hi:[1,0,0]
	ds_read_b128 v[146:149], v109 offset:8736
	v_pk_fma_f32 v[16:17], v[152:153], v[18:19], v[16:17] neg_lo:[1,0,0] neg_hi:[1,0,0]
	ds_read_b128 v[150:153], v109 offset:8992
	v_add_f32_e32 v42, v42, v113
	v_pk_fma_f32 v[20:21], v[156:157], v[18:19], v[20:21] neg_lo:[1,0,0] neg_hi:[1,0,0]
	ds_read_b128 v[154:157], v109 offset:8048
	v_pk_fma_f32 v[24:25], v[160:161], v[18:19], v[24:25] neg_lo:[1,0,0] neg_hi:[1,0,0]
	ds_read_b128 v[158:161], v109 offset:8240
	s_waitcnt lgkmcnt(4)
	v_fma_f32 v71, -v220, v70, v34
	ds_read_b128 v[220:223], v109 offset:8496
	v_pk_fma_f32 v[10:11], v[230:231], v[22:23], v[10:11] neg_lo:[1,0,0] neg_hi:[1,0,0]
	v_pk_fma_f32 v[16:17], v[234:235], v[22:23], v[16:17] neg_lo:[1,0,0] neg_hi:[1,0,0]
	v_fma_f32 v38, -v142, v70, v38
	s_waitcnt lgkmcnt(2)
	v_pk_fma_f32 v[20:21], v[146:147], v[22:23], v[20:21] neg_lo:[1,0,0] neg_hi:[1,0,0]
	v_pk_fma_f32 v[24:25], v[150:151], v[22:23], v[24:25] neg_lo:[1,0,0] neg_hi:[1,0,0]
	v_fma_f32 v42, -v154, v70, v42
	v_pk_fma_f32 v[10:11], v[232:233], v[26:27], v[10:11] neg_lo:[1,0,0] neg_hi:[1,0,0]
	ds_read_b128 v[230:233], v109 offset:8752
	v_pk_fma_f32 v[16:17], v[236:237], v[26:27], v[16:17] neg_lo:[1,0,0] neg_hi:[1,0,0]
	ds_read_b128 v[234:237], v109 offset:9008
	v_fma_f32 v112, -v143, v71, v38
	ds_read_b128 v[142:145], v109 offset:8256
	v_pk_fma_f32 v[20:21], v[148:149], v[26:27], v[20:21] neg_lo:[1,0,0] neg_hi:[1,0,0]
	ds_read_b128 v[146:149], v109 offset:8512
	v_pk_fma_f32 v[24:25], v[152:153], v[26:27], v[24:25] neg_lo:[1,0,0] neg_hi:[1,0,0]
	ds_read_b128 v[150:153], v109 offset:8768
	v_fma_f32 v42, -v155, v71, v42
	s_waitcnt lgkmcnt(4)
	v_pk_fma_f32 v[10:11], v[158:159], v[30:31], v[10:11] neg_lo:[1,0,0] neg_hi:[1,0,0]
	v_pk_fma_f32 v[16:17], v[220:221], v[30:31], v[16:17] neg_lo:[1,0,0] neg_hi:[1,0,0]
	v_fma_f32 v113, -v156, v112, v42
	ds_read_b128 v[154:157], v109 offset:9024
	v_pk_fma_f32 v[20:21], v[230:231], v[30:31], v[20:21] neg_lo:[1,0,0] neg_hi:[1,0,0]
	s_waitcnt lgkmcnt(4)
	v_pk_fma_f32 v[24:25], v[234:235], v[30:31], v[24:25] neg_lo:[1,0,0] neg_hi:[1,0,0]
	v_pk_fma_f32 v[10:11], v[160:161], v[36:37], v[10:11] neg_lo:[1,0,0] neg_hi:[1,0,0]
	ds_read_b128 v[158:161], v109 offset:8272
	v_pk_fma_f32 v[16:17], v[222:223], v[36:37], v[16:17] neg_lo:[1,0,0] neg_hi:[1,0,0]
	ds_read_b128 v[220:223], v109 offset:8528
	v_pk_fma_f32 v[20:21], v[232:233], v[36:37], v[20:21] neg_lo:[1,0,0] neg_hi:[1,0,0]
	ds_read_b128 v[230:233], v109 offset:8784
	v_pk_fma_f32 v[24:25], v[236:237], v[36:37], v[24:25] neg_lo:[1,0,0] neg_hi:[1,0,0]
	ds_read_b128 v[234:237], v109 offset:9040
	s_waitcnt lgkmcnt(4)
	v_pk_fma_f32 v[10:11], v[142:143], v[40:41], v[10:11] neg_lo:[1,0,0] neg_hi:[1,0,0]
	v_pk_fma_f32 v[16:17], v[146:147], v[40:41], v[16:17] neg_lo:[1,0,0] neg_hi:[1,0,0]
	v_pk_fma_f32 v[20:21], v[150:151], v[40:41], v[20:21] neg_lo:[1,0,0] neg_hi:[1,0,0]
	v_pk_fma_f32 v[24:25], v[154:155], v[40:41], v[24:25] neg_lo:[1,0,0] neg_hi:[1,0,0]
	v_pk_fma_f32 v[10:11], v[144:145], v[44:45], v[10:11] neg_lo:[1,0,0] neg_hi:[1,0,0]
	ds_read_b128 v[142:145], v109 offset:8288
	v_pk_fma_f32 v[16:17], v[148:149], v[44:45], v[16:17] neg_lo:[1,0,0] neg_hi:[1,0,0]
	ds_read_b128 v[146:149], v109 offset:8544
	v_pk_fma_f32 v[20:21], v[152:153], v[44:45], v[20:21] neg_lo:[1,0,0] neg_hi:[1,0,0]
	ds_read_b128 v[150:153], v109 offset:8800
	v_pk_fma_f32 v[24:25], v[156:157], v[44:45], v[24:25] neg_lo:[1,0,0] neg_hi:[1,0,0]
	ds_read_b128 v[154:157], v109 offset:9056
	s_waitcnt lgkmcnt(4)
	v_pk_fma_f32 v[10:11], v[158:159], v[50:51], v[10:11] neg_lo:[1,0,0] neg_hi:[1,0,0]
	v_pk_fma_f32 v[16:17], v[220:221], v[50:51], v[16:17] neg_lo:[1,0,0] neg_hi:[1,0,0]
	v_pk_fma_f32 v[20:21], v[230:231], v[50:51], v[20:21] neg_lo:[1,0,0] neg_hi:[1,0,0]
	v_pk_fma_f32 v[24:25], v[234:235], v[50:51], v[24:25] neg_lo:[1,0,0] neg_hi:[1,0,0]
	v_pk_fma_f32 v[10:11], v[160:161], v[54:55], v[10:11] neg_lo:[1,0,0] neg_hi:[1,0,0]
	ds_read_b128 v[158:161], v109 offset:8304
	v_pk_fma_f32 v[16:17], v[222:223], v[54:55], v[16:17] neg_lo:[1,0,0] neg_hi:[1,0,0]
	ds_read_b128 v[220:223], v109 offset:8560
	v_pk_fma_f32 v[20:21], v[232:233], v[54:55], v[20:21] neg_lo:[1,0,0] neg_hi:[1,0,0]
	ds_read_b128 v[230:233], v109 offset:8816
	v_pk_fma_f32 v[24:25], v[236:237], v[54:55], v[24:25] neg_lo:[1,0,0] neg_hi:[1,0,0]
	ds_read_b128 v[234:237], v109 offset:9072
	s_waitcnt lgkmcnt(4)
; #define LAS __attribute__((address_space(3)))
; __device__ __forceinline__ void gdn_local_unit(LAS unsigned char* lds, const GdnP& P, int unit, const int tid, const int pf) {
;     ...
; #pragma unroll
;         for (int c = 1; c < 64; ++c) { f32x2 sp = (f32x2){sol2[c >> 1][c & 1], 0.f};
; #pragma unroll
;             for (int jb = 0; jb <= (c - 1) / 4; ++jb) { const f32x4 m4 = *(const LAS f32x4*)(Ms + c * 64 + 4 * jb);
;                 sp -= (f32x2){m4.x, m4.y} * sol2[2 * jb]; sp -= (f32x2){m4.z, m4.w} * sol2[2 * jb + 1]; }
;             sol2[c >> 1][c & 1] = sp.x + sp.y; }
	v_pk_fma_f32 v[10:11], v[142:143], v[60:61], v[10:11] neg_lo:[1,0,0] neg_hi:[1,0,0]
	v_pk_fma_f32 v[16:17], v[146:147], v[60:61], v[16:17] neg_lo:[1,0,0] neg_hi:[1,0,0]
	v_pk_fma_f32 v[20:21], v[150:151], v[60:61], v[20:21] neg_lo:[1,0,0] neg_hi:[1,0,0]
	v_pk_fma_f32 v[24:25], v[154:155], v[60:61], v[24:25] neg_lo:[1,0,0] neg_hi:[1,0,0]
	v_pk_fma_f32 v[10:11], v[144:145], v[64:65], v[10:11] neg_lo:[1,0,0] neg_hi:[1,0,0]
	ds_read_b128 v[142:145], v109 offset:9216
	v_pk_fma_f32 v[16:17], v[148:149], v[64:65], v[16:17] neg_lo:[1,0,0] neg_hi:[1,0,0]
	ds_read_b128 v[146:149], v109 offset:9472
	v_pk_fma_f32 v[20:21], v[152:153], v[64:65], v[20:21] neg_lo:[1,0,0] neg_hi:[1,0,0]
	ds_read_b128 v[150:153], v109 offset:9728
	v_pk_fma_f32 v[24:25], v[156:157], v[64:65], v[24:25] neg_lo:[1,0,0] neg_hi:[1,0,0]
	ds_read_b128 v[154:157], v109 offset:9984
	s_waitcnt lgkmcnt(4)
	v_pk_fma_f32 v[10:11], v[158:159], v[70:71], v[10:11] neg_lo:[1,0,0] neg_hi:[1,0,0]
	v_pk_fma_f32 v[16:17], v[220:221], v[70:71], v[16:17] neg_lo:[1,0,0] neg_hi:[1,0,0]
	v_pk_fma_f32 v[20:21], v[230:231], v[70:71], v[20:21] neg_lo:[1,0,0] neg_hi:[1,0,0]
	v_pk_fma_f32 v[24:25], v[234:235], v[70:71], v[24:25] neg_lo:[1,0,0] neg_hi:[1,0,0]
	v_pk_fma_f32 v[10:11], v[160:161], v[112:113], v[10:11] neg_lo:[1,0,0] neg_hi:[1,0,0]
	ds_read_b128 v[158:161], v109 offset:9232
	v_pk_fma_f32 v[16:17], v[222:223], v[112:113], v[16:17] neg_lo:[1,0,0] neg_hi:[1,0,0]
	ds_read_b128 v[220:223], v109 offset:9488
	v_pk_fma_f32 v[20:21], v[232:233], v[112:113], v[20:21] neg_lo:[1,0,0] neg_hi:[1,0,0]
	ds_read_b128 v[230:233], v109 offset:9744
	v_pk_fma_f32 v[24:25], v[236:237], v[112:113], v[24:25] neg_lo:[1,0,0] neg_hi:[1,0,0]
	ds_read_b128 v[234:237], v109 offset:10000
	v_add_f32_e32 v10, v10, v11
	s_waitcnt lgkmcnt(5)
	v_pk_mul_f32 v[28:29], v[142:143], v[0:1] neg_lo:[1,0] neg_hi:[1,0]
	v_pk_mul_f32 v[34:35], v[146:147], v[0:1] neg_lo:[1,0] neg_hi:[1,0]
	v_add_f32_e32 v16, v16, v17
	v_pk_mul_f32 v[38:39], v[150:151], v[0:1] neg_lo:[1,0] neg_hi:[1,0]
	s_waitcnt lgkmcnt(4)
	v_pk_mul_f32 v[42:43], v[154:155], v[0:1] neg_lo:[1,0] neg_hi:[1,0]
	v_add_f32_e32 v20, v20, v21
	v_pk_fma_f32 v[28:29], v[144:145], v[8:9], v[28:29] neg_lo:[1,0,0] neg_hi:[1,0,0]
	ds_read_b128 v[142:145], v109 offset:8576
	v_pk_fma_f32 v[34:35], v[148:149], v[8:9], v[34:35] neg_lo:[1,0,0] neg_hi:[1,0,0]
	ds_read_b128 v[146:149], v109 offset:9248
	v_add_f32_e32 v24, v24, v25
	v_pk_fma_f32 v[38:39], v[152:153], v[8:9], v[38:39] neg_lo:[1,0,0] neg_hi:[1,0,0]
	ds_read_b128 v[150:153], v109 offset:9504
	v_pk_fma_f32 v[42:43], v[156:157], v[8:9], v[42:43] neg_lo:[1,0,0] neg_hi:[1,0,0]
	ds_read_b128 v[154:157], v109 offset:8832
	v_add_f32_e32 v116, v10, v116
	s_waitcnt lgkmcnt(5)
	v_pk_fma_f32 v[28:29], v[158:159], v[14:15], v[28:29] neg_lo:[1,0,0] neg_hi:[1,0,0]
	v_pk_fma_f32 v[34:35], v[220:221], v[14:15], v[34:35] neg_lo:[1,0,0] neg_hi:[1,0,0]
	v_add_f32_e32 v16, v16, v117
	v_pk_fma_f32 v[38:39], v[230:231], v[14:15], v[38:39] neg_lo:[1,0,0] neg_hi:[1,0,0]
	s_waitcnt lgkmcnt(4)
	v_pk_fma_f32 v[42:43], v[234:235], v[14:15], v[42:43] neg_lo:[1,0,0] neg_hi:[1,0,0]
	v_add_f32_e32 v20, v20, v122
	v_pk_fma_f32 v[28:29], v[160:161], v[18:19], v[28:29] neg_lo:[1,0,0] neg_hi:[1,0,0]
	ds_read_b128 v[158:161], v109 offset:9760
	v_pk_fma_f32 v[34:35], v[222:223], v[18:19], v[34:35] neg_lo:[1,0,0] neg_hi:[1,0,0]
	ds_read_b128 v[220:223], v109 offset:10016
	v_add_f32_e32 v24, v24, v123
	v_pk_fma_f32 v[38:39], v[232:233], v[18:19], v[38:39] neg_lo:[1,0,0] neg_hi:[1,0,0]
	ds_read_b128 v[230:233], v109 offset:9088
	v_pk_fma_f32 v[42:43], v[236:237], v[18:19], v[42:43] neg_lo:[1,0,0] neg_hi:[1,0,0]
	ds_read_b128 v[234:237], v109 offset:9264
	s_waitcnt lgkmcnt(4)
	v_fma_f32 v117, -v142, v116, v16
	ds_read_b128 v[142:145], v109 offset:9520
	v_pk_fma_f32 v[28:29], v[146:147], v[22:23], v[28:29] neg_lo:[1,0,0] neg_hi:[1,0,0]
	v_pk_fma_f32 v[34:35], v[150:151], v[22:23], v[34:35] neg_lo:[1,0,0] neg_hi:[1,0,0]
	v_fma_f32 v20, -v154, v116, v20
	s_waitcnt lgkmcnt(2)
	v_pk_fma_f32 v[38:39], v[158:159], v[22:23], v[38:39] neg_lo:[1,0,0] neg_hi:[1,0,0]
	v_pk_fma_f32 v[42:43], v[220:221], v[22:23], v[42:43] neg_lo:[1,0,0] neg_hi:[1,0,0]
	v_fma_f32 v24, -v230, v116, v24
	v_pk_fma_f32 v[28:29], v[148:149], v[26:27], v[28:29] neg_lo:[1,0,0] neg_hi:[1,0,0]
	ds_read_b128 v[146:149], v109 offset:9776
	v_pk_fma_f32 v[34:35], v[152:153], v[26:27], v[34:35] neg_lo:[1,0,0] neg_hi:[1,0,0]
	ds_read_b128 v[150:153], v109 offset:10032
	v_fma_f32 v122, -v155, v117, v20
	ds_read_b128 v[154:157], v109 offset:9280
	v_pk_fma_f32 v[38:39], v[160:161], v[26:27], v[38:39] neg_lo:[1,0,0] neg_hi:[1,0,0]
	ds_read_b128 v[158:161], v109 offset:9536
	v_pk_fma_f32 v[42:43], v[222:223], v[26:27], v[42:43] neg_lo:[1,0,0] neg_hi:[1,0,0]
	ds_read_b128 v[220:223], v109 offset:9792
	v_fma_f32 v24, -v231, v117, v24
	s_waitcnt lgkmcnt(4)
	v_pk_fma_f32 v[28:29], v[234:235], v[30:31], v[28:29] neg_lo:[1,0,0] neg_hi:[1,0,0]
	v_pk_fma_f32 v[34:35], v[142:143], v[30:31], v[34:35] neg_lo:[1,0,0] neg_hi:[1,0,0]
	v_fma_f32 v123, -v232, v122, v24
	ds_read_b128 v[230:233], v109 offset:10048
	v_pk_fma_f32 v[38:39], v[146:147], v[30:31], v[38:39] neg_lo:[1,0,0] neg_hi:[1,0,0]
	s_waitcnt lgkmcnt(4)
	v_pk_fma_f32 v[42:43], v[150:151], v[30:31], v[42:43] neg_lo:[1,0,0] neg_hi:[1,0,0]
	v_pk_fma_f32 v[28:29], v[236:237], v[36:37], v[28:29] neg_lo:[1,0,0] neg_hi:[1,0,0]
	ds_read_b128 v[234:237], v109 offset:9296
	v_pk_fma_f32 v[34:35], v[144:145], v[36:37], v[34:35] neg_lo:[1,0,0] neg_hi:[1,0,0]
	ds_read_b128 v[142:145], v109 offset:9552
	v_pk_fma_f32 v[38:39], v[148:149], v[36:37], v[38:39] neg_lo:[1,0,0] neg_hi:[1,0,0]
	ds_read_b128 v[146:149], v109 offset:9808
	v_pk_fma_f32 v[42:43], v[152:153], v[36:37], v[42:43] neg_lo:[1,0,0] neg_hi:[1,0,0]
	ds_read_b128 v[150:153], v109 offset:10064
	s_waitcnt lgkmcnt(4)
; #define LAS __attribute__((address_space(3)))
; __device__ __forceinline__ void gdn_local_unit(LAS unsigned char* lds, const GdnP& P, int unit, const int tid, const int pf) {
;     ...
; #pragma unroll
;         for (int c = 1; c < 64; ++c) { f32x2 sp = (f32x2){sol2[c >> 1][c & 1], 0.f};
; #pragma unroll
;             for (int jb = 0; jb <= (c - 1) / 4; ++jb) { const f32x4 m4 = *(const LAS f32x4*)(Ms + c * 64 + 4 * jb);
;                 sp -= (f32x2){m4.x, m4.y} * sol2[2 * jb]; sp -= (f32x2){m4.z, m4.w} * sol2[2 * jb + 1]; }
;             sol2[c >> 1][c & 1] = sp.x + sp.y; }
	v_pk_fma_f32 v[28:29], v[154:155], v[40:41], v[28:29] neg_lo:[1,0,0] neg_hi:[1,0,0]
	v_pk_fma_f32 v[34:35], v[158:159], v[40:41], v[34:35] neg_lo:[1,0,0] neg_hi:[1,0,0]
	v_pk_fma_f32 v[38:39], v[220:221], v[40:41], v[38:39] neg_lo:[1,0,0] neg_hi:[1,0,0]
	v_pk_fma_f32 v[42:43], v[230:231], v[40:41], v[42:43] neg_lo:[1,0,0] neg_hi:[1,0,0]
	v_pk_fma_f32 v[28:29], v[156:157], v[44:45], v[28:29] neg_lo:[1,0,0] neg_hi:[1,0,0]
	ds_read_b128 v[154:157], v109 offset:9312
	v_pk_fma_f32 v[34:35], v[160:161], v[44:45], v[34:35] neg_lo:[1,0,0] neg_hi:[1,0,0]
	ds_read_b128 v[158:161], v109 offset:9568
	v_pk_fma_f32 v[38:39], v[222:223], v[44:45], v[38:39] neg_lo:[1,0,0] neg_hi:[1,0,0]
	ds_read_b128 v[220:223], v109 offset:9824
	v_pk_fma_f32 v[42:43], v[232:233], v[44:45], v[42:43] neg_lo:[1,0,0] neg_hi:[1,0,0]
	ds_read_b128 v[230:233], v109 offset:10080
	s_waitcnt lgkmcnt(4)
	v_pk_fma_f32 v[28:29], v[234:235], v[50:51], v[28:29] neg_lo:[1,0,0] neg_hi:[1,0,0]
	v_pk_fma_f32 v[34:35], v[142:143], v[50:51], v[34:35] neg_lo:[1,0,0] neg_hi:[1,0,0]
	v_pk_fma_f32 v[38:39], v[146:147], v[50:51], v[38:39] neg_lo:[1,0,0] neg_hi:[1,0,0]
	v_pk_fma_f32 v[42:43], v[150:151], v[50:51], v[42:43] neg_lo:[1,0,0] neg_hi:[1,0,0]
	v_pk_fma_f32 v[28:29], v[236:237], v[54:55], v[28:29] neg_lo:[1,0,0] neg_hi:[1,0,0]
	ds_read_b128 v[234:237], v109 offset:9328
	v_pk_fma_f32 v[34:35], v[144:145], v[54:55], v[34:35] neg_lo:[1,0,0] neg_hi:[1,0,0]
	ds_read_b128 v[142:145], v109 offset:9584
	v_pk_fma_f32 v[38:39], v[148:149], v[54:55], v[38:39] neg_lo:[1,0,0] neg_hi:[1,0,0]
	ds_read_b128 v[146:149], v109 offset:9840
	v_pk_fma_f32 v[42:43], v[152:153], v[54:55], v[42:43] neg_lo:[1,0,0] neg_hi:[1,0,0]
	ds_read_b128 v[150:153], v109 offset:10096
	s_waitcnt lgkmcnt(4)
	v_pk_fma_f32 v[28:29], v[154:155], v[60:61], v[28:29] neg_lo:[1,0,0] neg_hi:[1,0,0]
	v_pk_fma_f32 v[34:35], v[158:159], v[60:61], v[34:35] neg_lo:[1,0,0] neg_hi:[1,0,0]
	v_pk_fma_f32 v[38:39], v[220:221], v[60:61], v[38:39] neg_lo:[1,0,0] neg_hi:[1,0,0]
	v_pk_fma_f32 v[42:43], v[230:231], v[60:61], v[42:43] neg_lo:[1,0,0] neg_hi:[1,0,0]
	v_pk_fma_f32 v[28:29], v[156:157], v[64:65], v[28:29] neg_lo:[1,0,0] neg_hi:[1,0,0]
	ds_read_b128 v[154:157], v109 offset:9344
	v_pk_fma_f32 v[34:35], v[160:161], v[64:65], v[34:35] neg_lo:[1,0,0] neg_hi:[1,0,0]
	ds_read_b128 v[158:161], v109 offset:9600
	v_pk_fma_f32 v[38:39], v[222:223], v[64:65], v[38:39] neg_lo:[1,0,0] neg_hi:[1,0,0]
	ds_read_b128 v[220:223], v109 offset:9856
	v_pk_fma_f32 v[42:43], v[232:233], v[64:65], v[42:43] neg_lo:[1,0,0] neg_hi:[1,0,0]
	ds_read_b128 v[230:233], v109 offset:10112
	s_waitcnt lgkmcnt(4)
	v_pk_fma_f32 v[28:29], v[234:235], v[70:71], v[28:29] neg_lo:[1,0,0] neg_hi:[1,0,0]
	v_pk_fma_f32 v[34:35], v[142:143], v[70:71], v[34:35] neg_lo:[1,0,0] neg_hi:[1,0,0]
	v_pk_fma_f32 v[38:39], v[146:147], v[70:71], v[38:39] neg_lo:[1,0,0] neg_hi:[1,0,0]
	v_pk_fma_f32 v[42:43], v[150:151], v[70:71], v[42:43] neg_lo:[1,0,0] neg_hi:[1,0,0]
	v_pk_fma_f32 v[28:29], v[236:237], v[112:113], v[28:29] neg_lo:[1,0,0] neg_hi:[1,0,0]
	ds_read_b128 v[234:237], v109 offset:10240
	v_pk_fma_f32 v[34:35], v[144:145], v[112:113], v[34:35] neg_lo:[1,0,0] neg_hi:[1,0,0]
	ds_read_b128 v[142:145], v109 offset:10496
	v_pk_fma_f32 v[38:39], v[148:149], v[112:113], v[38:39] neg_lo:[1,0,0] neg_hi:[1,0,0]
	ds_read_b128 v[146:149], v109 offset:10752
	v_pk_fma_f32 v[42:43], v[152:153], v[112:113], v[42:43] neg_lo:[1,0,0] neg_hi:[1,0,0]
	ds_read_b128 v[150:153], v109 offset:11008
	s_waitcnt lgkmcnt(4)
	v_pk_fma_f32 v[28:29], v[154:155], v[116:117], v[28:29] neg_lo:[1,0,0] neg_hi:[1,0,0]
	v_pk_fma_f32 v[34:35], v[158:159], v[116:117], v[34:35] neg_lo:[1,0,0] neg_hi:[1,0,0]
	v_pk_fma_f32 v[38:39], v[220:221], v[116:117], v[38:39] neg_lo:[1,0,0] neg_hi:[1,0,0]
	v_pk_fma_f32 v[42:43], v[230:231], v[116:117], v[42:43] neg_lo:[1,0,0] neg_hi:[1,0,0]
	v_pk_fma_f32 v[28:29], v[156:157], v[122:123], v[28:29] neg_lo:[1,0,0] neg_hi:[1,0,0]
	ds_read_b128 v[154:157], v109 offset:10256
	v_pk_fma_f32 v[34:35], v[160:161], v[122:123], v[34:35] neg_lo:[1,0,0] neg_hi:[1,0,0]
	ds_read_b128 v[158:161], v109 offset:10512
	v_pk_fma_f32 v[38:39], v[222:223], v[122:123], v[38:39] neg_lo:[1,0,0] neg_hi:[1,0,0]
	ds_read_b128 v[220:223], v109 offset:10768
	v_pk_fma_f32 v[42:43], v[232:233], v[122:123], v[42:43] neg_lo:[1,0,0] neg_hi:[1,0,0]
	ds_read_b128 v[230:233], v109 offset:11024
	v_add_f32_e32 v28, v28, v29
	s_waitcnt lgkmcnt(5)
	v_pk_mul_f32 v[10:11], v[234:235], v[0:1] neg_lo:[1,0] neg_hi:[1,0]
	v_pk_mul_f32 v[16:17], v[142:143], v[0:1] neg_lo:[1,0] neg_hi:[1,0]
	v_add_f32_e32 v34, v34, v35
	v_pk_mul_f32 v[20:21], v[146:147], v[0:1] neg_lo:[1,0] neg_hi:[1,0]
	s_waitcnt lgkmcnt(4)
	v_pk_mul_f32 v[24:25], v[150:151], v[0:1] neg_lo:[1,0] neg_hi:[1,0]
	v_add_f32_e32 v38, v38, v39
	v_pk_fma_f32 v[10:11], v[236:237], v[8:9], v[10:11] neg_lo:[1,0,0] neg_hi:[1,0,0]
	ds_read_b128 v[234:237], v109 offset:9616
	v_pk_fma_f32 v[16:17], v[144:145], v[8:9], v[16:17] neg_lo:[1,0,0] neg_hi:[1,0,0]
	ds_read_b128 v[142:145], v109 offset:10272
	v_add_f32_e32 v42, v42, v43
	v_pk_fma_f32 v[20:21], v[148:149], v[8:9], v[20:21] neg_lo:[1,0,0] neg_hi:[1,0,0]
	ds_read_b128 v[146:149], v109 offset:10528
	v_pk_fma_f32 v[24:25], v[152:153], v[8:9], v[24:25] neg_lo:[1,0,0] neg_hi:[1,0,0]
	ds_read_b128 v[150:153], v109 offset:9872
	v_add_f32_e32 v128, v28, v128
	s_waitcnt lgkmcnt(5)
	v_pk_fma_f32 v[10:11], v[154:155], v[14:15], v[10:11] neg_lo:[1,0,0] neg_hi:[1,0,0]
	v_pk_fma_f32 v[16:17], v[158:159], v[14:15], v[16:17] neg_lo:[1,0,0] neg_hi:[1,0,0]
	v_add_f32_e32 v34, v34, v129
	v_pk_fma_f32 v[20:21], v[220:221], v[14:15], v[20:21] neg_lo:[1,0,0] neg_hi:[1,0,0]
	s_waitcnt lgkmcnt(4)
; #define LAS __attribute__((address_space(3)))
; __device__ __forceinline__ void gdn_local_unit(LAS unsigned char* lds, const GdnP& P, int unit, const int tid, const int pf) {
;     ...
; #pragma unroll
;         for (int c = 1; c < 64; ++c) { f32x2 sp = (f32x2){sol2[c >> 1][c & 1], 0.f};
; #pragma unroll
;             for (int jb = 0; jb <= (c - 1) / 4; ++jb) { const f32x4 m4 = *(const LAS f32x4*)(Ms + c * 64 + 4 * jb);
;                 sp -= (f32x2){m4.x, m4.y} * sol2[2 * jb]; sp -= (f32x2){m4.z, m4.w} * sol2[2 * jb + 1]; }
;             sol2[c >> 1][c & 1] = sp.x + sp.y; }
	v_pk_fma_f32 v[24:25], v[230:231], v[14:15], v[24:25] neg_lo:[1,0,0] neg_hi:[1,0,0]
	v_add_f32_e32 v38, v38, v134
	v_pk_fma_f32 v[10:11], v[156:157], v[18:19], v[10:11] neg_lo:[1,0,0] neg_hi:[1,0,0]
	ds_read_b128 v[154:157], v109 offset:10784
	v_pk_fma_f32 v[16:17], v[160:161], v[18:19], v[16:17] neg_lo:[1,0,0] neg_hi:[1,0,0]
	ds_read_b128 v[158:161], v109 offset:11040
	v_add_f32_e32 v42, v42, v135
	v_pk_fma_f32 v[20:21], v[222:223], v[18:19], v[20:21] neg_lo:[1,0,0] neg_hi:[1,0,0]
	ds_read_b128 v[220:223], v109 offset:10128
	v_pk_fma_f32 v[24:25], v[232:233], v[18:19], v[24:25] neg_lo:[1,0,0] neg_hi:[1,0,0]
	ds_read_b128 v[230:233], v109 offset:10288
	s_waitcnt lgkmcnt(4)
	v_fma_f32 v129, -v234, v128, v34
	ds_read_b128 v[234:237], v109 offset:10544
	v_pk_fma_f32 v[10:11], v[142:143], v[22:23], v[10:11] neg_lo:[1,0,0] neg_hi:[1,0,0]
	v_pk_fma_f32 v[16:17], v[146:147], v[22:23], v[16:17] neg_lo:[1,0,0] neg_hi:[1,0,0]
	v_fma_f32 v38, -v150, v128, v38
	s_waitcnt lgkmcnt(2)
	v_pk_fma_f32 v[20:21], v[154:155], v[22:23], v[20:21] neg_lo:[1,0,0] neg_hi:[1,0,0]
	v_pk_fma_f32 v[24:25], v[158:159], v[22:23], v[24:25] neg_lo:[1,0,0] neg_hi:[1,0,0]
	v_fma_f32 v42, -v220, v128, v42
	v_pk_fma_f32 v[10:11], v[144:145], v[26:27], v[10:11] neg_lo:[1,0,0] neg_hi:[1,0,0]
	ds_read_b128 v[142:145], v109 offset:10800
	v_pk_fma_f32 v[16:17], v[148:149], v[26:27], v[16:17] neg_lo:[1,0,0] neg_hi:[1,0,0]
	ds_read_b128 v[146:149], v109 offset:11056
	v_fma_f32 v134, -v151, v129, v38
	ds_read_b128 v[150:153], v109 offset:10304
	v_pk_fma_f32 v[20:21], v[156:157], v[26:27], v[20:21] neg_lo:[1,0,0] neg_hi:[1,0,0]
	ds_read_b128 v[154:157], v109 offset:10560
	v_pk_fma_f32 v[24:25], v[160:161], v[26:27], v[24:25] neg_lo:[1,0,0] neg_hi:[1,0,0]
	ds_read_b128 v[158:161], v109 offset:10816
	v_fma_f32 v42, -v221, v129, v42
	s_waitcnt lgkmcnt(4)
	v_pk_fma_f32 v[10:11], v[230:231], v[30:31], v[10:11] neg_lo:[1,0,0] neg_hi:[1,0,0]
	v_pk_fma_f32 v[16:17], v[234:235], v[30:31], v[16:17] neg_lo:[1,0,0] neg_hi:[1,0,0]
	v_fma_f32 v135, -v222, v134, v42
	ds_read_b128 v[220:223], v109 offset:11072
	v_pk_fma_f32 v[20:21], v[142:143], v[30:31], v[20:21] neg_lo:[1,0,0] neg_hi:[1,0,0]
	s_waitcnt lgkmcnt(4)
	v_pk_fma_f32 v[24:25], v[146:147], v[30:31], v[24:25] neg_lo:[1,0,0] neg_hi:[1,0,0]
	v_pk_fma_f32 v[10:11], v[232:233], v[36:37], v[10:11] neg_lo:[1,0,0] neg_hi:[1,0,0]
	ds_read_b128 v[230:233], v109 offset:10320
	v_pk_fma_f32 v[16:17], v[236:237], v[36:37], v[16:17] neg_lo:[1,0,0] neg_hi:[1,0,0]
	ds_read_b128 v[234:237], v109 offset:10576
	v_pk_fma_f32 v[20:21], v[144:145], v[36:37], v[20:21] neg_lo:[1,0,0] neg_hi:[1,0,0]
	ds_read_b128 v[142:145], v109 offset:10832
	v_pk_fma_f32 v[24:25], v[148:149], v[36:37], v[24:25] neg_lo:[1,0,0] neg_hi:[1,0,0]
	ds_read_b128 v[146:149], v109 offset:11088
	s_waitcnt lgkmcnt(4)
	v_pk_fma_f32 v[10:11], v[150:151], v[40:41], v[10:11] neg_lo:[1,0,0] neg_hi:[1,0,0]
	v_pk_fma_f32 v[16:17], v[154:155], v[40:41], v[16:17] neg_lo:[1,0,0] neg_hi:[1,0,0]
	v_pk_fma_f32 v[20:21], v[158:159], v[40:41], v[20:21] neg_lo:[1,0,0] neg_hi:[1,0,0]
	v_pk_fma_f32 v[24:25], v[220:221], v[40:41], v[24:25] neg_lo:[1,0,0] neg_hi:[1,0,0]
	v_pk_fma_f32 v[10:11], v[152:153], v[44:45], v[10:11] neg_lo:[1,0,0] neg_hi:[1,0,0]
	ds_read_b128 v[150:153], v109 offset:10336
	v_pk_fma_f32 v[16:17], v[156:157], v[44:45], v[16:17] neg_lo:[1,0,0] neg_hi:[1,0,0]
	ds_read_b128 v[154:157], v109 offset:10592
	v_pk_fma_f32 v[20:21], v[160:161], v[44:45], v[20:21] neg_lo:[1,0,0] neg_hi:[1,0,0]
	ds_read_b128 v[158:161], v109 offset:10848
	v_pk_fma_f32 v[24:25], v[222:223], v[44:45], v[24:25] neg_lo:[1,0,0] neg_hi:[1,0,0]
	ds_read_b128 v[220:223], v109 offset:11104
	s_waitcnt lgkmcnt(4)
	v_pk_fma_f32 v[10:11], v[230:231], v[50:51], v[10:11] neg_lo:[1,0,0] neg_hi:[1,0,0]
	v_pk_fma_f32 v[16:17], v[234:235], v[50:51], v[16:17] neg_lo:[1,0,0] neg_hi:[1,0,0]
	v_pk_fma_f32 v[20:21], v[142:143], v[50:51], v[20:21] neg_lo:[1,0,0] neg_hi:[1,0,0]
	v_pk_fma_f32 v[24:25], v[146:147], v[50:51], v[24:25] neg_lo:[1,0,0] neg_hi:[1,0,0]
	v_pk_fma_f32 v[10:11], v[232:233], v[54:55], v[10:11] neg_lo:[1,0,0] neg_hi:[1,0,0]
	ds_read_b128 v[230:233], v109 offset:10352
	v_pk_fma_f32 v[16:17], v[236:237], v[54:55], v[16:17] neg_lo:[1,0,0] neg_hi:[1,0,0]
	ds_read_b128 v[234:237], v109 offset:10608
	v_pk_fma_f32 v[20:21], v[144:145], v[54:55], v[20:21] neg_lo:[1,0,0] neg_hi:[1,0,0]
	ds_read_b128 v[142:145], v109 offset:10864
	v_pk_fma_f32 v[24:25], v[148:149], v[54:55], v[24:25] neg_lo:[1,0,0] neg_hi:[1,0,0]
	ds_read_b128 v[146:149], v109 offset:11120
	s_waitcnt lgkmcnt(4)
	v_pk_fma_f32 v[10:11], v[150:151], v[60:61], v[10:11] neg_lo:[1,0,0] neg_hi:[1,0,0]
	v_pk_fma_f32 v[16:17], v[154:155], v[60:61], v[16:17] neg_lo:[1,0,0] neg_hi:[1,0,0]
	v_pk_fma_f32 v[20:21], v[158:159], v[60:61], v[20:21] neg_lo:[1,0,0] neg_hi:[1,0,0]
	v_pk_fma_f32 v[24:25], v[220:221], v[60:61], v[24:25] neg_lo:[1,0,0] neg_hi:[1,0,0]
	v_pk_fma_f32 v[10:11], v[152:153], v[64:65], v[10:11] neg_lo:[1,0,0] neg_hi:[1,0,0]
	ds_read_b128 v[150:153], v109 offset:10368
	v_pk_fma_f32 v[16:17], v[156:157], v[64:65], v[16:17] neg_lo:[1,0,0] neg_hi:[1,0,0]
	ds_read_b128 v[154:157], v109 offset:10624
	v_pk_fma_f32 v[20:21], v[160:161], v[64:65], v[20:21] neg_lo:[1,0,0] neg_hi:[1,0,0]
	ds_read_b128 v[158:161], v109 offset:10880
	v_pk_fma_f32 v[24:25], v[222:223], v[64:65], v[24:25] neg_lo:[1,0,0] neg_hi:[1,0,0]
	ds_read_b128 v[220:223], v109 offset:11136
	s_waitcnt lgkmcnt(4)
; #define LAS __attribute__((address_space(3)))
; __device__ __forceinline__ void gdn_local_unit(LAS unsigned char* lds, const GdnP& P, int unit, const int tid, const int pf) {
;     ...
; #pragma unroll
;         for (int c = 1; c < 64; ++c) { f32x2 sp = (f32x2){sol2[c >> 1][c & 1], 0.f};
; #pragma unroll
;             for (int jb = 0; jb <= (c - 1) / 4; ++jb) { const f32x4 m4 = *(const LAS f32x4*)(Ms + c * 64 + 4 * jb);
;                 sp -= (f32x2){m4.x, m4.y} * sol2[2 * jb]; sp -= (f32x2){m4.z, m4.w} * sol2[2 * jb + 1]; }
;             sol2[c >> 1][c & 1] = sp.x + sp.y; }
	v_pk_fma_f32 v[10:11], v[230:231], v[70:71], v[10:11] neg_lo:[1,0,0] neg_hi:[1,0,0]
	v_pk_fma_f32 v[16:17], v[234:235], v[70:71], v[16:17] neg_lo:[1,0,0] neg_hi:[1,0,0]
	v_pk_fma_f32 v[20:21], v[142:143], v[70:71], v[20:21] neg_lo:[1,0,0] neg_hi:[1,0,0]
	v_pk_fma_f32 v[24:25], v[146:147], v[70:71], v[24:25] neg_lo:[1,0,0] neg_hi:[1,0,0]
	v_pk_fma_f32 v[10:11], v[232:233], v[112:113], v[10:11] neg_lo:[1,0,0] neg_hi:[1,0,0]
	ds_read_b128 v[230:233], v109 offset:10384
	v_pk_fma_f32 v[16:17], v[236:237], v[112:113], v[16:17] neg_lo:[1,0,0] neg_hi:[1,0,0]
	ds_read_b128 v[234:237], v109 offset:10640
	v_pk_fma_f32 v[20:21], v[144:145], v[112:113], v[20:21] neg_lo:[1,0,0] neg_hi:[1,0,0]
	ds_read_b128 v[142:145], v109 offset:10896
	v_pk_fma_f32 v[24:25], v[148:149], v[112:113], v[24:25] neg_lo:[1,0,0] neg_hi:[1,0,0]
	ds_read_b128 v[146:149], v109 offset:11152
	s_waitcnt lgkmcnt(4)
	v_pk_fma_f32 v[10:11], v[150:151], v[116:117], v[10:11] neg_lo:[1,0,0] neg_hi:[1,0,0]
	v_pk_fma_f32 v[16:17], v[154:155], v[116:117], v[16:17] neg_lo:[1,0,0] neg_hi:[1,0,0]
	v_pk_fma_f32 v[20:21], v[158:159], v[116:117], v[20:21] neg_lo:[1,0,0] neg_hi:[1,0,0]
	v_pk_fma_f32 v[24:25], v[220:221], v[116:117], v[24:25] neg_lo:[1,0,0] neg_hi:[1,0,0]
	v_pk_fma_f32 v[10:11], v[152:153], v[122:123], v[10:11] neg_lo:[1,0,0] neg_hi:[1,0,0]
	ds_read_b128 v[150:153], v109 offset:11264
	v_pk_fma_f32 v[16:17], v[156:157], v[122:123], v[16:17] neg_lo:[1,0,0] neg_hi:[1,0,0]
	ds_read_b128 v[154:157], v109 offset:11520
	v_pk_fma_f32 v[20:21], v[160:161], v[122:123], v[20:21] neg_lo:[1,0,0] neg_hi:[1,0,0]
	ds_read_b128 v[158:161], v109 offset:11776
	v_pk_fma_f32 v[24:25], v[222:223], v[122:123], v[24:25] neg_lo:[1,0,0] neg_hi:[1,0,0]
	ds_read_b128 v[220:223], v109 offset:12032
	s_waitcnt lgkmcnt(4)
	v_pk_fma_f32 v[10:11], v[230:231], v[128:129], v[10:11] neg_lo:[1,0,0] neg_hi:[1,0,0]
	v_pk_fma_f32 v[16:17], v[234:235], v[128:129], v[16:17] neg_lo:[1,0,0] neg_hi:[1,0,0]
	v_pk_fma_f32 v[20:21], v[142:143], v[128:129], v[20:21] neg_lo:[1,0,0] neg_hi:[1,0,0]
	v_pk_fma_f32 v[24:25], v[146:147], v[128:129], v[24:25] neg_lo:[1,0,0] neg_hi:[1,0,0]
	v_pk_fma_f32 v[10:11], v[232:233], v[134:135], v[10:11] neg_lo:[1,0,0] neg_hi:[1,0,0]
	ds_read_b128 v[230:233], v109 offset:11280
	v_pk_fma_f32 v[16:17], v[236:237], v[134:135], v[16:17] neg_lo:[1,0,0] neg_hi:[1,0,0]
	ds_read_b128 v[234:237], v109 offset:11536
	v_pk_fma_f32 v[20:21], v[144:145], v[134:135], v[20:21] neg_lo:[1,0,0] neg_hi:[1,0,0]
	ds_read_b128 v[142:145], v109 offset:11792
	v_pk_fma_f32 v[24:25], v[148:149], v[134:135], v[24:25] neg_lo:[1,0,0] neg_hi:[1,0,0]
	ds_read_b128 v[146:149], v109 offset:12048
	v_add_f32_e32 v10, v10, v11
	s_waitcnt lgkmcnt(5)
	v_pk_mul_f32 v[28:29], v[150:151], v[0:1] neg_lo:[1,0] neg_hi:[1,0]
	v_pk_mul_f32 v[34:35], v[154:155], v[0:1] neg_lo:[1,0] neg_hi:[1,0]
	v_add_f32_e32 v16, v16, v17
	v_pk_mul_f32 v[38:39], v[158:159], v[0:1] neg_lo:[1,0] neg_hi:[1,0]
	s_waitcnt lgkmcnt(4)
	v_pk_mul_f32 v[42:43], v[220:221], v[0:1] neg_lo:[1,0] neg_hi:[1,0]
	v_add_f32_e32 v20, v20, v21
	v_pk_fma_f32 v[28:29], v[152:153], v[8:9], v[28:29] neg_lo:[1,0,0] neg_hi:[1,0,0]
	ds_read_b128 v[150:153], v109 offset:10656
	v_pk_fma_f32 v[34:35], v[156:157], v[8:9], v[34:35] neg_lo:[1,0,0] neg_hi:[1,0,0]
	ds_read_b128 v[154:157], v109 offset:11296
	v_add_f32_e32 v24, v24, v25
	v_pk_fma_f32 v[38:39], v[160:161], v[8:9], v[38:39] neg_lo:[1,0,0] neg_hi:[1,0,0]
	ds_read_b128 v[158:161], v109 offset:11552
	v_pk_fma_f32 v[42:43], v[222:223], v[8:9], v[42:43] neg_lo:[1,0,0] neg_hi:[1,0,0]
	ds_read_b128 v[220:223], v109 offset:10912
	v_add_f32_e32 v140, v10, v140
	s_waitcnt lgkmcnt(5)
	v_pk_fma_f32 v[28:29], v[230:231], v[14:15], v[28:29] neg_lo:[1,0,0] neg_hi:[1,0,0]
	v_pk_fma_f32 v[34:35], v[234:235], v[14:15], v[34:35] neg_lo:[1,0,0] neg_hi:[1,0,0]
	v_add_f32_e32 v16, v16, v141
	v_pk_fma_f32 v[38:39], v[142:143], v[14:15], v[38:39] neg_lo:[1,0,0] neg_hi:[1,0,0]
	s_waitcnt lgkmcnt(4)
	v_pk_fma_f32 v[42:43], v[146:147], v[14:15], v[42:43] neg_lo:[1,0,0] neg_hi:[1,0,0]
	v_add_f32_e32 v20, v20, v138
	v_pk_fma_f32 v[28:29], v[232:233], v[18:19], v[28:29] neg_lo:[1,0,0] neg_hi:[1,0,0]
	ds_read_b128 v[230:233], v109 offset:11808
	v_pk_fma_f32 v[34:35], v[236:237], v[18:19], v[34:35] neg_lo:[1,0,0] neg_hi:[1,0,0]
	ds_read_b128 v[234:237], v109 offset:12064
	v_add_f32_e32 v24, v24, v139
	v_pk_fma_f32 v[38:39], v[144:145], v[18:19], v[38:39] neg_lo:[1,0,0] neg_hi:[1,0,0]
	ds_read_b128 v[142:145], v109 offset:11168
	v_pk_fma_f32 v[42:43], v[148:149], v[18:19], v[42:43] neg_lo:[1,0,0] neg_hi:[1,0,0]
	ds_read_b128 v[146:149], v109 offset:11312
	s_waitcnt lgkmcnt(4)
	v_fma_f32 v141, -v150, v140, v16
	ds_read_b128 v[150:153], v109 offset:11568
	v_pk_fma_f32 v[28:29], v[154:155], v[22:23], v[28:29] neg_lo:[1,0,0] neg_hi:[1,0,0]
	v_pk_fma_f32 v[34:35], v[158:159], v[22:23], v[34:35] neg_lo:[1,0,0] neg_hi:[1,0,0]
	v_fma_f32 v20, -v220, v140, v20
	s_waitcnt lgkmcnt(2)
	v_pk_fma_f32 v[38:39], v[230:231], v[22:23], v[38:39] neg_lo:[1,0,0] neg_hi:[1,0,0]
	v_pk_fma_f32 v[42:43], v[234:235], v[22:23], v[42:43] neg_lo:[1,0,0] neg_hi:[1,0,0]
	v_fma_f32 v24, -v142, v140, v24
	v_pk_fma_f32 v[28:29], v[156:157], v[26:27], v[28:29] neg_lo:[1,0,0] neg_hi:[1,0,0]
	ds_read_b128 v[154:157], v109 offset:11824
	v_pk_fma_f32 v[34:35], v[160:161], v[26:27], v[34:35] neg_lo:[1,0,0] neg_hi:[1,0,0]
	ds_read_b128 v[158:161], v109 offset:12080
	v_fma_f32 v138, -v221, v141, v20
	ds_read_b128 v[220:223], v109 offset:11328
	v_pk_fma_f32 v[38:39], v[232:233], v[26:27], v[38:39] neg_lo:[1,0,0] neg_hi:[1,0,0]
	ds_read_b128 v[230:233], v109 offset:11584
	v_pk_fma_f32 v[42:43], v[236:237], v[26:27], v[42:43] neg_lo:[1,0,0] neg_hi:[1,0,0]
	ds_read_b128 v[234:237], v109 offset:11840
	v_fma_f32 v24, -v143, v141, v24
	s_waitcnt lgkmcnt(4)
; #define LAS __attribute__((address_space(3)))
; __device__ __forceinline__ void gdn_local_unit(LAS unsigned char* lds, const GdnP& P, int unit, const int tid, const int pf) {
;     ...
; #pragma unroll
;         for (int c = 1; c < 64; ++c) { f32x2 sp = (f32x2){sol2[c >> 1][c & 1], 0.f};
; #pragma unroll
;             for (int jb = 0; jb <= (c - 1) / 4; ++jb) { const f32x4 m4 = *(const LAS f32x4*)(Ms + c * 64 + 4 * jb);
;                 sp -= (f32x2){m4.x, m4.y} * sol2[2 * jb]; sp -= (f32x2){m4.z, m4.w} * sol2[2 * jb + 1]; }
;             sol2[c >> 1][c & 1] = sp.x + sp.y; }
	v_pk_fma_f32 v[28:29], v[146:147], v[30:31], v[28:29] neg_lo:[1,0,0] neg_hi:[1,0,0]
	v_pk_fma_f32 v[34:35], v[150:151], v[30:31], v[34:35] neg_lo:[1,0,0] neg_hi:[1,0,0]
	v_fma_f32 v139, -v144, v138, v24
	ds_read_b128 v[142:145], v109 offset:12096
	v_pk_fma_f32 v[38:39], v[154:155], v[30:31], v[38:39] neg_lo:[1,0,0] neg_hi:[1,0,0]
	s_waitcnt lgkmcnt(4)
	v_pk_fma_f32 v[42:43], v[158:159], v[30:31], v[42:43] neg_lo:[1,0,0] neg_hi:[1,0,0]
	v_pk_fma_f32 v[28:29], v[148:149], v[36:37], v[28:29] neg_lo:[1,0,0] neg_hi:[1,0,0]
	ds_read_b128 v[146:149], v109 offset:11344
	v_pk_fma_f32 v[34:35], v[152:153], v[36:37], v[34:35] neg_lo:[1,0,0] neg_hi:[1,0,0]
	ds_read_b128 v[150:153], v109 offset:11600
	v_pk_fma_f32 v[38:39], v[156:157], v[36:37], v[38:39] neg_lo:[1,0,0] neg_hi:[1,0,0]
	ds_read_b128 v[154:157], v109 offset:11856
	v_pk_fma_f32 v[42:43], v[160:161], v[36:37], v[42:43] neg_lo:[1,0,0] neg_hi:[1,0,0]
	ds_read_b128 v[158:161], v109 offset:12112
	s_waitcnt lgkmcnt(4)
	v_pk_fma_f32 v[28:29], v[220:221], v[40:41], v[28:29] neg_lo:[1,0,0] neg_hi:[1,0,0]
	v_pk_fma_f32 v[34:35], v[230:231], v[40:41], v[34:35] neg_lo:[1,0,0] neg_hi:[1,0,0]
	v_pk_fma_f32 v[38:39], v[234:235], v[40:41], v[38:39] neg_lo:[1,0,0] neg_hi:[1,0,0]
	v_pk_fma_f32 v[42:43], v[142:143], v[40:41], v[42:43] neg_lo:[1,0,0] neg_hi:[1,0,0]
	v_pk_fma_f32 v[28:29], v[222:223], v[44:45], v[28:29] neg_lo:[1,0,0] neg_hi:[1,0,0]
	ds_read_b128 v[220:223], v109 offset:11360
	v_pk_fma_f32 v[34:35], v[232:233], v[44:45], v[34:35] neg_lo:[1,0,0] neg_hi:[1,0,0]
	ds_read_b128 v[230:233], v109 offset:11616
	v_pk_fma_f32 v[38:39], v[236:237], v[44:45], v[38:39] neg_lo:[1,0,0] neg_hi:[1,0,0]
	ds_read_b128 v[234:237], v109 offset:11872
	v_pk_fma_f32 v[42:43], v[144:145], v[44:45], v[42:43] neg_lo:[1,0,0] neg_hi:[1,0,0]
	ds_read_b128 v[142:145], v109 offset:12128
	s_waitcnt lgkmcnt(4)
	v_pk_fma_f32 v[28:29], v[146:147], v[50:51], v[28:29] neg_lo:[1,0,0] neg_hi:[1,0,0]
	v_pk_fma_f32 v[34:35], v[150:151], v[50:51], v[34:35] neg_lo:[1,0,0] neg_hi:[1,0,0]
	v_pk_fma_f32 v[38:39], v[154:155], v[50:51], v[38:39] neg_lo:[1,0,0] neg_hi:[1,0,0]
	v_pk_fma_f32 v[42:43], v[158:159], v[50:51], v[42:43] neg_lo:[1,0,0] neg_hi:[1,0,0]
	v_pk_fma_f32 v[28:29], v[148:149], v[54:55], v[28:29] neg_lo:[1,0,0] neg_hi:[1,0,0]
	ds_read_b128 v[146:149], v109 offset:11376
	v_pk_fma_f32 v[34:35], v[152:153], v[54:55], v[34:35] neg_lo:[1,0,0] neg_hi:[1,0,0]
	ds_read_b128 v[150:153], v109 offset:11632
	v_pk_fma_f32 v[38:39], v[156:157], v[54:55], v[38:39] neg_lo:[1,0,0] neg_hi:[1,0,0]
	ds_read_b128 v[154:157], v109 offset:11888
	v_pk_fma_f32 v[42:43], v[160:161], v[54:55], v[42:43] neg_lo:[1,0,0] neg_hi:[1,0,0]
	ds_read_b128 v[158:161], v109 offset:12144
	s_waitcnt lgkmcnt(4)
	v_pk_fma_f32 v[28:29], v[220:221], v[60:61], v[28:29] neg_lo:[1,0,0] neg_hi:[1,0,0]
	v_pk_fma_f32 v[34:35], v[230:231], v[60:61], v[34:35] neg_lo:[1,0,0] neg_hi:[1,0,0]
	v_pk_fma_f32 v[38:39], v[234:235], v[60:61], v[38:39] neg_lo:[1,0,0] neg_hi:[1,0,0]
	v_pk_fma_f32 v[42:43], v[142:143], v[60:61], v[42:43] neg_lo:[1,0,0] neg_hi:[1,0,0]
	v_pk_fma_f32 v[28:29], v[222:223], v[64:65], v[28:29] neg_lo:[1,0,0] neg_hi:[1,0,0]
	ds_read_b128 v[220:223], v109 offset:11392
	v_pk_fma_f32 v[34:35], v[232:233], v[64:65], v[34:35] neg_lo:[1,0,0] neg_hi:[1,0,0]
	ds_read_b128 v[230:233], v109 offset:11648
	v_pk_fma_f32 v[38:39], v[236:237], v[64:65], v[38:39] neg_lo:[1,0,0] neg_hi:[1,0,0]
	ds_read_b128 v[234:237], v109 offset:11904
	v_pk_fma_f32 v[42:43], v[144:145], v[64:65], v[42:43] neg_lo:[1,0,0] neg_hi:[1,0,0]
	ds_read_b128 v[142:145], v109 offset:12160
	s_waitcnt lgkmcnt(4)
	v_pk_fma_f32 v[28:29], v[146:147], v[70:71], v[28:29] neg_lo:[1,0,0] neg_hi:[1,0,0]
	v_pk_fma_f32 v[34:35], v[150:151], v[70:71], v[34:35] neg_lo:[1,0,0] neg_hi:[1,0,0]
	v_pk_fma_f32 v[38:39], v[154:155], v[70:71], v[38:39] neg_lo:[1,0,0] neg_hi:[1,0,0]
	v_pk_fma_f32 v[42:43], v[158:159], v[70:71], v[42:43] neg_lo:[1,0,0] neg_hi:[1,0,0]
	v_pk_fma_f32 v[28:29], v[148:149], v[112:113], v[28:29] neg_lo:[1,0,0] neg_hi:[1,0,0]
	ds_read_b128 v[146:149], v109 offset:11408
	v_pk_fma_f32 v[34:35], v[152:153], v[112:113], v[34:35] neg_lo:[1,0,0] neg_hi:[1,0,0]
	ds_read_b128 v[150:153], v109 offset:11664
	v_pk_fma_f32 v[38:39], v[156:157], v[112:113], v[38:39] neg_lo:[1,0,0] neg_hi:[1,0,0]
	ds_read_b128 v[154:157], v109 offset:11920
	v_pk_fma_f32 v[42:43], v[160:161], v[112:113], v[42:43] neg_lo:[1,0,0] neg_hi:[1,0,0]
	ds_read_b128 v[158:161], v109 offset:12176
	s_waitcnt lgkmcnt(4)
	v_pk_fma_f32 v[28:29], v[220:221], v[116:117], v[28:29] neg_lo:[1,0,0] neg_hi:[1,0,0]
	v_pk_fma_f32 v[34:35], v[230:231], v[116:117], v[34:35] neg_lo:[1,0,0] neg_hi:[1,0,0]
	v_pk_fma_f32 v[38:39], v[234:235], v[116:117], v[38:39] neg_lo:[1,0,0] neg_hi:[1,0,0]
	v_pk_fma_f32 v[42:43], v[142:143], v[116:117], v[42:43] neg_lo:[1,0,0] neg_hi:[1,0,0]
	v_pk_fma_f32 v[28:29], v[222:223], v[122:123], v[28:29] neg_lo:[1,0,0] neg_hi:[1,0,0]
	ds_read_b128 v[220:223], v109 offset:11424
	v_pk_fma_f32 v[34:35], v[232:233], v[122:123], v[34:35] neg_lo:[1,0,0] neg_hi:[1,0,0]
	ds_read_b128 v[230:233], v109 offset:11680
	v_pk_fma_f32 v[38:39], v[236:237], v[122:123], v[38:39] neg_lo:[1,0,0] neg_hi:[1,0,0]
	ds_read_b128 v[234:237], v109 offset:11936
	v_pk_fma_f32 v[42:43], v[144:145], v[122:123], v[42:43] neg_lo:[1,0,0] neg_hi:[1,0,0]
	ds_read_b128 v[142:145], v109 offset:12192
	s_waitcnt lgkmcnt(4)
; #define LAS __attribute__((address_space(3)))
; __device__ __forceinline__ void gdn_local_unit(LAS unsigned char* lds, const GdnP& P, int unit, const int tid, const int pf) {
;     ...
; #pragma unroll
;         for (int c = 1; c < 64; ++c) { f32x2 sp = (f32x2){sol2[c >> 1][c & 1], 0.f};
; #pragma unroll
;             for (int jb = 0; jb <= (c - 1) / 4; ++jb) { const f32x4 m4 = *(const LAS f32x4*)(Ms + c * 64 + 4 * jb);
;                 sp -= (f32x2){m4.x, m4.y} * sol2[2 * jb]; sp -= (f32x2){m4.z, m4.w} * sol2[2 * jb + 1]; }
;             sol2[c >> 1][c & 1] = sp.x + sp.y; }
	v_pk_fma_f32 v[28:29], v[146:147], v[128:129], v[28:29] neg_lo:[1,0,0] neg_hi:[1,0,0]
	v_pk_fma_f32 v[34:35], v[150:151], v[128:129], v[34:35] neg_lo:[1,0,0] neg_hi:[1,0,0]
	v_pk_fma_f32 v[38:39], v[154:155], v[128:129], v[38:39] neg_lo:[1,0,0] neg_hi:[1,0,0]
	v_pk_fma_f32 v[42:43], v[158:159], v[128:129], v[42:43] neg_lo:[1,0,0] neg_hi:[1,0,0]
	v_pk_fma_f32 v[28:29], v[148:149], v[134:135], v[28:29] neg_lo:[1,0,0] neg_hi:[1,0,0]
	ds_read_b128 v[146:149], v109 offset:12288
	v_pk_fma_f32 v[34:35], v[152:153], v[134:135], v[34:35] neg_lo:[1,0,0] neg_hi:[1,0,0]
	ds_read_b128 v[150:153], v109 offset:12544
	v_pk_fma_f32 v[38:39], v[156:157], v[134:135], v[38:39] neg_lo:[1,0,0] neg_hi:[1,0,0]
	ds_read_b128 v[154:157], v109 offset:12800
	v_pk_fma_f32 v[42:43], v[160:161], v[134:135], v[42:43] neg_lo:[1,0,0] neg_hi:[1,0,0]
	ds_read_b128 v[158:161], v109 offset:13056
	s_waitcnt lgkmcnt(4)
	v_pk_fma_f32 v[28:29], v[220:221], v[140:141], v[28:29] neg_lo:[1,0,0] neg_hi:[1,0,0]
	v_pk_fma_f32 v[34:35], v[230:231], v[140:141], v[34:35] neg_lo:[1,0,0] neg_hi:[1,0,0]
	v_pk_fma_f32 v[38:39], v[234:235], v[140:141], v[38:39] neg_lo:[1,0,0] neg_hi:[1,0,0]
	v_pk_fma_f32 v[42:43], v[142:143], v[140:141], v[42:43] neg_lo:[1,0,0] neg_hi:[1,0,0]
	v_pk_fma_f32 v[28:29], v[222:223], v[138:139], v[28:29] neg_lo:[1,0,0] neg_hi:[1,0,0]
	ds_read_b128 v[220:223], v109 offset:12304
	v_pk_fma_f32 v[34:35], v[232:233], v[138:139], v[34:35] neg_lo:[1,0,0] neg_hi:[1,0,0]
	ds_read_b128 v[230:233], v109 offset:12560
	v_pk_fma_f32 v[38:39], v[236:237], v[138:139], v[38:39] neg_lo:[1,0,0] neg_hi:[1,0,0]
	ds_read_b128 v[234:237], v109 offset:12816
	v_pk_fma_f32 v[42:43], v[144:145], v[138:139], v[42:43] neg_lo:[1,0,0] neg_hi:[1,0,0]
	ds_read_b128 v[142:145], v109 offset:13072
	v_add_f32_e32 v28, v28, v29
	s_waitcnt lgkmcnt(5)
	v_pk_mul_f32 v[10:11], v[146:147], v[0:1] neg_lo:[1,0] neg_hi:[1,0]
	v_pk_mul_f32 v[16:17], v[150:151], v[0:1] neg_lo:[1,0] neg_hi:[1,0]
	v_add_f32_e32 v34, v34, v35
	v_pk_mul_f32 v[20:21], v[154:155], v[0:1] neg_lo:[1,0] neg_hi:[1,0]
	s_waitcnt lgkmcnt(4)
	v_pk_mul_f32 v[24:25], v[158:159], v[0:1] neg_lo:[1,0] neg_hi:[1,0]
	v_add_f32_e32 v38, v38, v39
	v_pk_fma_f32 v[10:11], v[148:149], v[8:9], v[10:11] neg_lo:[1,0,0] neg_hi:[1,0,0]
	ds_read_b128 v[146:149], v109 offset:11696
	v_pk_fma_f32 v[16:17], v[152:153], v[8:9], v[16:17] neg_lo:[1,0,0] neg_hi:[1,0,0]
	ds_read_b128 v[150:153], v109 offset:12320
	v_add_f32_e32 v42, v42, v43
	v_pk_fma_f32 v[20:21], v[156:157], v[8:9], v[20:21] neg_lo:[1,0,0] neg_hi:[1,0,0]
	ds_read_b128 v[154:157], v109 offset:12576
	v_pk_fma_f32 v[24:25], v[160:161], v[8:9], v[24:25] neg_lo:[1,0,0] neg_hi:[1,0,0]
	ds_read_b128 v[158:161], v109 offset:11952
	v_add_f32_e32 v132, v28, v132
	s_waitcnt lgkmcnt(5)
	v_pk_fma_f32 v[10:11], v[220:221], v[14:15], v[10:11] neg_lo:[1,0,0] neg_hi:[1,0,0]
	v_pk_fma_f32 v[16:17], v[230:231], v[14:15], v[16:17] neg_lo:[1,0,0] neg_hi:[1,0,0]
	v_add_f32_e32 v34, v34, v133
	v_pk_fma_f32 v[20:21], v[234:235], v[14:15], v[20:21] neg_lo:[1,0,0] neg_hi:[1,0,0]
	s_waitcnt lgkmcnt(4)
	v_pk_fma_f32 v[24:25], v[142:143], v[14:15], v[24:25] neg_lo:[1,0,0] neg_hi:[1,0,0]
	v_add_f32_e32 v38, v38, v124
	v_pk_fma_f32 v[10:11], v[222:223], v[18:19], v[10:11] neg_lo:[1,0,0] neg_hi:[1,0,0]
	ds_read_b128 v[220:223], v109 offset:12832
	v_pk_fma_f32 v[16:17], v[232:233], v[18:19], v[16:17] neg_lo:[1,0,0] neg_hi:[1,0,0]
	ds_read_b128 v[230:233], v109 offset:13088
	v_add_f32_e32 v42, v42, v125
	v_pk_fma_f32 v[20:21], v[236:237], v[18:19], v[20:21] neg_lo:[1,0,0] neg_hi:[1,0,0]
	ds_read_b128 v[234:237], v109 offset:12208
	v_pk_fma_f32 v[24:25], v[144:145], v[18:19], v[24:25] neg_lo:[1,0,0] neg_hi:[1,0,0]
	ds_read_b128 v[142:145], v109 offset:12336
	s_waitcnt lgkmcnt(4)
	v_fma_f32 v133, -v146, v132, v34
	ds_read_b128 v[146:149], v109 offset:12592
	v_pk_fma_f32 v[10:11], v[150:151], v[22:23], v[10:11] neg_lo:[1,0,0] neg_hi:[1,0,0]
	v_pk_fma_f32 v[16:17], v[154:155], v[22:23], v[16:17] neg_lo:[1,0,0] neg_hi:[1,0,0]
	v_fma_f32 v38, -v158, v132, v38
	s_waitcnt lgkmcnt(2)
	v_pk_fma_f32 v[20:21], v[220:221], v[22:23], v[20:21] neg_lo:[1,0,0] neg_hi:[1,0,0]
	v_pk_fma_f32 v[24:25], v[230:231], v[22:23], v[24:25] neg_lo:[1,0,0] neg_hi:[1,0,0]
	v_fma_f32 v42, -v234, v132, v42
	v_pk_fma_f32 v[10:11], v[152:153], v[26:27], v[10:11] neg_lo:[1,0,0] neg_hi:[1,0,0]
	ds_read_b128 v[150:153], v109 offset:12848
	v_pk_fma_f32 v[16:17], v[156:157], v[26:27], v[16:17] neg_lo:[1,0,0] neg_hi:[1,0,0]
	ds_read_b128 v[154:157], v109 offset:13104
	v_fma_f32 v124, -v159, v133, v38
	ds_read_b128 v[158:161], v109 offset:12352
	v_pk_fma_f32 v[20:21], v[222:223], v[26:27], v[20:21] neg_lo:[1,0,0] neg_hi:[1,0,0]
	ds_read_b128 v[220:223], v109 offset:12608
	v_pk_fma_f32 v[24:25], v[232:233], v[26:27], v[24:25] neg_lo:[1,0,0] neg_hi:[1,0,0]
	ds_read_b128 v[230:233], v109 offset:12864
	v_fma_f32 v42, -v235, v133, v42
	s_waitcnt lgkmcnt(4)
	v_pk_fma_f32 v[10:11], v[142:143], v[30:31], v[10:11] neg_lo:[1,0,0] neg_hi:[1,0,0]
	v_pk_fma_f32 v[16:17], v[146:147], v[30:31], v[16:17] neg_lo:[1,0,0] neg_hi:[1,0,0]
	v_fma_f32 v125, -v236, v124, v42
	ds_read_b128 v[234:237], v109 offset:13120
	v_pk_fma_f32 v[20:21], v[150:151], v[30:31], v[20:21] neg_lo:[1,0,0] neg_hi:[1,0,0]
	s_waitcnt lgkmcnt(4)
	v_pk_fma_f32 v[24:25], v[154:155], v[30:31], v[24:25] neg_lo:[1,0,0] neg_hi:[1,0,0]
	v_pk_fma_f32 v[10:11], v[144:145], v[36:37], v[10:11] neg_lo:[1,0,0] neg_hi:[1,0,0]
	ds_read_b128 v[142:145], v109 offset:12368
	v_pk_fma_f32 v[16:17], v[148:149], v[36:37], v[16:17] neg_lo:[1,0,0] neg_hi:[1,0,0]
	ds_read_b128 v[146:149], v109 offset:12624
	v_pk_fma_f32 v[20:21], v[152:153], v[36:37], v[20:21] neg_lo:[1,0,0] neg_hi:[1,0,0]
	ds_read_b128 v[150:153], v109 offset:12880
	v_pk_fma_f32 v[24:25], v[156:157], v[36:37], v[24:25] neg_lo:[1,0,0] neg_hi:[1,0,0]
	ds_read_b128 v[154:157], v109 offset:13136
	s_waitcnt lgkmcnt(4)
; #define LAS __attribute__((address_space(3)))
; __device__ __forceinline__ void gdn_local_unit(LAS unsigned char* lds, const GdnP& P, int unit, const int tid, const int pf) {
;     ...
; #pragma unroll
;         for (int c = 1; c < 64; ++c) { f32x2 sp = (f32x2){sol2[c >> 1][c & 1], 0.f};
; #pragma unroll
;             for (int jb = 0; jb <= (c - 1) / 4; ++jb) { const f32x4 m4 = *(const LAS f32x4*)(Ms + c * 64 + 4 * jb);
;                 sp -= (f32x2){m4.x, m4.y} * sol2[2 * jb]; sp -= (f32x2){m4.z, m4.w} * sol2[2 * jb + 1]; }
;             sol2[c >> 1][c & 1] = sp.x + sp.y; }
	v_pk_fma_f32 v[10:11], v[158:159], v[40:41], v[10:11] neg_lo:[1,0,0] neg_hi:[1,0,0]
	v_pk_fma_f32 v[16:17], v[220:221], v[40:41], v[16:17] neg_lo:[1,0,0] neg_hi:[1,0,0]
	v_pk_fma_f32 v[20:21], v[230:231], v[40:41], v[20:21] neg_lo:[1,0,0] neg_hi:[1,0,0]
	v_pk_fma_f32 v[24:25], v[234:235], v[40:41], v[24:25] neg_lo:[1,0,0] neg_hi:[1,0,0]
	v_pk_fma_f32 v[10:11], v[160:161], v[44:45], v[10:11] neg_lo:[1,0,0] neg_hi:[1,0,0]
	ds_read_b128 v[158:161], v109 offset:12384
	v_pk_fma_f32 v[16:17], v[222:223], v[44:45], v[16:17] neg_lo:[1,0,0] neg_hi:[1,0,0]
	ds_read_b128 v[220:223], v109 offset:12640
	v_pk_fma_f32 v[20:21], v[232:233], v[44:45], v[20:21] neg_lo:[1,0,0] neg_hi:[1,0,0]
	ds_read_b128 v[230:233], v109 offset:12896
	v_pk_fma_f32 v[24:25], v[236:237], v[44:45], v[24:25] neg_lo:[1,0,0] neg_hi:[1,0,0]
	ds_read_b128 v[234:237], v109 offset:13152
	s_waitcnt lgkmcnt(4)
	v_pk_fma_f32 v[10:11], v[142:143], v[50:51], v[10:11] neg_lo:[1,0,0] neg_hi:[1,0,0]
	v_pk_fma_f32 v[16:17], v[146:147], v[50:51], v[16:17] neg_lo:[1,0,0] neg_hi:[1,0,0]
	v_pk_fma_f32 v[20:21], v[150:151], v[50:51], v[20:21] neg_lo:[1,0,0] neg_hi:[1,0,0]
	v_pk_fma_f32 v[24:25], v[154:155], v[50:51], v[24:25] neg_lo:[1,0,0] neg_hi:[1,0,0]
	v_pk_fma_f32 v[10:11], v[144:145], v[54:55], v[10:11] neg_lo:[1,0,0] neg_hi:[1,0,0]
	ds_read_b128 v[142:145], v109 offset:12400
	v_pk_fma_f32 v[16:17], v[148:149], v[54:55], v[16:17] neg_lo:[1,0,0] neg_hi:[1,0,0]
	ds_read_b128 v[146:149], v109 offset:12656
	v_pk_fma_f32 v[20:21], v[152:153], v[54:55], v[20:21] neg_lo:[1,0,0] neg_hi:[1,0,0]
	ds_read_b128 v[150:153], v109 offset:12912
	v_pk_fma_f32 v[24:25], v[156:157], v[54:55], v[24:25] neg_lo:[1,0,0] neg_hi:[1,0,0]
	ds_read_b128 v[154:157], v109 offset:13168
	s_waitcnt lgkmcnt(4)
	v_pk_fma_f32 v[10:11], v[158:159], v[60:61], v[10:11] neg_lo:[1,0,0] neg_hi:[1,0,0]
	v_pk_fma_f32 v[16:17], v[220:221], v[60:61], v[16:17] neg_lo:[1,0,0] neg_hi:[1,0,0]
	v_pk_fma_f32 v[20:21], v[230:231], v[60:61], v[20:21] neg_lo:[1,0,0] neg_hi:[1,0,0]
	v_pk_fma_f32 v[24:25], v[234:235], v[60:61], v[24:25] neg_lo:[1,0,0] neg_hi:[1,0,0]
	v_pk_fma_f32 v[10:11], v[160:161], v[64:65], v[10:11] neg_lo:[1,0,0] neg_hi:[1,0,0]
	ds_read_b128 v[158:161], v109 offset:12416
	v_pk_fma_f32 v[16:17], v[222:223], v[64:65], v[16:17] neg_lo:[1,0,0] neg_hi:[1,0,0]
	ds_read_b128 v[220:223], v109 offset:12672
	v_pk_fma_f32 v[20:21], v[232:233], v[64:65], v[20:21] neg_lo:[1,0,0] neg_hi:[1,0,0]
	ds_read_b128 v[230:233], v109 offset:12928
	v_pk_fma_f32 v[24:25], v[236:237], v[64:65], v[24:25] neg_lo:[1,0,0] neg_hi:[1,0,0]
	ds_read_b128 v[234:237], v109 offset:13184
	s_waitcnt lgkmcnt(4)
	v_pk_fma_f32 v[10:11], v[142:143], v[70:71], v[10:11] neg_lo:[1,0,0] neg_hi:[1,0,0]
	v_pk_fma_f32 v[16:17], v[146:147], v[70:71], v[16:17] neg_lo:[1,0,0] neg_hi:[1,0,0]
	v_pk_fma_f32 v[20:21], v[150:151], v[70:71], v[20:21] neg_lo:[1,0,0] neg_hi:[1,0,0]
	v_pk_fma_f32 v[24:25], v[154:155], v[70:71], v[24:25] neg_lo:[1,0,0] neg_hi:[1,0,0]
	v_pk_fma_f32 v[10:11], v[144:145], v[112:113], v[10:11] neg_lo:[1,0,0] neg_hi:[1,0,0]
	ds_read_b128 v[142:145], v109 offset:12432
	v_pk_fma_f32 v[16:17], v[148:149], v[112:113], v[16:17] neg_lo:[1,0,0] neg_hi:[1,0,0]
	ds_read_b128 v[146:149], v109 offset:12688
	v_pk_fma_f32 v[20:21], v[152:153], v[112:113], v[20:21] neg_lo:[1,0,0] neg_hi:[1,0,0]
	ds_read_b128 v[150:153], v109 offset:12944
	v_pk_fma_f32 v[24:25], v[156:157], v[112:113], v[24:25] neg_lo:[1,0,0] neg_hi:[1,0,0]
	ds_read_b128 v[154:157], v109 offset:13200
	s_waitcnt lgkmcnt(4)
	v_pk_fma_f32 v[10:11], v[158:159], v[116:117], v[10:11] neg_lo:[1,0,0] neg_hi:[1,0,0]
	v_pk_fma_f32 v[16:17], v[220:221], v[116:117], v[16:17] neg_lo:[1,0,0] neg_hi:[1,0,0]
	v_pk_fma_f32 v[20:21], v[230:231], v[116:117], v[20:21] neg_lo:[1,0,0] neg_hi:[1,0,0]
	v_pk_fma_f32 v[24:25], v[234:235], v[116:117], v[24:25] neg_lo:[1,0,0] neg_hi:[1,0,0]
	v_pk_fma_f32 v[10:11], v[160:161], v[122:123], v[10:11] neg_lo:[1,0,0] neg_hi:[1,0,0]
	ds_read_b128 v[158:161], v109 offset:12448
	v_pk_fma_f32 v[16:17], v[222:223], v[122:123], v[16:17] neg_lo:[1,0,0] neg_hi:[1,0,0]
	ds_read_b128 v[220:223], v109 offset:12704
	v_pk_fma_f32 v[20:21], v[232:233], v[122:123], v[20:21] neg_lo:[1,0,0] neg_hi:[1,0,0]
	ds_read_b128 v[230:233], v109 offset:12960
	v_pk_fma_f32 v[24:25], v[236:237], v[122:123], v[24:25] neg_lo:[1,0,0] neg_hi:[1,0,0]
	ds_read_b128 v[234:237], v109 offset:13216
	s_waitcnt lgkmcnt(4)
	v_pk_fma_f32 v[10:11], v[142:143], v[128:129], v[10:11] neg_lo:[1,0,0] neg_hi:[1,0,0]
	v_pk_fma_f32 v[16:17], v[146:147], v[128:129], v[16:17] neg_lo:[1,0,0] neg_hi:[1,0,0]
	v_pk_fma_f32 v[20:21], v[150:151], v[128:129], v[20:21] neg_lo:[1,0,0] neg_hi:[1,0,0]
	v_pk_fma_f32 v[24:25], v[154:155], v[128:129], v[24:25] neg_lo:[1,0,0] neg_hi:[1,0,0]
	v_pk_fma_f32 v[10:11], v[144:145], v[134:135], v[10:11] neg_lo:[1,0,0] neg_hi:[1,0,0]
	ds_read_b128 v[142:145], v109 offset:12464
	v_pk_fma_f32 v[16:17], v[148:149], v[134:135], v[16:17] neg_lo:[1,0,0] neg_hi:[1,0,0]
	ds_read_b128 v[146:149], v109 offset:12720
	v_pk_fma_f32 v[20:21], v[152:153], v[134:135], v[20:21] neg_lo:[1,0,0] neg_hi:[1,0,0]
	ds_read_b128 v[150:153], v109 offset:12976
	v_pk_fma_f32 v[24:25], v[156:157], v[134:135], v[24:25] neg_lo:[1,0,0] neg_hi:[1,0,0]
	ds_read_b128 v[154:157], v109 offset:13232
	s_waitcnt lgkmcnt(4)
; #define LAS __attribute__((address_space(3)))
; __device__ __forceinline__ void gdn_local_unit(LAS unsigned char* lds, const GdnP& P, int unit, const int tid, const int pf) {
;     ...
; #pragma unroll
;         for (int c = 1; c < 64; ++c) { f32x2 sp = (f32x2){sol2[c >> 1][c & 1], 0.f};
; #pragma unroll
;             for (int jb = 0; jb <= (c - 1) / 4; ++jb) { const f32x4 m4 = *(const LAS f32x4*)(Ms + c * 64 + 4 * jb);
;                 sp -= (f32x2){m4.x, m4.y} * sol2[2 * jb]; sp -= (f32x2){m4.z, m4.w} * sol2[2 * jb + 1]; }
;             sol2[c >> 1][c & 1] = sp.x + sp.y; }
	v_pk_fma_f32 v[10:11], v[158:159], v[140:141], v[10:11] neg_lo:[1,0,0] neg_hi:[1,0,0]
	v_pk_fma_f32 v[16:17], v[220:221], v[140:141], v[16:17] neg_lo:[1,0,0] neg_hi:[1,0,0]
	v_pk_fma_f32 v[20:21], v[230:231], v[140:141], v[20:21] neg_lo:[1,0,0] neg_hi:[1,0,0]
	v_pk_fma_f32 v[24:25], v[234:235], v[140:141], v[24:25] neg_lo:[1,0,0] neg_hi:[1,0,0]
	v_pk_fma_f32 v[10:11], v[160:161], v[138:139], v[10:11] neg_lo:[1,0,0] neg_hi:[1,0,0]
	ds_read_b128 v[158:161], v109 offset:13312
	v_pk_fma_f32 v[16:17], v[222:223], v[138:139], v[16:17] neg_lo:[1,0,0] neg_hi:[1,0,0]
	ds_read_b128 v[220:223], v109 offset:13568
	v_pk_fma_f32 v[20:21], v[232:233], v[138:139], v[20:21] neg_lo:[1,0,0] neg_hi:[1,0,0]
	ds_read_b128 v[230:233], v109 offset:13824
	v_pk_fma_f32 v[24:25], v[236:237], v[138:139], v[24:25] neg_lo:[1,0,0] neg_hi:[1,0,0]
	ds_read_b128 v[234:237], v109 offset:14080
	s_waitcnt lgkmcnt(4)
	v_pk_fma_f32 v[10:11], v[142:143], v[132:133], v[10:11] neg_lo:[1,0,0] neg_hi:[1,0,0]
	v_pk_fma_f32 v[16:17], v[146:147], v[132:133], v[16:17] neg_lo:[1,0,0] neg_hi:[1,0,0]
	v_pk_fma_f32 v[20:21], v[150:151], v[132:133], v[20:21] neg_lo:[1,0,0] neg_hi:[1,0,0]
	v_pk_fma_f32 v[24:25], v[154:155], v[132:133], v[24:25] neg_lo:[1,0,0] neg_hi:[1,0,0]
	v_pk_fma_f32 v[10:11], v[144:145], v[124:125], v[10:11] neg_lo:[1,0,0] neg_hi:[1,0,0]
	ds_read_b128 v[142:145], v109 offset:13328
	v_pk_fma_f32 v[16:17], v[148:149], v[124:125], v[16:17] neg_lo:[1,0,0] neg_hi:[1,0,0]
	ds_read_b128 v[146:149], v109 offset:13584
	v_pk_fma_f32 v[20:21], v[152:153], v[124:125], v[20:21] neg_lo:[1,0,0] neg_hi:[1,0,0]
	ds_read_b128 v[150:153], v109 offset:13840
	v_pk_fma_f32 v[24:25], v[156:157], v[124:125], v[24:25] neg_lo:[1,0,0] neg_hi:[1,0,0]
	ds_read_b128 v[154:157], v109 offset:14096
	v_add_f32_e32 v10, v10, v11
	s_waitcnt lgkmcnt(5)
	v_pk_mul_f32 v[28:29], v[158:159], v[0:1] neg_lo:[1,0] neg_hi:[1,0]
	v_pk_mul_f32 v[34:35], v[220:221], v[0:1] neg_lo:[1,0] neg_hi:[1,0]
	v_add_f32_e32 v16, v16, v17
	v_pk_mul_f32 v[38:39], v[230:231], v[0:1] neg_lo:[1,0] neg_hi:[1,0]
	s_waitcnt lgkmcnt(4)
	v_pk_mul_f32 v[42:43], v[234:235], v[0:1] neg_lo:[1,0] neg_hi:[1,0]
	v_add_f32_e32 v20, v20, v21
	v_pk_fma_f32 v[28:29], v[160:161], v[8:9], v[28:29] neg_lo:[1,0,0] neg_hi:[1,0,0]
	ds_read_b128 v[158:161], v109 offset:12736
	v_pk_fma_f32 v[34:35], v[222:223], v[8:9], v[34:35] neg_lo:[1,0,0] neg_hi:[1,0,0]
	ds_read_b128 v[220:223], v109 offset:13344
	v_add_f32_e32 v24, v24, v25
	v_pk_fma_f32 v[38:39], v[232:233], v[8:9], v[38:39] neg_lo:[1,0,0] neg_hi:[1,0,0]
	ds_read_b128 v[230:233], v109 offset:13600
	v_pk_fma_f32 v[42:43], v[236:237], v[8:9], v[42:43] neg_lo:[1,0,0] neg_hi:[1,0,0]
	ds_read_b128 v[234:237], v109 offset:12992
	v_add_f32_e32 v118, v10, v118
	s_waitcnt lgkmcnt(5)
	v_pk_fma_f32 v[28:29], v[142:143], v[14:15], v[28:29] neg_lo:[1,0,0] neg_hi:[1,0,0]
	v_pk_fma_f32 v[34:35], v[146:147], v[14:15], v[34:35] neg_lo:[1,0,0] neg_hi:[1,0,0]
	v_add_f32_e32 v16, v16, v119
	v_pk_fma_f32 v[38:39], v[150:151], v[14:15], v[38:39] neg_lo:[1,0,0] neg_hi:[1,0,0]
	s_waitcnt lgkmcnt(4)
	v_pk_fma_f32 v[42:43], v[154:155], v[14:15], v[42:43] neg_lo:[1,0,0] neg_hi:[1,0,0]
	v_add_f32_e32 v20, v20, v74
	v_pk_fma_f32 v[28:29], v[144:145], v[18:19], v[28:29] neg_lo:[1,0,0] neg_hi:[1,0,0]
	ds_read_b128 v[142:145], v109 offset:13856
	v_pk_fma_f32 v[34:35], v[148:149], v[18:19], v[34:35] neg_lo:[1,0,0] neg_hi:[1,0,0]
	ds_read_b128 v[146:149], v109 offset:14112
	v_add_f32_e32 v24, v24, v75
	v_pk_fma_f32 v[38:39], v[152:153], v[18:19], v[38:39] neg_lo:[1,0,0] neg_hi:[1,0,0]
	ds_read_b128 v[150:153], v109 offset:13248
	v_pk_fma_f32 v[42:43], v[156:157], v[18:19], v[42:43] neg_lo:[1,0,0] neg_hi:[1,0,0]
	ds_read_b128 v[154:157], v109 offset:13360
	s_waitcnt lgkmcnt(4)
	v_fma_f32 v119, -v158, v118, v16
	ds_read_b128 v[158:161], v109 offset:13616
	v_pk_fma_f32 v[28:29], v[220:221], v[22:23], v[28:29] neg_lo:[1,0,0] neg_hi:[1,0,0]
	v_pk_fma_f32 v[34:35], v[230:231], v[22:23], v[34:35] neg_lo:[1,0,0] neg_hi:[1,0,0]
	v_fma_f32 v20, -v234, v118, v20
	s_waitcnt lgkmcnt(2)
	v_pk_fma_f32 v[38:39], v[142:143], v[22:23], v[38:39] neg_lo:[1,0,0] neg_hi:[1,0,0]
	v_pk_fma_f32 v[42:43], v[146:147], v[22:23], v[42:43] neg_lo:[1,0,0] neg_hi:[1,0,0]
	v_fma_f32 v24, -v150, v118, v24
	v_pk_fma_f32 v[28:29], v[222:223], v[26:27], v[28:29] neg_lo:[1,0,0] neg_hi:[1,0,0]
	ds_read_b128 v[220:223], v109 offset:13872
	v_pk_fma_f32 v[34:35], v[232:233], v[26:27], v[34:35] neg_lo:[1,0,0] neg_hi:[1,0,0]
	ds_read_b128 v[230:233], v109 offset:14128
	v_fma_f32 v74, -v235, v119, v20
	ds_read_b128 v[234:237], v109 offset:13376
	v_pk_fma_f32 v[38:39], v[144:145], v[26:27], v[38:39] neg_lo:[1,0,0] neg_hi:[1,0,0]
	ds_read_b128 v[142:145], v109 offset:13632
	v_pk_fma_f32 v[42:43], v[148:149], v[26:27], v[42:43] neg_lo:[1,0,0] neg_hi:[1,0,0]
	ds_read_b128 v[146:149], v109 offset:13888
	v_fma_f32 v24, -v151, v119, v24
	s_waitcnt lgkmcnt(4)
	v_pk_fma_f32 v[28:29], v[154:155], v[30:31], v[28:29] neg_lo:[1,0,0] neg_hi:[1,0,0]
	v_pk_fma_f32 v[34:35], v[158:159], v[30:31], v[34:35] neg_lo:[1,0,0] neg_hi:[1,0,0]
	v_fma_f32 v75, -v152, v74, v24
	ds_read_b128 v[150:153], v109 offset:14144
	v_pk_fma_f32 v[38:39], v[220:221], v[30:31], v[38:39] neg_lo:[1,0,0] neg_hi:[1,0,0]
	s_waitcnt lgkmcnt(4)
	v_pk_fma_f32 v[42:43], v[230:231], v[30:31], v[42:43] neg_lo:[1,0,0] neg_hi:[1,0,0]
	v_pk_fma_f32 v[28:29], v[156:157], v[36:37], v[28:29] neg_lo:[1,0,0] neg_hi:[1,0,0]
	ds_read_b128 v[154:157], v109 offset:13392
	v_pk_fma_f32 v[34:35], v[160:161], v[36:37], v[34:35] neg_lo:[1,0,0] neg_hi:[1,0,0]
	ds_read_b128 v[158:161], v109 offset:13648
	v_pk_fma_f32 v[38:39], v[222:223], v[36:37], v[38:39] neg_lo:[1,0,0] neg_hi:[1,0,0]
	ds_read_b128 v[220:223], v109 offset:13904
	v_pk_fma_f32 v[42:43], v[232:233], v[36:37], v[42:43] neg_lo:[1,0,0] neg_hi:[1,0,0]
	ds_read_b128 v[230:233], v109 offset:14160
	s_waitcnt lgkmcnt(4)
; #define LAS __attribute__((address_space(3)))
; __device__ __forceinline__ void gdn_local_unit(LAS unsigned char* lds, const GdnP& P, int unit, const int tid, const int pf) {
;     ...
;         for (int c = 1; c < 64; ++c) { f32x2 sp = (f32x2){sol2[c >> 1][c & 1], 0.f};
; #pragma unroll
;             for (int jb = 0; jb <= (c - 1) / 4; ++jb) { const f32x4 m4 = *(const LAS f32x4*)(Ms + c * 64 + 4 * jb);
;                 sp -= (f32x2){m4.x, m4.y} * sol2[2 * jb]; sp -= (f32x2){m4.z, m4.w} * sol2[2 * jb + 1]; }
;             sol2[c >> 1][c & 1] = sp.x + sp.y; }
	v_pk_fma_f32 v[28:29], v[234:235], v[40:41], v[28:29] neg_lo:[1,0,0] neg_hi:[1,0,0]
	v_pk_fma_f32 v[34:35], v[142:143], v[40:41], v[34:35] neg_lo:[1,0,0] neg_hi:[1,0,0]
	v_pk_fma_f32 v[38:39], v[146:147], v[40:41], v[38:39] neg_lo:[1,0,0] neg_hi:[1,0,0]
	v_pk_fma_f32 v[42:43], v[150:151], v[40:41], v[42:43] neg_lo:[1,0,0] neg_hi:[1,0,0]
	v_pk_fma_f32 v[28:29], v[236:237], v[44:45], v[28:29] neg_lo:[1,0,0] neg_hi:[1,0,0]
	ds_read_b128 v[234:237], v109 offset:13408
	v_pk_fma_f32 v[34:35], v[144:145], v[44:45], v[34:35] neg_lo:[1,0,0] neg_hi:[1,0,0]
	ds_read_b128 v[142:145], v109 offset:13664
	v_pk_fma_f32 v[38:39], v[148:149], v[44:45], v[38:39] neg_lo:[1,0,0] neg_hi:[1,0,0]
	ds_read_b128 v[146:149], v109 offset:13920
	v_pk_fma_f32 v[42:43], v[152:153], v[44:45], v[42:43] neg_lo:[1,0,0] neg_hi:[1,0,0]
	ds_read_b128 v[150:153], v109 offset:14176
	s_waitcnt lgkmcnt(4)
	v_pk_fma_f32 v[28:29], v[154:155], v[50:51], v[28:29] neg_lo:[1,0,0] neg_hi:[1,0,0]
	v_pk_fma_f32 v[34:35], v[158:159], v[50:51], v[34:35] neg_lo:[1,0,0] neg_hi:[1,0,0]
	v_pk_fma_f32 v[38:39], v[220:221], v[50:51], v[38:39] neg_lo:[1,0,0] neg_hi:[1,0,0]
	v_pk_fma_f32 v[42:43], v[230:231], v[50:51], v[42:43] neg_lo:[1,0,0] neg_hi:[1,0,0]
	v_pk_fma_f32 v[28:29], v[156:157], v[54:55], v[28:29] neg_lo:[1,0,0] neg_hi:[1,0,0]
	ds_read_b128 v[154:157], v109 offset:13424
	v_pk_fma_f32 v[34:35], v[160:161], v[54:55], v[34:35] neg_lo:[1,0,0] neg_hi:[1,0,0]
	ds_read_b128 v[158:161], v109 offset:13680
	v_pk_fma_f32 v[38:39], v[222:223], v[54:55], v[38:39] neg_lo:[1,0,0] neg_hi:[1,0,0]
	ds_read_b128 v[220:223], v109 offset:13936
	v_pk_fma_f32 v[42:43], v[232:233], v[54:55], v[42:43] neg_lo:[1,0,0] neg_hi:[1,0,0]
	ds_read_b128 v[230:233], v109 offset:14192
	s_waitcnt lgkmcnt(4)
	v_pk_fma_f32 v[28:29], v[234:235], v[60:61], v[28:29] neg_lo:[1,0,0] neg_hi:[1,0,0]
	v_pk_fma_f32 v[34:35], v[142:143], v[60:61], v[34:35] neg_lo:[1,0,0] neg_hi:[1,0,0]
	v_pk_fma_f32 v[38:39], v[146:147], v[60:61], v[38:39] neg_lo:[1,0,0] neg_hi:[1,0,0]
	v_pk_fma_f32 v[42:43], v[150:151], v[60:61], v[42:43] neg_lo:[1,0,0] neg_hi:[1,0,0]
	v_pk_fma_f32 v[28:29], v[236:237], v[64:65], v[28:29] neg_lo:[1,0,0] neg_hi:[1,0,0]
	ds_read_b128 v[234:237], v109 offset:13440
	v_pk_fma_f32 v[34:35], v[144:145], v[64:65], v[34:35] neg_lo:[1,0,0] neg_hi:[1,0,0]
	ds_read_b128 v[142:145], v109 offset:13696
	v_pk_fma_f32 v[38:39], v[148:149], v[64:65], v[38:39] neg_lo:[1,0,0] neg_hi:[1,0,0]
	ds_read_b128 v[146:149], v109 offset:13952
	v_pk_fma_f32 v[42:43], v[152:153], v[64:65], v[42:43] neg_lo:[1,0,0] neg_hi:[1,0,0]
	ds_read_b128 v[150:153], v109 offset:14208
	s_waitcnt lgkmcnt(4)
	v_pk_fma_f32 v[28:29], v[154:155], v[70:71], v[28:29] neg_lo:[1,0,0] neg_hi:[1,0,0]
	v_pk_fma_f32 v[34:35], v[158:159], v[70:71], v[34:35] neg_lo:[1,0,0] neg_hi:[1,0,0]
	v_pk_fma_f32 v[38:39], v[220:221], v[70:71], v[38:39] neg_lo:[1,0,0] neg_hi:[1,0,0]
	v_pk_fma_f32 v[42:43], v[230:231], v[70:71], v[42:43] neg_lo:[1,0,0] neg_hi:[1,0,0]
	v_pk_fma_f32 v[28:29], v[156:157], v[112:113], v[28:29] neg_lo:[1,0,0] neg_hi:[1,0,0]
	ds_read_b128 v[154:157], v109 offset:13456
	v_pk_fma_f32 v[34:35], v[160:161], v[112:113], v[34:35] neg_lo:[1,0,0] neg_hi:[1,0,0]
	ds_read_b128 v[158:161], v109 offset:13712
	v_pk_fma_f32 v[38:39], v[222:223], v[112:113], v[38:39] neg_lo:[1,0,0] neg_hi:[1,0,0]
	ds_read_b128 v[220:223], v109 offset:13968
	v_pk_fma_f32 v[42:43], v[232:233], v[112:113], v[42:43] neg_lo:[1,0,0] neg_hi:[1,0,0]
	ds_read_b128 v[230:233], v109 offset:14224
	s_waitcnt lgkmcnt(4)
	v_pk_fma_f32 v[28:29], v[234:235], v[116:117], v[28:29] neg_lo:[1,0,0] neg_hi:[1,0,0]
	v_pk_fma_f32 v[34:35], v[142:143], v[116:117], v[34:35] neg_lo:[1,0,0] neg_hi:[1,0,0]
	v_pk_fma_f32 v[38:39], v[146:147], v[116:117], v[38:39] neg_lo:[1,0,0] neg_hi:[1,0,0]
	v_pk_fma_f32 v[42:43], v[150:151], v[116:117], v[42:43] neg_lo:[1,0,0] neg_hi:[1,0,0]
	v_pk_fma_f32 v[28:29], v[236:237], v[122:123], v[28:29] neg_lo:[1,0,0] neg_hi:[1,0,0]
	ds_read_b128 v[234:237], v109 offset:13472
	v_pk_fma_f32 v[34:35], v[144:145], v[122:123], v[34:35] neg_lo:[1,0,0] neg_hi:[1,0,0]
	ds_read_b128 v[142:145], v109 offset:13728
	v_pk_fma_f32 v[38:39], v[148:149], v[122:123], v[38:39] neg_lo:[1,0,0] neg_hi:[1,0,0]
	ds_read_b128 v[146:149], v109 offset:13984
	v_pk_fma_f32 v[42:43], v[152:153], v[122:123], v[42:43] neg_lo:[1,0,0] neg_hi:[1,0,0]
	ds_read_b128 v[150:153], v109 offset:14240
	s_waitcnt lgkmcnt(4)
	v_pk_fma_f32 v[28:29], v[154:155], v[128:129], v[28:29] neg_lo:[1,0,0] neg_hi:[1,0,0]
	v_pk_fma_f32 v[34:35], v[158:159], v[128:129], v[34:35] neg_lo:[1,0,0] neg_hi:[1,0,0]
	v_pk_fma_f32 v[38:39], v[220:221], v[128:129], v[38:39] neg_lo:[1,0,0] neg_hi:[1,0,0]
	v_pk_fma_f32 v[42:43], v[230:231], v[128:129], v[42:43] neg_lo:[1,0,0] neg_hi:[1,0,0]
	v_pk_fma_f32 v[28:29], v[156:157], v[134:135], v[28:29] neg_lo:[1,0,0] neg_hi:[1,0,0]
	ds_read_b128 v[154:157], v109 offset:13488
	v_pk_fma_f32 v[34:35], v[160:161], v[134:135], v[34:35] neg_lo:[1,0,0] neg_hi:[1,0,0]
	ds_read_b128 v[158:161], v109 offset:13744
	v_pk_fma_f32 v[38:39], v[222:223], v[134:135], v[38:39] neg_lo:[1,0,0] neg_hi:[1,0,0]
	ds_read_b128 v[220:223], v109 offset:14000
	v_pk_fma_f32 v[42:43], v[232:233], v[134:135], v[42:43] neg_lo:[1,0,0] neg_hi:[1,0,0]
	ds_read_b128 v[230:233], v109 offset:14256
	s_waitcnt lgkmcnt(4)
; #define LAS __attribute__((address_space(3)))
; __device__ __forceinline__ void gdn_local_unit(LAS unsigned char* lds, const GdnP& P, int unit, const int tid, const int pf) {
;     ...
;         for (int c = 1; c < 64; ++c) { f32x2 sp = (f32x2){sol2[c >> 1][c & 1], 0.f};
; #pragma unroll
;             for (int jb = 0; jb <= (c - 1) / 4; ++jb) { const f32x4 m4 = *(const LAS f32x4*)(Ms + c * 64 + 4 * jb);
;                 sp -= (f32x2){m4.x, m4.y} * sol2[2 * jb]; sp -= (f32x2){m4.z, m4.w} * sol2[2 * jb + 1]; }
;             sol2[c >> 1][c & 1] = sp.x + sp.y; }
	v_pk_fma_f32 v[28:29], v[234:235], v[140:141], v[28:29] neg_lo:[1,0,0] neg_hi:[1,0,0]
	v_pk_fma_f32 v[34:35], v[142:143], v[140:141], v[34:35] neg_lo:[1,0,0] neg_hi:[1,0,0]
	v_pk_fma_f32 v[38:39], v[146:147], v[140:141], v[38:39] neg_lo:[1,0,0] neg_hi:[1,0,0]
	v_pk_fma_f32 v[42:43], v[150:151], v[140:141], v[42:43] neg_lo:[1,0,0] neg_hi:[1,0,0]
	v_pk_fma_f32 v[28:29], v[236:237], v[138:139], v[28:29] neg_lo:[1,0,0] neg_hi:[1,0,0]
	ds_read_b128 v[234:237], v109 offset:13504
	v_pk_fma_f32 v[34:35], v[144:145], v[138:139], v[34:35] neg_lo:[1,0,0] neg_hi:[1,0,0]
	ds_read_b128 v[142:145], v109 offset:13760
	v_pk_fma_f32 v[38:39], v[148:149], v[138:139], v[38:39] neg_lo:[1,0,0] neg_hi:[1,0,0]
	ds_read_b128 v[146:149], v109 offset:14016
	v_pk_fma_f32 v[42:43], v[152:153], v[138:139], v[42:43] neg_lo:[1,0,0] neg_hi:[1,0,0]
	ds_read_b128 v[150:153], v109 offset:14272
	s_waitcnt lgkmcnt(4)
	v_pk_fma_f32 v[28:29], v[154:155], v[132:133], v[28:29] neg_lo:[1,0,0] neg_hi:[1,0,0]
	v_pk_fma_f32 v[34:35], v[158:159], v[132:133], v[34:35] neg_lo:[1,0,0] neg_hi:[1,0,0]
	v_pk_fma_f32 v[38:39], v[220:221], v[132:133], v[38:39] neg_lo:[1,0,0] neg_hi:[1,0,0]
	v_pk_fma_f32 v[42:43], v[230:231], v[132:133], v[42:43] neg_lo:[1,0,0] neg_hi:[1,0,0]
	v_pk_fma_f32 v[28:29], v[156:157], v[124:125], v[28:29] neg_lo:[1,0,0] neg_hi:[1,0,0]
	ds_read_b128 v[154:157], v109 offset:14336
	v_pk_fma_f32 v[34:35], v[160:161], v[124:125], v[34:35] neg_lo:[1,0,0] neg_hi:[1,0,0]
	ds_read_b128 v[158:161], v109 offset:14592
	v_pk_fma_f32 v[38:39], v[222:223], v[124:125], v[38:39] neg_lo:[1,0,0] neg_hi:[1,0,0]
	ds_read_b128 v[220:223], v109 offset:14848
	v_pk_fma_f32 v[42:43], v[232:233], v[124:125], v[42:43] neg_lo:[1,0,0] neg_hi:[1,0,0]
	ds_read_b128 v[230:233], v109 offset:15104
	s_waitcnt lgkmcnt(4)
	v_pk_fma_f32 v[28:29], v[234:235], v[118:119], v[28:29] neg_lo:[1,0,0] neg_hi:[1,0,0]
	v_pk_fma_f32 v[34:35], v[142:143], v[118:119], v[34:35] neg_lo:[1,0,0] neg_hi:[1,0,0]
	v_pk_fma_f32 v[38:39], v[146:147], v[118:119], v[38:39] neg_lo:[1,0,0] neg_hi:[1,0,0]
	v_pk_fma_f32 v[42:43], v[150:151], v[118:119], v[42:43] neg_lo:[1,0,0] neg_hi:[1,0,0]
	v_pk_fma_f32 v[28:29], v[236:237], v[74:75], v[28:29] neg_lo:[1,0,0] neg_hi:[1,0,0]
	ds_read_b128 v[234:237], v109 offset:14352
	v_pk_fma_f32 v[34:35], v[144:145], v[74:75], v[34:35] neg_lo:[1,0,0] neg_hi:[1,0,0]
	ds_read_b128 v[142:145], v109 offset:14608
	v_pk_fma_f32 v[38:39], v[148:149], v[74:75], v[38:39] neg_lo:[1,0,0] neg_hi:[1,0,0]
	ds_read_b128 v[146:149], v109 offset:14864
	v_pk_fma_f32 v[42:43], v[152:153], v[74:75], v[42:43] neg_lo:[1,0,0] neg_hi:[1,0,0]
	ds_read_b128 v[150:153], v109 offset:15120
	v_add_f32_e32 v28, v28, v29
	s_waitcnt lgkmcnt(5)
	v_pk_mul_f32 v[10:11], v[154:155], v[0:1] neg_lo:[1,0] neg_hi:[1,0]
	v_pk_mul_f32 v[16:17], v[158:159], v[0:1] neg_lo:[1,0] neg_hi:[1,0]
	v_add_f32_e32 v34, v34, v35
	v_pk_mul_f32 v[20:21], v[220:221], v[0:1] neg_lo:[1,0] neg_hi:[1,0]
	s_waitcnt lgkmcnt(4)
	v_pk_mul_f32 v[24:25], v[230:231], v[0:1] neg_lo:[1,0] neg_hi:[1,0]
	v_add_f32_e32 v38, v38, v39
	v_pk_fma_f32 v[10:11], v[156:157], v[8:9], v[10:11] neg_lo:[1,0,0] neg_hi:[1,0,0]
	ds_read_b128 v[154:157], v109 offset:13776
	v_pk_fma_f32 v[16:17], v[160:161], v[8:9], v[16:17] neg_lo:[1,0,0] neg_hi:[1,0,0]
	ds_read_b128 v[158:161], v109 offset:14368
	v_add_f32_e32 v42, v42, v43
	v_pk_fma_f32 v[20:21], v[222:223], v[8:9], v[20:21] neg_lo:[1,0,0] neg_hi:[1,0,0]
	ds_read_b128 v[220:223], v109 offset:14624
	v_pk_fma_f32 v[24:25], v[232:233], v[8:9], v[24:25] neg_lo:[1,0,0] neg_hi:[1,0,0]
	ds_read_b128 v[230:233], v109 offset:14032
	v_add_f32_e32 v66, v28, v66
	s_waitcnt lgkmcnt(5)
	v_pk_fma_f32 v[10:11], v[234:235], v[14:15], v[10:11] neg_lo:[1,0,0] neg_hi:[1,0,0]
	v_pk_fma_f32 v[16:17], v[142:143], v[14:15], v[16:17] neg_lo:[1,0,0] neg_hi:[1,0,0]
	v_add_f32_e32 v34, v34, v67
	v_pk_fma_f32 v[20:21], v[146:147], v[14:15], v[20:21] neg_lo:[1,0,0] neg_hi:[1,0,0]
	s_waitcnt lgkmcnt(4)
	v_pk_fma_f32 v[24:25], v[150:151], v[14:15], v[24:25] neg_lo:[1,0,0] neg_hi:[1,0,0]
	v_add_f32_e32 v38, v38, v56
	v_pk_fma_f32 v[10:11], v[236:237], v[18:19], v[10:11] neg_lo:[1,0,0] neg_hi:[1,0,0]
	ds_read_b128 v[234:237], v109 offset:14880
	v_pk_fma_f32 v[16:17], v[144:145], v[18:19], v[16:17] neg_lo:[1,0,0] neg_hi:[1,0,0]
	ds_read_b128 v[142:145], v109 offset:15136
	v_add_f32_e32 v42, v42, v57
	v_pk_fma_f32 v[20:21], v[148:149], v[18:19], v[20:21] neg_lo:[1,0,0] neg_hi:[1,0,0]
	ds_read_b128 v[146:149], v109 offset:14288
	v_pk_fma_f32 v[24:25], v[152:153], v[18:19], v[24:25] neg_lo:[1,0,0] neg_hi:[1,0,0]
	ds_read_b128 v[150:153], v109 offset:14384
	s_waitcnt lgkmcnt(4)
	v_fma_f32 v67, -v154, v66, v34
	ds_read_b128 v[154:157], v109 offset:14640
	v_pk_fma_f32 v[10:11], v[158:159], v[22:23], v[10:11] neg_lo:[1,0,0] neg_hi:[1,0,0]
	v_pk_fma_f32 v[16:17], v[220:221], v[22:23], v[16:17] neg_lo:[1,0,0] neg_hi:[1,0,0]
	v_fma_f32 v38, -v230, v66, v38
	s_waitcnt lgkmcnt(2)
	v_pk_fma_f32 v[20:21], v[234:235], v[22:23], v[20:21] neg_lo:[1,0,0] neg_hi:[1,0,0]
	v_pk_fma_f32 v[24:25], v[142:143], v[22:23], v[24:25] neg_lo:[1,0,0] neg_hi:[1,0,0]
	v_fma_f32 v42, -v146, v66, v42
	v_pk_fma_f32 v[10:11], v[160:161], v[26:27], v[10:11] neg_lo:[1,0,0] neg_hi:[1,0,0]
	ds_read_b128 v[158:161], v109 offset:14896
	v_pk_fma_f32 v[16:17], v[222:223], v[26:27], v[16:17] neg_lo:[1,0,0] neg_hi:[1,0,0]
	ds_read_b128 v[220:223], v109 offset:15152
	v_fma_f32 v56, -v231, v67, v38
	ds_read_b128 v[230:233], v109 offset:14400
	v_pk_fma_f32 v[20:21], v[236:237], v[26:27], v[20:21] neg_lo:[1,0,0] neg_hi:[1,0,0]
	ds_read_b128 v[234:237], v109 offset:14656
	v_pk_fma_f32 v[24:25], v[144:145], v[26:27], v[24:25] neg_lo:[1,0,0] neg_hi:[1,0,0]
	ds_read_b128 v[142:145], v109 offset:14912
	v_fma_f32 v42, -v147, v67, v42
	s_waitcnt lgkmcnt(4)
; #define LAS __attribute__((address_space(3)))
; __device__ __forceinline__ void gdn_local_unit(LAS unsigned char* lds, const GdnP& P, int unit, const int tid, const int pf) {
;     ...
;         for (int c = 1; c < 64; ++c) { f32x2 sp = (f32x2){sol2[c >> 1][c & 1], 0.f};
; #pragma unroll
;             for (int jb = 0; jb <= (c - 1) / 4; ++jb) { const f32x4 m4 = *(const LAS f32x4*)(Ms + c * 64 + 4 * jb);
;                 sp -= (f32x2){m4.x, m4.y} * sol2[2 * jb]; sp -= (f32x2){m4.z, m4.w} * sol2[2 * jb + 1]; }
;             sol2[c >> 1][c & 1] = sp.x + sp.y; }
	v_pk_fma_f32 v[10:11], v[150:151], v[30:31], v[10:11] neg_lo:[1,0,0] neg_hi:[1,0,0]
	v_pk_fma_f32 v[16:17], v[154:155], v[30:31], v[16:17] neg_lo:[1,0,0] neg_hi:[1,0,0]
	v_fma_f32 v57, -v148, v56, v42
	ds_read_b128 v[146:149], v109 offset:15168
	v_pk_fma_f32 v[20:21], v[158:159], v[30:31], v[20:21] neg_lo:[1,0,0] neg_hi:[1,0,0]
	s_waitcnt lgkmcnt(4)
	v_pk_fma_f32 v[24:25], v[220:221], v[30:31], v[24:25] neg_lo:[1,0,0] neg_hi:[1,0,0]
	v_pk_fma_f32 v[10:11], v[152:153], v[36:37], v[10:11] neg_lo:[1,0,0] neg_hi:[1,0,0]
	ds_read_b128 v[150:153], v109 offset:14416
	v_pk_fma_f32 v[16:17], v[156:157], v[36:37], v[16:17] neg_lo:[1,0,0] neg_hi:[1,0,0]
	ds_read_b128 v[154:157], v109 offset:14672
	v_pk_fma_f32 v[20:21], v[160:161], v[36:37], v[20:21] neg_lo:[1,0,0] neg_hi:[1,0,0]
	ds_read_b128 v[158:161], v109 offset:14928
	v_pk_fma_f32 v[24:25], v[222:223], v[36:37], v[24:25] neg_lo:[1,0,0] neg_hi:[1,0,0]
	ds_read_b128 v[220:223], v109 offset:15184
	s_waitcnt lgkmcnt(4)
	v_pk_fma_f32 v[10:11], v[230:231], v[40:41], v[10:11] neg_lo:[1,0,0] neg_hi:[1,0,0]
	v_pk_fma_f32 v[16:17], v[234:235], v[40:41], v[16:17] neg_lo:[1,0,0] neg_hi:[1,0,0]
	v_pk_fma_f32 v[20:21], v[142:143], v[40:41], v[20:21] neg_lo:[1,0,0] neg_hi:[1,0,0]
	v_pk_fma_f32 v[24:25], v[146:147], v[40:41], v[24:25] neg_lo:[1,0,0] neg_hi:[1,0,0]
	v_pk_fma_f32 v[10:11], v[232:233], v[44:45], v[10:11] neg_lo:[1,0,0] neg_hi:[1,0,0]
	ds_read_b128 v[230:233], v109 offset:14432
	v_pk_fma_f32 v[16:17], v[236:237], v[44:45], v[16:17] neg_lo:[1,0,0] neg_hi:[1,0,0]
	ds_read_b128 v[234:237], v109 offset:14688
	v_pk_fma_f32 v[20:21], v[144:145], v[44:45], v[20:21] neg_lo:[1,0,0] neg_hi:[1,0,0]
	ds_read_b128 v[142:145], v109 offset:14944
	v_pk_fma_f32 v[24:25], v[148:149], v[44:45], v[24:25] neg_lo:[1,0,0] neg_hi:[1,0,0]
	ds_read_b128 v[146:149], v109 offset:15200
	s_waitcnt lgkmcnt(4)
	v_pk_fma_f32 v[10:11], v[150:151], v[50:51], v[10:11] neg_lo:[1,0,0] neg_hi:[1,0,0]
	v_pk_fma_f32 v[16:17], v[154:155], v[50:51], v[16:17] neg_lo:[1,0,0] neg_hi:[1,0,0]
	v_pk_fma_f32 v[20:21], v[158:159], v[50:51], v[20:21] neg_lo:[1,0,0] neg_hi:[1,0,0]
	v_pk_fma_f32 v[24:25], v[220:221], v[50:51], v[24:25] neg_lo:[1,0,0] neg_hi:[1,0,0]
	v_pk_fma_f32 v[10:11], v[152:153], v[54:55], v[10:11] neg_lo:[1,0,0] neg_hi:[1,0,0]
	ds_read_b128 v[150:153], v109 offset:14448
	v_pk_fma_f32 v[16:17], v[156:157], v[54:55], v[16:17] neg_lo:[1,0,0] neg_hi:[1,0,0]
	ds_read_b128 v[154:157], v109 offset:14704
	v_pk_fma_f32 v[20:21], v[160:161], v[54:55], v[20:21] neg_lo:[1,0,0] neg_hi:[1,0,0]
	ds_read_b128 v[158:161], v109 offset:14960
	v_pk_fma_f32 v[24:25], v[222:223], v[54:55], v[24:25] neg_lo:[1,0,0] neg_hi:[1,0,0]
	ds_read_b128 v[220:223], v109 offset:15216
	s_waitcnt lgkmcnt(4)
	v_pk_fma_f32 v[10:11], v[230:231], v[60:61], v[10:11] neg_lo:[1,0,0] neg_hi:[1,0,0]
	v_pk_fma_f32 v[16:17], v[234:235], v[60:61], v[16:17] neg_lo:[1,0,0] neg_hi:[1,0,0]
	v_pk_fma_f32 v[20:21], v[142:143], v[60:61], v[20:21] neg_lo:[1,0,0] neg_hi:[1,0,0]
	v_pk_fma_f32 v[24:25], v[146:147], v[60:61], v[24:25] neg_lo:[1,0,0] neg_hi:[1,0,0]
	v_pk_fma_f32 v[10:11], v[232:233], v[64:65], v[10:11] neg_lo:[1,0,0] neg_hi:[1,0,0]
	ds_read_b128 v[230:233], v109 offset:14464
	v_pk_fma_f32 v[16:17], v[236:237], v[64:65], v[16:17] neg_lo:[1,0,0] neg_hi:[1,0,0]
	ds_read_b128 v[234:237], v109 offset:14720
	v_pk_fma_f32 v[20:21], v[144:145], v[64:65], v[20:21] neg_lo:[1,0,0] neg_hi:[1,0,0]
	ds_read_b128 v[142:145], v109 offset:14976
	v_pk_fma_f32 v[24:25], v[148:149], v[64:65], v[24:25] neg_lo:[1,0,0] neg_hi:[1,0,0]
	ds_read_b128 v[146:149], v109 offset:15232
	s_waitcnt lgkmcnt(4)
	v_pk_fma_f32 v[10:11], v[150:151], v[70:71], v[10:11] neg_lo:[1,0,0] neg_hi:[1,0,0]
	v_pk_fma_f32 v[16:17], v[154:155], v[70:71], v[16:17] neg_lo:[1,0,0] neg_hi:[1,0,0]
	v_pk_fma_f32 v[20:21], v[158:159], v[70:71], v[20:21] neg_lo:[1,0,0] neg_hi:[1,0,0]
	v_pk_fma_f32 v[24:25], v[220:221], v[70:71], v[24:25] neg_lo:[1,0,0] neg_hi:[1,0,0]
	v_pk_fma_f32 v[10:11], v[152:153], v[112:113], v[10:11] neg_lo:[1,0,0] neg_hi:[1,0,0]
	ds_read_b128 v[150:153], v109 offset:14480
	v_pk_fma_f32 v[16:17], v[156:157], v[112:113], v[16:17] neg_lo:[1,0,0] neg_hi:[1,0,0]
	ds_read_b128 v[154:157], v109 offset:14736
	v_pk_fma_f32 v[20:21], v[160:161], v[112:113], v[20:21] neg_lo:[1,0,0] neg_hi:[1,0,0]
	ds_read_b128 v[158:161], v109 offset:14992
	v_pk_fma_f32 v[24:25], v[222:223], v[112:113], v[24:25] neg_lo:[1,0,0] neg_hi:[1,0,0]
	ds_read_b128 v[220:223], v109 offset:15248
	s_waitcnt lgkmcnt(4)
	v_pk_fma_f32 v[10:11], v[230:231], v[116:117], v[10:11] neg_lo:[1,0,0] neg_hi:[1,0,0]
	v_pk_fma_f32 v[16:17], v[234:235], v[116:117], v[16:17] neg_lo:[1,0,0] neg_hi:[1,0,0]
	v_pk_fma_f32 v[20:21], v[142:143], v[116:117], v[20:21] neg_lo:[1,0,0] neg_hi:[1,0,0]
	v_pk_fma_f32 v[24:25], v[146:147], v[116:117], v[24:25] neg_lo:[1,0,0] neg_hi:[1,0,0]
	v_pk_fma_f32 v[10:11], v[232:233], v[122:123], v[10:11] neg_lo:[1,0,0] neg_hi:[1,0,0]
	ds_read_b128 v[230:233], v109 offset:14496
	v_pk_fma_f32 v[16:17], v[236:237], v[122:123], v[16:17] neg_lo:[1,0,0] neg_hi:[1,0,0]
	ds_read_b128 v[234:237], v109 offset:14752
	v_pk_fma_f32 v[20:21], v[144:145], v[122:123], v[20:21] neg_lo:[1,0,0] neg_hi:[1,0,0]
	ds_read_b128 v[142:145], v109 offset:15008
	v_pk_fma_f32 v[24:25], v[148:149], v[122:123], v[24:25] neg_lo:[1,0,0] neg_hi:[1,0,0]
	ds_read_b128 v[146:149], v109 offset:15264
	s_waitcnt lgkmcnt(4)
; #define LAS __attribute__((address_space(3)))
; __device__ __forceinline__ void gdn_local_unit(LAS unsigned char* lds, const GdnP& P, int unit, const int tid, const int pf) {
;     ...
;         for (int c = 1; c < 64; ++c) { f32x2 sp = (f32x2){sol2[c >> 1][c & 1], 0.f};
; #pragma unroll
;             for (int jb = 0; jb <= (c - 1) / 4; ++jb) { const f32x4 m4 = *(const LAS f32x4*)(Ms + c * 64 + 4 * jb);
;                 sp -= (f32x2){m4.x, m4.y} * sol2[2 * jb]; sp -= (f32x2){m4.z, m4.w} * sol2[2 * jb + 1]; }
;             sol2[c >> 1][c & 1] = sp.x + sp.y; }
	v_pk_fma_f32 v[10:11], v[150:151], v[128:129], v[10:11] neg_lo:[1,0,0] neg_hi:[1,0,0]
	v_pk_fma_f32 v[16:17], v[154:155], v[128:129], v[16:17] neg_lo:[1,0,0] neg_hi:[1,0,0]
	v_pk_fma_f32 v[20:21], v[158:159], v[128:129], v[20:21] neg_lo:[1,0,0] neg_hi:[1,0,0]
	v_pk_fma_f32 v[24:25], v[220:221], v[128:129], v[24:25] neg_lo:[1,0,0] neg_hi:[1,0,0]
	v_pk_fma_f32 v[10:11], v[152:153], v[134:135], v[10:11] neg_lo:[1,0,0] neg_hi:[1,0,0]
	ds_read_b128 v[150:153], v109 offset:14512
	v_pk_fma_f32 v[16:17], v[156:157], v[134:135], v[16:17] neg_lo:[1,0,0] neg_hi:[1,0,0]
	ds_read_b128 v[154:157], v109 offset:14768
	v_pk_fma_f32 v[20:21], v[160:161], v[134:135], v[20:21] neg_lo:[1,0,0] neg_hi:[1,0,0]
	ds_read_b128 v[158:161], v109 offset:15024
	v_pk_fma_f32 v[24:25], v[222:223], v[134:135], v[24:25] neg_lo:[1,0,0] neg_hi:[1,0,0]
	ds_read_b128 v[220:223], v109 offset:15280
	s_waitcnt lgkmcnt(4)
	v_pk_fma_f32 v[10:11], v[230:231], v[140:141], v[10:11] neg_lo:[1,0,0] neg_hi:[1,0,0]
	v_pk_fma_f32 v[16:17], v[234:235], v[140:141], v[16:17] neg_lo:[1,0,0] neg_hi:[1,0,0]
	v_pk_fma_f32 v[20:21], v[142:143], v[140:141], v[20:21] neg_lo:[1,0,0] neg_hi:[1,0,0]
	v_pk_fma_f32 v[24:25], v[146:147], v[140:141], v[24:25] neg_lo:[1,0,0] neg_hi:[1,0,0]
	v_pk_fma_f32 v[10:11], v[232:233], v[138:139], v[10:11] neg_lo:[1,0,0] neg_hi:[1,0,0]
	ds_read_b128 v[230:233], v109 offset:14528
	v_pk_fma_f32 v[16:17], v[236:237], v[138:139], v[16:17] neg_lo:[1,0,0] neg_hi:[1,0,0]
	ds_read_b128 v[234:237], v109 offset:14784
	v_pk_fma_f32 v[20:21], v[144:145], v[138:139], v[20:21] neg_lo:[1,0,0] neg_hi:[1,0,0]
	ds_read_b128 v[142:145], v109 offset:15040
	v_pk_fma_f32 v[24:25], v[148:149], v[138:139], v[24:25] neg_lo:[1,0,0] neg_hi:[1,0,0]
	ds_read_b128 v[146:149], v109 offset:15296
	s_waitcnt lgkmcnt(4)
	v_pk_fma_f32 v[10:11], v[150:151], v[132:133], v[10:11] neg_lo:[1,0,0] neg_hi:[1,0,0]
	v_pk_fma_f32 v[16:17], v[154:155], v[132:133], v[16:17] neg_lo:[1,0,0] neg_hi:[1,0,0]
	v_pk_fma_f32 v[20:21], v[158:159], v[132:133], v[20:21] neg_lo:[1,0,0] neg_hi:[1,0,0]
	v_pk_fma_f32 v[24:25], v[220:221], v[132:133], v[24:25] neg_lo:[1,0,0] neg_hi:[1,0,0]
	v_pk_fma_f32 v[10:11], v[152:153], v[124:125], v[10:11] neg_lo:[1,0,0] neg_hi:[1,0,0]
	ds_read_b128 v[150:153], v109 offset:14544
	v_pk_fma_f32 v[16:17], v[156:157], v[124:125], v[16:17] neg_lo:[1,0,0] neg_hi:[1,0,0]
	ds_read_b128 v[154:157], v109 offset:14800
	v_pk_fma_f32 v[20:21], v[160:161], v[124:125], v[20:21] neg_lo:[1,0,0] neg_hi:[1,0,0]
	ds_read_b128 v[158:161], v109 offset:15056
	v_pk_fma_f32 v[24:25], v[222:223], v[124:125], v[24:25] neg_lo:[1,0,0] neg_hi:[1,0,0]
	ds_read_b128 v[220:223], v109 offset:15312
	s_waitcnt lgkmcnt(4)
	v_pk_fma_f32 v[10:11], v[230:231], v[118:119], v[10:11] neg_lo:[1,0,0] neg_hi:[1,0,0]
	v_pk_fma_f32 v[16:17], v[234:235], v[118:119], v[16:17] neg_lo:[1,0,0] neg_hi:[1,0,0]
	v_pk_fma_f32 v[20:21], v[142:143], v[118:119], v[20:21] neg_lo:[1,0,0] neg_hi:[1,0,0]
	v_pk_fma_f32 v[24:25], v[146:147], v[118:119], v[24:25] neg_lo:[1,0,0] neg_hi:[1,0,0]
	v_pk_fma_f32 v[10:11], v[232:233], v[74:75], v[10:11] neg_lo:[1,0,0] neg_hi:[1,0,0]
	ds_read_b128 v[230:233], v109 offset:15360
	v_pk_fma_f32 v[16:17], v[236:237], v[74:75], v[16:17] neg_lo:[1,0,0] neg_hi:[1,0,0]
	ds_read_b128 v[234:237], v109 offset:15616
	v_pk_fma_f32 v[20:21], v[144:145], v[74:75], v[20:21] neg_lo:[1,0,0] neg_hi:[1,0,0]
	ds_read_b128 v[142:145], v109 offset:15872
	v_pk_fma_f32 v[24:25], v[148:149], v[74:75], v[24:25] neg_lo:[1,0,0] neg_hi:[1,0,0]
	ds_read_b128 v[146:149], v109 offset:16128
	s_waitcnt lgkmcnt(4)
	v_pk_fma_f32 v[10:11], v[150:151], v[66:67], v[10:11] neg_lo:[1,0,0] neg_hi:[1,0,0]
	v_pk_fma_f32 v[16:17], v[154:155], v[66:67], v[16:17] neg_lo:[1,0,0] neg_hi:[1,0,0]
	v_pk_fma_f32 v[20:21], v[158:159], v[66:67], v[20:21] neg_lo:[1,0,0] neg_hi:[1,0,0]
	v_pk_fma_f32 v[24:25], v[220:221], v[66:67], v[24:25] neg_lo:[1,0,0] neg_hi:[1,0,0]
	v_pk_fma_f32 v[10:11], v[152:153], v[56:57], v[10:11] neg_lo:[1,0,0] neg_hi:[1,0,0]
	ds_read_b128 v[150:153], v109 offset:15376
	v_pk_fma_f32 v[16:17], v[156:157], v[56:57], v[16:17] neg_lo:[1,0,0] neg_hi:[1,0,0]
	ds_read_b128 v[154:157], v109 offset:15632
	v_pk_fma_f32 v[20:21], v[160:161], v[56:57], v[20:21] neg_lo:[1,0,0] neg_hi:[1,0,0]
	ds_read_b128 v[158:161], v109 offset:15888
	v_pk_fma_f32 v[24:25], v[222:223], v[56:57], v[24:25] neg_lo:[1,0,0] neg_hi:[1,0,0]
	ds_read_b128 v[220:223], v109 offset:16144
	v_add_f32_e32 v10, v10, v11
	s_waitcnt lgkmcnt(5)
	v_pk_mul_f32 v[28:29], v[230:231], v[0:1] neg_lo:[1,0] neg_hi:[1,0]
	v_pk_mul_f32 v[34:35], v[234:235], v[0:1] neg_lo:[1,0] neg_hi:[1,0]
	v_add_f32_e32 v16, v16, v17
	v_pk_mul_f32 v[38:39], v[142:143], v[0:1] neg_lo:[1,0] neg_hi:[1,0]
	s_waitcnt lgkmcnt(4)
	v_pk_mul_f32 v[42:43], v[146:147], v[0:1] neg_lo:[1,0] neg_hi:[1,0]
	v_add_f32_e32 v20, v20, v21
	v_pk_fma_f32 v[28:29], v[232:233], v[8:9], v[28:29] neg_lo:[1,0,0] neg_hi:[1,0,0]
	ds_read_b128 v[230:233], v109 offset:14816
	v_pk_fma_f32 v[34:35], v[236:237], v[8:9], v[34:35] neg_lo:[1,0,0] neg_hi:[1,0,0]
	ds_read_b128 v[234:237], v109 offset:15392
	v_add_f32_e32 v24, v24, v25
	v_pk_fma_f32 v[38:39], v[144:145], v[8:9], v[38:39] neg_lo:[1,0,0] neg_hi:[1,0,0]
	ds_read_b128 v[142:145], v109 offset:15648
	v_pk_fma_f32 v[42:43], v[148:149], v[8:9], v[42:43] neg_lo:[1,0,0] neg_hi:[1,0,0]
	ds_read_b128 v[146:149], v109 offset:15072
	v_add_f32_e32 v46, v10, v46
	s_waitcnt lgkmcnt(5)
	v_pk_fma_f32 v[28:29], v[150:151], v[14:15], v[28:29] neg_lo:[1,0,0] neg_hi:[1,0,0]
	v_pk_fma_f32 v[34:35], v[154:155], v[14:15], v[34:35] neg_lo:[1,0,0] neg_hi:[1,0,0]
	v_add_f32_e32 v16, v16, v47
	v_pk_fma_f32 v[38:39], v[158:159], v[14:15], v[38:39] neg_lo:[1,0,0] neg_hi:[1,0,0]
	s_waitcnt lgkmcnt(4)
; #define LAS __attribute__((address_space(3)))
; __device__ __forceinline__ void gdn_local_unit(LAS unsigned char* lds, const GdnP& P, int unit, const int tid, const int pf) {
;     ...
;         for (int c = 1; c < 64; ++c) { f32x2 sp = (f32x2){sol2[c >> 1][c & 1], 0.f};
; #pragma unroll
;             for (int jb = 0; jb <= (c - 1) / 4; ++jb) { const f32x4 m4 = *(const LAS f32x4*)(Ms + c * 64 + 4 * jb);
;                 sp -= (f32x2){m4.x, m4.y} * sol2[2 * jb]; sp -= (f32x2){m4.z, m4.w} * sol2[2 * jb + 1]; }
;             sol2[c >> 1][c & 1] = sp.x + sp.y; }
	v_pk_fma_f32 v[42:43], v[220:221], v[14:15], v[42:43] neg_lo:[1,0,0] neg_hi:[1,0,0]
	v_add_f32_e32 v20, v20, v32
	v_pk_fma_f32 v[28:29], v[152:153], v[18:19], v[28:29] neg_lo:[1,0,0] neg_hi:[1,0,0]
	ds_read_b128 v[150:153], v109 offset:15904
	v_pk_fma_f32 v[34:35], v[156:157], v[18:19], v[34:35] neg_lo:[1,0,0] neg_hi:[1,0,0]
	ds_read_b128 v[154:157], v109 offset:16160
	v_add_f32_e32 v24, v24, v33
	v_pk_fma_f32 v[38:39], v[160:161], v[18:19], v[38:39] neg_lo:[1,0,0] neg_hi:[1,0,0]
	ds_read_b128 v[158:161], v109 offset:15328
	v_pk_fma_f32 v[42:43], v[222:223], v[18:19], v[42:43] neg_lo:[1,0,0] neg_hi:[1,0,0]
	ds_read_b128 v[220:223], v109 offset:15408
	s_waitcnt lgkmcnt(4)
	v_fma_f32 v47, -v230, v46, v16
	ds_read_b128 v[230:233], v109 offset:15664
	v_pk_fma_f32 v[28:29], v[234:235], v[22:23], v[28:29] neg_lo:[1,0,0] neg_hi:[1,0,0]
	v_pk_fma_f32 v[34:35], v[142:143], v[22:23], v[34:35] neg_lo:[1,0,0] neg_hi:[1,0,0]
	v_fma_f32 v20, -v146, v46, v20
	s_waitcnt lgkmcnt(2)
	v_pk_fma_f32 v[38:39], v[150:151], v[22:23], v[38:39] neg_lo:[1,0,0] neg_hi:[1,0,0]
	v_pk_fma_f32 v[42:43], v[154:155], v[22:23], v[42:43] neg_lo:[1,0,0] neg_hi:[1,0,0]
	v_fma_f32 v24, -v158, v46, v24
	v_pk_fma_f32 v[28:29], v[236:237], v[26:27], v[28:29] neg_lo:[1,0,0] neg_hi:[1,0,0]
	ds_read_b128 v[234:237], v109 offset:15920
	v_pk_fma_f32 v[34:35], v[144:145], v[26:27], v[34:35] neg_lo:[1,0,0] neg_hi:[1,0,0]
	ds_read_b128 v[142:145], v109 offset:16176
	v_fma_f32 v32, -v147, v47, v20
	ds_read_b128 v[146:149], v109 offset:15424
	v_pk_fma_f32 v[38:39], v[152:153], v[26:27], v[38:39] neg_lo:[1,0,0] neg_hi:[1,0,0]
	ds_read_b128 v[150:153], v109 offset:15680
	v_pk_fma_f32 v[42:43], v[156:157], v[26:27], v[42:43] neg_lo:[1,0,0] neg_hi:[1,0,0]
	ds_read_b128 v[154:157], v109 offset:15936
	v_fma_f32 v24, -v159, v47, v24
	s_waitcnt lgkmcnt(4)
	v_pk_fma_f32 v[28:29], v[220:221], v[30:31], v[28:29] neg_lo:[1,0,0] neg_hi:[1,0,0]
	v_pk_fma_f32 v[34:35], v[230:231], v[30:31], v[34:35] neg_lo:[1,0,0] neg_hi:[1,0,0]
	v_fma_f32 v33, -v160, v32, v24
	ds_read_b128 v[158:161], v109 offset:16192
	v_pk_fma_f32 v[38:39], v[234:235], v[30:31], v[38:39] neg_lo:[1,0,0] neg_hi:[1,0,0]
	s_waitcnt lgkmcnt(4)
	v_pk_fma_f32 v[42:43], v[142:143], v[30:31], v[42:43] neg_lo:[1,0,0] neg_hi:[1,0,0]
	v_pk_fma_f32 v[28:29], v[222:223], v[36:37], v[28:29] neg_lo:[1,0,0] neg_hi:[1,0,0]
	ds_read_b128 v[220:223], v109 offset:15440
	v_pk_fma_f32 v[34:35], v[232:233], v[36:37], v[34:35] neg_lo:[1,0,0] neg_hi:[1,0,0]
	ds_read_b128 v[230:233], v109 offset:15696
	v_pk_fma_f32 v[38:39], v[236:237], v[36:37], v[38:39] neg_lo:[1,0,0] neg_hi:[1,0,0]
	ds_read_b128 v[234:237], v109 offset:15952
	v_pk_fma_f32 v[42:43], v[144:145], v[36:37], v[42:43] neg_lo:[1,0,0] neg_hi:[1,0,0]
	ds_read_b128 v[142:145], v109 offset:16208
	s_waitcnt lgkmcnt(4)
	v_pk_fma_f32 v[28:29], v[146:147], v[40:41], v[28:29] neg_lo:[1,0,0] neg_hi:[1,0,0]
	v_pk_fma_f32 v[34:35], v[150:151], v[40:41], v[34:35] neg_lo:[1,0,0] neg_hi:[1,0,0]
	v_pk_fma_f32 v[38:39], v[154:155], v[40:41], v[38:39] neg_lo:[1,0,0] neg_hi:[1,0,0]
	v_pk_fma_f32 v[42:43], v[158:159], v[40:41], v[42:43] neg_lo:[1,0,0] neg_hi:[1,0,0]
	v_pk_fma_f32 v[28:29], v[148:149], v[44:45], v[28:29] neg_lo:[1,0,0] neg_hi:[1,0,0]
	ds_read_b128 v[146:149], v109 offset:15456
	v_pk_fma_f32 v[34:35], v[152:153], v[44:45], v[34:35] neg_lo:[1,0,0] neg_hi:[1,0,0]
	ds_read_b128 v[150:153], v109 offset:15712
	v_pk_fma_f32 v[38:39], v[156:157], v[44:45], v[38:39] neg_lo:[1,0,0] neg_hi:[1,0,0]
	ds_read_b128 v[154:157], v109 offset:15968
	v_pk_fma_f32 v[42:43], v[160:161], v[44:45], v[42:43] neg_lo:[1,0,0] neg_hi:[1,0,0]
	ds_read_b128 v[158:161], v109 offset:16224
	s_waitcnt lgkmcnt(4)
	v_pk_fma_f32 v[28:29], v[220:221], v[50:51], v[28:29] neg_lo:[1,0,0] neg_hi:[1,0,0]
	v_pk_fma_f32 v[34:35], v[230:231], v[50:51], v[34:35] neg_lo:[1,0,0] neg_hi:[1,0,0]
	v_pk_fma_f32 v[38:39], v[234:235], v[50:51], v[38:39] neg_lo:[1,0,0] neg_hi:[1,0,0]
	v_pk_fma_f32 v[42:43], v[142:143], v[50:51], v[42:43] neg_lo:[1,0,0] neg_hi:[1,0,0]
	v_pk_fma_f32 v[28:29], v[222:223], v[54:55], v[28:29] neg_lo:[1,0,0] neg_hi:[1,0,0]
	ds_read_b128 v[220:223], v109 offset:15472
	v_pk_fma_f32 v[34:35], v[232:233], v[54:55], v[34:35] neg_lo:[1,0,0] neg_hi:[1,0,0]
	ds_read_b128 v[230:233], v109 offset:15728
	v_pk_fma_f32 v[38:39], v[236:237], v[54:55], v[38:39] neg_lo:[1,0,0] neg_hi:[1,0,0]
	ds_read_b128 v[234:237], v109 offset:15984
	v_pk_fma_f32 v[42:43], v[144:145], v[54:55], v[42:43] neg_lo:[1,0,0] neg_hi:[1,0,0]
	ds_read_b128 v[142:145], v109 offset:16240
	s_waitcnt lgkmcnt(4)
	v_pk_fma_f32 v[28:29], v[146:147], v[60:61], v[28:29] neg_lo:[1,0,0] neg_hi:[1,0,0]
	v_pk_fma_f32 v[34:35], v[150:151], v[60:61], v[34:35] neg_lo:[1,0,0] neg_hi:[1,0,0]
	v_pk_fma_f32 v[38:39], v[154:155], v[60:61], v[38:39] neg_lo:[1,0,0] neg_hi:[1,0,0]
	v_pk_fma_f32 v[42:43], v[158:159], v[60:61], v[42:43] neg_lo:[1,0,0] neg_hi:[1,0,0]
	v_pk_fma_f32 v[28:29], v[148:149], v[64:65], v[28:29] neg_lo:[1,0,0] neg_hi:[1,0,0]
	ds_read_b128 v[146:149], v109 offset:15488
	v_pk_fma_f32 v[34:35], v[152:153], v[64:65], v[34:35] neg_lo:[1,0,0] neg_hi:[1,0,0]
	ds_read_b128 v[150:153], v109 offset:15744
	v_pk_fma_f32 v[38:39], v[156:157], v[64:65], v[38:39] neg_lo:[1,0,0] neg_hi:[1,0,0]
	ds_read_b128 v[154:157], v109 offset:16000
	v_pk_fma_f32 v[42:43], v[160:161], v[64:65], v[42:43] neg_lo:[1,0,0] neg_hi:[1,0,0]
	ds_read_b128 v[158:161], v109 offset:16256
	s_waitcnt lgkmcnt(4)
; #define LAS __attribute__((address_space(3)))
; __device__ __forceinline__ void gdn_local_unit(LAS unsigned char* lds, const GdnP& P, int unit, const int tid, const int pf) {
;     ...
;         for (int c = 1; c < 64; ++c) { f32x2 sp = (f32x2){sol2[c >> 1][c & 1], 0.f};
; #pragma unroll
;             for (int jb = 0; jb <= (c - 1) / 4; ++jb) { const f32x4 m4 = *(const LAS f32x4*)(Ms + c * 64 + 4 * jb);
;                 sp -= (f32x2){m4.x, m4.y} * sol2[2 * jb]; sp -= (f32x2){m4.z, m4.w} * sol2[2 * jb + 1]; }
;             sol2[c >> 1][c & 1] = sp.x + sp.y; }
	v_pk_fma_f32 v[28:29], v[220:221], v[70:71], v[28:29] neg_lo:[1,0,0] neg_hi:[1,0,0]
	v_pk_fma_f32 v[34:35], v[230:231], v[70:71], v[34:35] neg_lo:[1,0,0] neg_hi:[1,0,0]
	v_pk_fma_f32 v[38:39], v[234:235], v[70:71], v[38:39] neg_lo:[1,0,0] neg_hi:[1,0,0]
	v_pk_fma_f32 v[42:43], v[142:143], v[70:71], v[42:43] neg_lo:[1,0,0] neg_hi:[1,0,0]
	v_pk_fma_f32 v[28:29], v[222:223], v[112:113], v[28:29] neg_lo:[1,0,0] neg_hi:[1,0,0]
	ds_read_b128 v[220:223], v109 offset:15504
	v_pk_fma_f32 v[34:35], v[232:233], v[112:113], v[34:35] neg_lo:[1,0,0] neg_hi:[1,0,0]
	ds_read_b128 v[230:233], v109 offset:15760
	v_pk_fma_f32 v[38:39], v[236:237], v[112:113], v[38:39] neg_lo:[1,0,0] neg_hi:[1,0,0]
	ds_read_b128 v[234:237], v109 offset:16016
	v_pk_fma_f32 v[42:43], v[144:145], v[112:113], v[42:43] neg_lo:[1,0,0] neg_hi:[1,0,0]
	ds_read_b128 v[142:145], v109 offset:16272
	s_waitcnt lgkmcnt(4)
	v_pk_fma_f32 v[28:29], v[146:147], v[116:117], v[28:29] neg_lo:[1,0,0] neg_hi:[1,0,0]
	v_pk_fma_f32 v[34:35], v[150:151], v[116:117], v[34:35] neg_lo:[1,0,0] neg_hi:[1,0,0]
	v_pk_fma_f32 v[38:39], v[154:155], v[116:117], v[38:39] neg_lo:[1,0,0] neg_hi:[1,0,0]
	v_pk_fma_f32 v[42:43], v[158:159], v[116:117], v[42:43] neg_lo:[1,0,0] neg_hi:[1,0,0]
	v_pk_fma_f32 v[28:29], v[148:149], v[122:123], v[28:29] neg_lo:[1,0,0] neg_hi:[1,0,0]
	ds_read_b128 v[146:149], v109 offset:15520
	v_pk_fma_f32 v[34:35], v[152:153], v[122:123], v[34:35] neg_lo:[1,0,0] neg_hi:[1,0,0]
	ds_read_b128 v[150:153], v109 offset:15776
	v_pk_fma_f32 v[38:39], v[156:157], v[122:123], v[38:39] neg_lo:[1,0,0] neg_hi:[1,0,0]
	ds_read_b128 v[154:157], v109 offset:16032
	v_pk_fma_f32 v[42:43], v[160:161], v[122:123], v[42:43] neg_lo:[1,0,0] neg_hi:[1,0,0]
	ds_read_b128 v[158:161], v109 offset:16288
	s_waitcnt lgkmcnt(4)
	v_pk_fma_f32 v[28:29], v[220:221], v[128:129], v[28:29] neg_lo:[1,0,0] neg_hi:[1,0,0]
	v_pk_fma_f32 v[34:35], v[230:231], v[128:129], v[34:35] neg_lo:[1,0,0] neg_hi:[1,0,0]
	v_pk_fma_f32 v[38:39], v[234:235], v[128:129], v[38:39] neg_lo:[1,0,0] neg_hi:[1,0,0]
	v_pk_fma_f32 v[42:43], v[142:143], v[128:129], v[42:43] neg_lo:[1,0,0] neg_hi:[1,0,0]
	v_pk_fma_f32 v[28:29], v[222:223], v[134:135], v[28:29] neg_lo:[1,0,0] neg_hi:[1,0,0]
	ds_read_b128 v[220:223], v109 offset:15536
	v_pk_fma_f32 v[34:35], v[232:233], v[134:135], v[34:35] neg_lo:[1,0,0] neg_hi:[1,0,0]
	ds_read_b128 v[230:233], v109 offset:15792
	v_pk_fma_f32 v[38:39], v[236:237], v[134:135], v[38:39] neg_lo:[1,0,0] neg_hi:[1,0,0]
	ds_read_b128 v[234:237], v109 offset:16048
	v_pk_fma_f32 v[42:43], v[144:145], v[134:135], v[42:43] neg_lo:[1,0,0] neg_hi:[1,0,0]
	ds_read_b128 v[142:145], v109 offset:16304
	s_waitcnt lgkmcnt(4)
	v_pk_fma_f32 v[28:29], v[146:147], v[140:141], v[28:29] neg_lo:[1,0,0] neg_hi:[1,0,0]
	v_pk_fma_f32 v[34:35], v[150:151], v[140:141], v[34:35] neg_lo:[1,0,0] neg_hi:[1,0,0]
	v_pk_fma_f32 v[38:39], v[154:155], v[140:141], v[38:39] neg_lo:[1,0,0] neg_hi:[1,0,0]
	v_pk_fma_f32 v[42:43], v[158:159], v[140:141], v[42:43] neg_lo:[1,0,0] neg_hi:[1,0,0]
	v_pk_fma_f32 v[28:29], v[148:149], v[138:139], v[28:29] neg_lo:[1,0,0] neg_hi:[1,0,0]
	ds_read_b128 v[146:149], v109 offset:15552
	v_pk_fma_f32 v[34:35], v[152:153], v[138:139], v[34:35] neg_lo:[1,0,0] neg_hi:[1,0,0]
	ds_read_b128 v[150:153], v109 offset:15808
	v_pk_fma_f32 v[38:39], v[156:157], v[138:139], v[38:39] neg_lo:[1,0,0] neg_hi:[1,0,0]
	ds_read_b128 v[154:157], v109 offset:16064
	v_pk_fma_f32 v[42:43], v[160:161], v[138:139], v[42:43] neg_lo:[1,0,0] neg_hi:[1,0,0]
	ds_read_b128 v[158:161], v109 offset:16320
	s_waitcnt lgkmcnt(4)
	v_pk_fma_f32 v[28:29], v[220:221], v[132:133], v[28:29] neg_lo:[1,0,0] neg_hi:[1,0,0]
	v_pk_fma_f32 v[34:35], v[230:231], v[132:133], v[34:35] neg_lo:[1,0,0] neg_hi:[1,0,0]
	v_pk_fma_f32 v[38:39], v[234:235], v[132:133], v[38:39] neg_lo:[1,0,0] neg_hi:[1,0,0]
	v_pk_fma_f32 v[42:43], v[142:143], v[132:133], v[42:43] neg_lo:[1,0,0] neg_hi:[1,0,0]
	v_pk_fma_f32 v[28:29], v[222:223], v[124:125], v[28:29] neg_lo:[1,0,0] neg_hi:[1,0,0]
	ds_read_b128 v[220:223], v109 offset:15568
	v_pk_fma_f32 v[34:35], v[232:233], v[124:125], v[34:35] neg_lo:[1,0,0] neg_hi:[1,0,0]
	ds_read_b128 v[230:233], v109 offset:15824
	v_pk_fma_f32 v[38:39], v[236:237], v[124:125], v[38:39] neg_lo:[1,0,0] neg_hi:[1,0,0]
	ds_read_b128 v[234:237], v109 offset:16080
	v_pk_fma_f32 v[42:43], v[144:145], v[124:125], v[42:43] neg_lo:[1,0,0] neg_hi:[1,0,0]
	ds_read_b128 v[142:145], v109 offset:16336
	s_waitcnt lgkmcnt(4)
	v_pk_fma_f32 v[28:29], v[146:147], v[118:119], v[28:29] neg_lo:[1,0,0] neg_hi:[1,0,0]
	v_pk_fma_f32 v[34:35], v[150:151], v[118:119], v[34:35] neg_lo:[1,0,0] neg_hi:[1,0,0]
	v_pk_fma_f32 v[38:39], v[154:155], v[118:119], v[38:39] neg_lo:[1,0,0] neg_hi:[1,0,0]
	v_pk_fma_f32 v[42:43], v[158:159], v[118:119], v[42:43] neg_lo:[1,0,0] neg_hi:[1,0,0]
	v_pk_fma_f32 v[28:29], v[148:149], v[74:75], v[28:29] neg_lo:[1,0,0] neg_hi:[1,0,0]
	ds_read_b128 v[146:149], v109 offset:15584
	v_pk_fma_f32 v[34:35], v[152:153], v[74:75], v[34:35] neg_lo:[1,0,0] neg_hi:[1,0,0]
	ds_read_b128 v[150:153], v109 offset:15840
	v_pk_fma_f32 v[38:39], v[156:157], v[74:75], v[38:39] neg_lo:[1,0,0] neg_hi:[1,0,0]
	ds_read_b128 v[154:157], v109 offset:16096
	v_pk_fma_f32 v[42:43], v[160:161], v[74:75], v[42:43] neg_lo:[1,0,0] neg_hi:[1,0,0]
	ds_read_b128 v[158:161], v109 offset:16352
	s_waitcnt lgkmcnt(4)
; #define LAS __attribute__((address_space(3)))
; __device__ __forceinline__ unsigned f2bf(float f) { return pk2(f, 0.f) & 0xffffu; }
; __device__ __forceinline__ void gdn_local_unit(LAS unsigned char* lds, const GdnP& P, int unit, const int tid, const int pf) {
;     ...
;         for (int c = 1; c < 64; ++c) { f32x2 sp = (f32x2){sol2[c >> 1][c & 1], 0.f};
; #pragma unroll
;             for (int jb = 0; jb <= (c - 1) / 4; ++jb) { const f32x4 m4 = *(const LAS f32x4*)(Ms + c * 64 + 4 * jb);
;                 sp -= (f32x2){m4.x, m4.y} * sol2[2 * jb]; sp -= (f32x2){m4.z, m4.w} * sol2[2 * jb + 1]; }
;             sol2[c >> 1][c & 1] = sp.x + sp.y; }
;         if (col < 128) {
; #pragma unroll
;             for (int t = 0; t < 64; ++t) Vs[t * 128 + col] = sol2[t >> 1][t & 1];
;         } else {
; #pragma unroll
;             for (int t = 0; t < 64; ++t) *(LAS bf16_t*)(lds + GL_QB + t * 272 + (col - 128) * 2) = (bf16_t)f2bf(sol2[t >> 1][t & 1]);
;         }
	v_pk_fma_f32 v[28:29], v[220:221], v[66:67], v[28:29] neg_lo:[1,0,0] neg_hi:[1,0,0]
	v_pk_fma_f32 v[34:35], v[230:231], v[66:67], v[34:35] neg_lo:[1,0,0] neg_hi:[1,0,0]
	v_pk_fma_f32 v[38:39], v[234:235], v[66:67], v[38:39] neg_lo:[1,0,0] neg_hi:[1,0,0]
	v_pk_fma_f32 v[42:43], v[142:143], v[66:67], v[42:43] neg_lo:[1,0,0] neg_hi:[1,0,0]
	v_pk_fma_f32 v[28:29], v[222:223], v[56:57], v[28:29] neg_lo:[1,0,0] neg_hi:[1,0,0]
	ds_read_b128 v[220:223], v109 offset:15856
	v_pk_fma_f32 v[34:35], v[232:233], v[56:57], v[34:35] neg_lo:[1,0,0] neg_hi:[1,0,0]
	ds_read_b128 v[230:233], v109 offset:16112
	v_pk_fma_f32 v[38:39], v[236:237], v[56:57], v[38:39] neg_lo:[1,0,0] neg_hi:[1,0,0]
	ds_read_b128 v[234:237], v109 offset:16368
	v_pk_fma_f32 v[42:43], v[144:145], v[56:57], v[42:43] neg_lo:[1,0,0] neg_hi:[1,0,0]
	s_waitcnt lgkmcnt(3)
	v_pk_fma_f32 v[28:29], v[146:147], v[46:47], v[28:29] neg_lo:[1,0,0] neg_hi:[1,0,0]
	v_pk_fma_f32 v[34:35], v[150:151], v[46:47], v[34:35] neg_lo:[1,0,0] neg_hi:[1,0,0]
	v_pk_fma_f32 v[38:39], v[154:155], v[46:47], v[38:39] neg_lo:[1,0,0] neg_hi:[1,0,0]
	v_pk_fma_f32 v[42:43], v[158:159], v[46:47], v[42:43] neg_lo:[1,0,0] neg_hi:[1,0,0]
	v_pk_fma_f32 v[28:29], v[148:149], v[32:33], v[28:29] neg_lo:[1,0,0] neg_hi:[1,0,0]
	v_pk_fma_f32 v[34:35], v[152:153], v[32:33], v[34:35] neg_lo:[1,0,0] neg_hi:[1,0,0]
	v_pk_fma_f32 v[38:39], v[156:157], v[32:33], v[38:39] neg_lo:[1,0,0] neg_hi:[1,0,0]
	v_pk_fma_f32 v[42:43], v[160:161], v[32:33], v[42:43] neg_lo:[1,0,0] neg_hi:[1,0,0]
	v_add_f32_e32 v28, v28, v29
	v_add_f32_e32 v34, v34, v35
	v_add_f32_e32 v38, v38, v39
	v_add_f32_e32 v42, v42, v43
	v_add_f32_e32 v12, v28, v12
	v_add_f32_e32 v34, v34, v13
	v_add_f32_e32 v38, v38, v2
	v_add_f32_e32 v42, v42, v3
	s_waitcnt lgkmcnt(0)
	v_fma_f32 v13, -v220, v12, v34
	v_fma_f32 v38, -v230, v12, v38
	v_fma_f32 v42, -v234, v12, v42
	v_fma_f32 v2, -v231, v13, v38
	v_fma_f32 v42, -v235, v13, v42
	v_fma_f32 v3, -v236, v2, v42
	s_and_saveexec_b64 s[0:1], s[8:9]
	s_xor_b64 s[0:1], exec, s[0:1]
	s_cbranch_execz .LBB0_1027
	v_cvt_pk_bf16_f32 v100, v0, v0
	ds_write_b16 v200, v100
	v_cvt_pk_bf16_f32 v100, v1, v1
	ds_write_b16 v199, v100 offset:16
	v_cvt_pk_bf16_f32 v100, v8, v8
	ds_write_b16 v199, v100 offset:288
	v_cvt_pk_bf16_f32 v100, v9, v9
	ds_write_b16 v199, v100 offset:560
	v_cvt_pk_bf16_f32 v100, v14, v14
	ds_write_b16 v199, v100 offset:832
	v_cvt_pk_bf16_f32 v100, v15, v15
	ds_write_b16 v199, v100 offset:1104
	v_cvt_pk_bf16_f32 v100, v18, v18
	ds_write_b16 v199, v100 offset:1376
	v_cvt_pk_bf16_f32 v100, v19, v19
	ds_write_b16 v199, v100 offset:1648
	v_cvt_pk_bf16_f32 v100, v22, v22
	ds_write_b16 v199, v100 offset:1920
	v_cvt_pk_bf16_f32 v100, v23, v23
	ds_write_b16 v199, v100 offset:2192
	v_cvt_pk_bf16_f32 v100, v26, v26
	ds_write_b16 v199, v100 offset:2464
	v_cvt_pk_bf16_f32 v100, v27, v27
	ds_write_b16 v199, v100 offset:2736
	v_cvt_pk_bf16_f32 v100, v30, v30
	ds_write_b16 v199, v100 offset:3008
	v_cvt_pk_bf16_f32 v100, v31, v31
	ds_write_b16 v199, v100 offset:3280
	v_cvt_pk_bf16_f32 v100, v36, v36
	ds_write_b16 v199, v100 offset:3552
	v_cvt_pk_bf16_f32 v100, v37, v37
	ds_write_b16 v199, v100 offset:3824
	v_cvt_pk_bf16_f32 v100, v40, v40
	ds_write_b16 v199, v100 offset:4096
	v_cvt_pk_bf16_f32 v100, v41, v41
	ds_write_b16 v199, v100 offset:4368
	v_cvt_pk_bf16_f32 v100, v44, v44
	ds_write_b16 v199, v100 offset:4640
	v_cvt_pk_bf16_f32 v100, v45, v45
	ds_write_b16 v199, v100 offset:4912
	v_cvt_pk_bf16_f32 v100, v50, v50
	ds_write_b16 v199, v100 offset:5184
	v_cvt_pk_bf16_f32 v100, v51, v51
	ds_write_b16 v199, v100 offset:5456
	v_cvt_pk_bf16_f32 v100, v54, v54
	ds_write_b16 v199, v100 offset:5728
	v_cvt_pk_bf16_f32 v100, v55, v55
	ds_write_b16 v199, v100 offset:6000
	v_cvt_pk_bf16_f32 v100, v60, v60
	ds_write_b16 v199, v100 offset:6272
	v_cvt_pk_bf16_f32 v100, v61, v61
	ds_write_b16 v199, v100 offset:6544
	v_cvt_pk_bf16_f32 v100, v64, v64
	ds_write_b16 v199, v100 offset:6816
	v_cvt_pk_bf16_f32 v100, v65, v65
	ds_write_b16 v199, v100 offset:7088
	v_cvt_pk_bf16_f32 v100, v70, v70
	ds_write_b16 v199, v100 offset:7360
	v_cvt_pk_bf16_f32 v100, v71, v71
	ds_write_b16 v199, v100 offset:7632
	v_cvt_pk_bf16_f32 v100, v112, v112
	ds_write_b16 v199, v100 offset:7904
	v_cvt_pk_bf16_f32 v100, v113, v113
	ds_write_b16 v199, v100 offset:8176
	v_cvt_pk_bf16_f32 v100, v116, v116
	ds_write_b16 v199, v100 offset:8448
	v_cvt_pk_bf16_f32 v100, v117, v117
	ds_write_b16 v199, v100 offset:8720
	v_cvt_pk_bf16_f32 v100, v122, v122
	ds_write_b16 v199, v100 offset:8992
	v_cvt_pk_bf16_f32 v100, v123, v123
	ds_write_b16 v199, v100 offset:9264
	v_cvt_pk_bf16_f32 v100, v128, v128
	ds_write_b16 v199, v100 offset:9536
	v_cvt_pk_bf16_f32 v100, v129, v129
	ds_write_b16 v199, v100 offset:9808
	v_cvt_pk_bf16_f32 v100, v134, v134
	ds_write_b16 v199, v100 offset:10080
	v_cvt_pk_bf16_f32 v100, v135, v135
	ds_write_b16 v199, v100 offset:10352
	v_cvt_pk_bf16_f32 v100, v140, v140
	ds_write_b16 v199, v100 offset:10624
	v_cvt_pk_bf16_f32 v100, v141, v141
	ds_write_b16 v199, v100 offset:10896
	v_cvt_pk_bf16_f32 v100, v138, v138
	ds_write_b16 v199, v100 offset:11168
	v_cvt_pk_bf16_f32 v100, v139, v139
	ds_write_b16 v199, v100 offset:11440
	v_cvt_pk_bf16_f32 v100, v132, v132
	ds_write_b16 v199, v100 offset:11712
	v_cvt_pk_bf16_f32 v100, v133, v133
	ds_write_b16 v199, v100 offset:11984
	v_cvt_pk_bf16_f32 v100, v124, v124
	ds_write_b16 v199, v100 offset:12256
	v_cvt_pk_bf16_f32 v100, v125, v125
	ds_write_b16 v199, v100 offset:12528
	v_cvt_pk_bf16_f32 v100, v118, v118
	ds_write_b16 v199, v100 offset:12800
	v_cvt_pk_bf16_f32 v100, v119, v119
	ds_write_b16 v199, v100 offset:13072
	v_cvt_pk_bf16_f32 v100, v74, v74
	ds_write_b16 v199, v100 offset:13344
	v_cvt_pk_bf16_f32 v100, v75, v75
	ds_write_b16 v199, v100 offset:13616
	v_cvt_pk_bf16_f32 v100, v66, v66
	ds_write_b16 v199, v100 offset:13888
	v_cvt_pk_bf16_f32 v100, v67, v67
	ds_write_b16 v199, v100 offset:14160
	v_cvt_pk_bf16_f32 v100, v56, v56
	ds_write_b16 v199, v100 offset:14432
	v_cvt_pk_bf16_f32 v100, v57, v57
	ds_write_b16 v199, v100 offset:14704
	v_cvt_pk_bf16_f32 v100, v46, v46
	ds_write_b16 v199, v100 offset:14976
	v_cvt_pk_bf16_f32 v100, v47, v47
	ds_write_b16 v199, v100 offset:15248
	v_cvt_pk_bf16_f32 v100, v32, v32
	ds_write_b16 v199, v100 offset:15520
	v_cvt_pk_bf16_f32 v100, v33, v33
	ds_write_b16 v199, v100 offset:15792
	v_cvt_pk_bf16_f32 v100, v12, v12
	ds_write_b16 v199, v100 offset:16064
	v_cvt_pk_bf16_f32 v100, v13, v13
	ds_write_b16 v199, v100 offset:16336
	v_cvt_pk_bf16_f32 v100, v2, v2
	ds_write_b16 v199, v100 offset:16608
	v_cvt_pk_bf16_f32 v100, v3, v3
	ds_write_b16 v199, v100 offset:16880
